# GEMM K-loops: back edge rotated in front of the loop-back barrier (barrier is the loop head; exit path keeps its own barrier)
# speedup vs baseline: 1.0082x; 1.0043x over previous
; #define STAGE(P, BASE, br, kt) STAGET(tid_, P, BASE, br, kt)
; #define WAIT_V(n) asm volatile("s_waitcnt vmcnt(" #n ")" ::: "memory")
; #define BAR __builtin_amdgcn_s_barrier()
; template <int EPI, int K, int KL> ...
;     ...
;   if (wr == 1) BAR;
;   WAIT_V(4); BAR;
;   STAGE(SB(1, 0), Bt, bcol, 1); STAGE(SA(1, 0), A, brow, 1); STAGE(SB(1, 1), Bt, bcol + HALF, 1);
;   WAIT_V(6); BAR;
.LBB0_235:
	s_or_b64 exec, exec, s[50:51]
	v_add_u32_e32 v2, v1, v2
	v_and_b32_e32 v2, 0xfffffc00, v2
	v_sub_u32_e32 v2, v1, v2
	v_lshrrev_b32_e32 v5, 4, v2
	v_add_u32_e32 v3, v129, v3
	v_bitop3_b32 v5, v5, v2, 32 bitop3:0x6c
	v_ashrrev_i32_e32 v2, 31, v2
	v_ashrrev_i32_e32 v3, 6, v3
	v_lshrrev_b32_e32 v2, 26, v2
	v_lshlrev_b32_e32 v6, 3, v3
	v_add_u32_e32 v2, v5, v2
	v_and_b32_e32 v6, -16, v6
	v_ashrrev_i32_e32 v7, 6, v2
	v_add_u32_e32 v2, v7, v6
	v_mul_i32_i24_e32 v6, 64, v7
	s_ashr_i32 s47, s46, 31
	v_lshlrev_b32_e32 v3, 5, v3
	v_sub_u32_e32 v5, v5, v6
	s_lshl_b64 s[52:53], s[46:47], 12
	v_readlane_b32 s56, v254, 12
	v_and_b32_e32 v3, 32, v3
	v_ashrrev_i16_sdwa v5, v207, sext(v5) dst_sel:DWORD dst_unused:UNUSED_PAD src0_sel:DWORD src1_sel:BYTE_0
	v_readlane_b32 s57, v254, 13
	s_add_u32 s18, s56, s52
	v_add_u32_sdwa v130, v3, sext(v5) dst_sel:DWORD dst_unused:UNUSED_PAD src0_sel:DWORD src1_sel:WORD_0
	v_ashrrev_i32_e32 v3, 31, v2
	s_addc_u32 s19, s57, s53
	v_lshlrev_b64 v[140:141], 12, v[2:3]
	v_ashrrev_i32_e32 v131, 31, v130
	v_readlane_b32 s47, v254, 45
	v_lshl_add_u64 v[2:3], s[18:19], 0, v[140:141]
	v_lshlrev_b64 v[6:7], 1, v[130:131]
	v_add_u32_e32 v165, s47, v1
	v_lshl_add_u64 v[2:3], v[2:3], 0, v[6:7]
	s_mov_b64 s[58:59], 0x80
	v_readfirstlane_b32 s15, v165
	v_lshl_add_u64 v[2:3], v[2:3], 0, s[58:59]
	s_mov_b32 m0, s15
	s_waitcnt vmcnt(4)
	s_barrier
	global_load_lds_dwordx4 v[2:3], off
	v_ashrrev_i32_e32 v2, 31, v0
	v_lshrrev_b32_e32 v2, 22, v2
	v_add_u32_e32 v2, v0, v2
	v_ashrrev_i32_e32 v3, 10, v2
	v_mul_i32_i24_e32 v2, 0x400, v3
	v_sub_u32_e32 v2, v0, v2
	v_lshrrev_b32_e32 v5, 4, v2
	v_bitop3_b32 v5, v5, v2, 32 bitop3:0x6c
	v_ashrrev_i32_e32 v8, 31, v5
	v_lshrrev_b32_e32 v8, 26, v8
	v_add_u32_e32 v8, v5, v8
	v_lshlrev_b32_e32 v2, 3, v3
	v_ashrrev_i32_e32 v9, 6, v8
	v_and_b32_e32 v8, 0xc0, v8
	v_and_b32_e32 v2, -16, v2
	v_lshlrev_b32_e32 v3, 5, v3
	v_sub_u32_e32 v5, v5, v8
	v_add_u32_e32 v2, v9, v2
	v_and_b32_e32 v3, 32, v3
	v_ashrrev_i16_sdwa v5, v207, sext(v5) dst_sel:DWORD dst_unused:UNUSED_PAD src0_sel:DWORD src1_sel:BYTE_0
	v_add_u32_sdwa v142, v3, sext(v5) dst_sel:DWORD dst_unused:UNUSED_PAD src0_sel:DWORD src1_sel:WORD_0
	v_ashrrev_i32_e32 v3, 31, v2
	v_lshlrev_b64 v[144:145], 12, v[2:3]
	v_ashrrev_i32_e32 v143, 31, v142
	v_lshl_add_u64 v[2:3], s[18:19], 0, v[144:145]
	v_lshlrev_b64 v[8:9], 1, v[142:143]
	v_add_u32_e32 v5, s47, v0
	s_lshl_b64 s[18:19], s[44:45], 12
	v_lshl_add_u64 v[2:3], v[2:3], 0, v[8:9]
	v_readfirstlane_b32 s15, v5
	s_add_u32 s50, s66, s18
	v_lshl_add_u64 v[2:3], v[2:3], 0, s[58:59]
	s_mov_b32 m0, s15
	s_addc_u32 s51, s67, s19
	global_load_lds_dwordx4 v[2:3], off
	v_lshl_add_u64 v[2:3], s[50:51], 0, v[140:141]
	v_add_u32_e32 v166, 0x8000, v157
	v_lshl_add_u64 v[2:3], v[2:3], 0, v[6:7]
	v_readfirstlane_b32 s15, v166
	s_or_b32 s54, s46, 0x80
	v_lshl_add_u64 v[2:3], v[2:3], 0, s[58:59]
	s_mov_b32 m0, s15
	s_ashr_i32 s55, s54, 31
	global_load_lds_dwordx4 v[2:3], off
	v_lshl_add_u64 v[2:3], s[50:51], 0, v[144:145]
	v_add_u32_e32 v167, 0xa000, v157
	s_lshl_b64 s[54:55], s[54:55], 12
	v_lshl_add_u64 v[2:3], v[2:3], 0, v[8:9]
	v_readfirstlane_b32 s15, v167
	s_add_u32 s54, s56, s54
	v_lshl_add_u64 v[2:3], v[2:3], 0, s[58:59]
	s_mov_b32 m0, s15
	s_addc_u32 s55, s57, s55
	v_readlane_b32 s56, v254, 46
	global_load_lds_dwordx4 v[2:3], off
	v_lshl_add_u64 v[2:3], s[54:55], 0, v[140:141]
	v_add_u32_e32 v169, s56, v1
	v_lshl_add_u64 v[2:3], v[2:3], 0, v[6:7]
	v_readfirstlane_b32 s15, v169
	v_lshl_add_u64 v[2:3], v[2:3], 0, s[58:59]
	s_mov_b32 m0, s15
	v_add_u32_e32 v0, s56, v0
	global_load_lds_dwordx4 v[2:3], off
	v_lshl_add_u64 v[2:3], s[54:55], 0, v[144:145]
	v_lshl_add_u64 v[2:3], v[2:3], 0, v[8:9]
	v_readfirstlane_b32 s15, v0
	v_lshl_add_u64 v[2:3], v[2:3], 0, s[58:59]
	s_mov_b32 m0, s15
	v_and_b32_e32 v132, 15, v129
	global_load_lds_dwordx4 v[2:3], off
	v_bfe_u32 v155, v129, 4, 2
	v_lshlrev_b32_e32 v3, 2, v129
	v_lshlrev_b32_e32 v0, 4, v155
	v_lshlrev_b32_e32 v1, 6, v132
	v_and_b32_e32 v3, 32, v3
	v_bitop3_b32 v1, v0, v3, v1 bitop3:0x36
	v_readlane_b32 s15, v254, 43
	v_add_u32_e32 v11, s47, v1
	v_add_u32_e32 v12, s56, v1
	v_add_u32_e32 v5, s15, v1
	v_readlane_b32 s15, v254, 44
	v_add_u32_e32 v13, 0, v1
	v_bfe_u32 v154, v129, 6, 2
	v_add_u32_e32 v10, s15, v1
	v_lshlrev_b32_e32 v1, 6, v129
	s_movk_i32 s15, 0x3c0
	v_and_or_b32 v0, v1, s15, v0
	v_xad_u32 v3, v0, v3, 0
	v_lshl_add_u64 v[0:1], s[52:53], 0, v[140:141]
	v_lshl_add_u64 v[146:147], v[0:1], 0, v[6:7]
	v_lshl_add_u64 v[0:1], s[52:53], 0, v[144:145]
	v_lshl_add_u64 v[148:149], v[0:1], 0, v[8:9]
	v_lshl_add_u64 v[0:1], s[18:19], 0, v[140:141]
	s_waitcnt vmcnt(6)
; #define STAGE(P, BASE, br, kt) STAGET(tid_, P, BASE, br, kt)
; #define LDA(dst, b, h) UFOR(m, 4) UFOR(k, 2) \
;     dst[m][k] = *reinterpret_cast<const bf16x8*>((char*)SA(b, h) + lds_byte(wr * 64 + m * 16 + fr, k * 32 + fq * 8))
; #define LDB(dst, b, h) UFOR(n, 2) UFOR(k, 2) \
;     dst[n][k] = *reinterpret_cast<const bf16x8*>((char*)SB(b, h) + lds_byte(wc * 32 + n * 16 + fr, k * 32 + fq * 8))
; #define MMA(ai, bj, At, Bq) do { __builtin_amdgcn_s_setprio(1); \
;     UFOR(m, 4) UFOR(n, 2) UFOR(k, 2) \
;       acc[ai][bj][m][n] = __builtin_amdgcn_mfma_f32_16x16x32_bf16(Bq[n][k], At[m][k], acc[ai][bj][m][n], 0, 0, 0); \
;     __builtin_amdgcn_s_setprio(0); } while (0)
; #define WAIT_V(n) asm volatile("s_waitcnt vmcnt(" #n ")" ::: "memory")
; #define WAIT_L(n) asm volatile("s_waitcnt lgkmcnt(" #n ")" ::: "memory")
; #define BAR __builtin_amdgcn_s_barrier()
; #define SCHED __builtin_amdgcn_sched_barrier(0)
; template <int EPI, int K, int KL> ...
;     ...
;   f32x4 acc[2][2][4][2] = {};
;   bf16x8 At[4][2], B0[2][2], B1[2][2];
;   const int nt = KL / BK;
;   if (own_prologue) {
;     STAGE(SB(0, 0), Bt, bcol, 0); STAGE(SA(0, 0), A, brow, 0);
;     STAGE(SB(0, 1), Bt, bcol + HALF, 0); STAGE(SA(0, 1), A, brow + HALF, 0);
;   }
;   if (wr == 1) BAR;
;   WAIT_V(4); BAR;
;   STAGE(SB(1, 0), Bt, bcol, 1); STAGE(SA(1, 0), A, brow, 1); STAGE(SB(1, 1), Bt, bcol + HALF, 1);
;   WAIT_V(6); BAR;
;   for (int t = 0; t < nt - 2; t += 2) {
;     LDB(B0, 0, 0); SCHED; LDA(At, 0, 0); STAGE(SA(1, 1), A, brow + HALF, t + 1);
;     WAIT_L(8); BAR; WAIT_L(0); MMA(0, 0, At, B0); BAR; SCHED;
	v_lshlrev_b32_e32 v128, 6, v4
	v_lshlrev_b32_e32 v4, 13, v4
	v_lshl_add_u64 v[150:151], v[0:1], 0, v[6:7]
	v_lshl_add_u64 v[0:1], s[18:19], 0, v[144:145]
	v_lshlrev_b32_e32 v2, 12, v154
	v_or_b32_e32 v14, 0x800, v4
	v_or_b32_e32 v15, 0x1000, v4
	v_or_b32_e32 v16, 0x1800, v4
	v_lshl_add_u64 v[152:153], v[0:1], 0, v[8:9]
	v_mov_b32_e32 v0, 0
	s_mov_b32 s15, -2
	v_add_u32_e32 v170, v5, v2
	v_add_u32_e32 v162, v13, v4
	v_add_u32_e32 v161, v3, v14
	v_add_u32_e32 v160, v3, v15
	v_add_u32_e32 v159, v3, v16
	v_add_u32_e32 v168, v10, v2
	v_add_u32_e32 v164, v11, v2
	v_add_u32_e32 v163, v12, v2
	v_mov_b32_e32 v1, v0
	v_mov_b32_e32 v2, v0
	v_mov_b32_e32 v3, v0
	v_mov_b32_e32 v4, v0
	v_mov_b32_e32 v5, v0
	v_mov_b32_e32 v6, v0
	v_mov_b32_e32 v7, v0
	v_mov_b32_e32 v8, v0
	v_mov_b32_e32 v9, v0
	v_mov_b32_e32 v10, v0
	v_mov_b32_e32 v11, v0
	v_mov_b32_e32 v12, v0
	v_mov_b32_e32 v13, v0
	v_mov_b32_e32 v14, v0
	v_mov_b32_e32 v15, v0
	v_mov_b32_e32 v16, v0
	v_mov_b32_e32 v17, v0
	v_mov_b32_e32 v18, v0
	v_mov_b32_e32 v19, v0
	v_mov_b32_e32 v20, v0
	v_mov_b32_e32 v21, v0
	v_mov_b32_e32 v22, v0
	v_mov_b32_e32 v23, v0
	v_mov_b32_e32 v24, v0
	v_mov_b32_e32 v25, v0
	v_mov_b32_e32 v26, v0
	v_mov_b32_e32 v27, v0
	v_mov_b32_e32 v28, v0
	v_mov_b32_e32 v29, v0
	v_mov_b32_e32 v30, v0
	v_mov_b32_e32 v31, v0
	v_mov_b32_e32 v32, v0
	v_mov_b32_e32 v33, v0
	v_mov_b32_e32 v34, v0
	v_mov_b32_e32 v35, v0
	v_mov_b32_e32 v36, v0
	v_mov_b32_e32 v37, v0
	v_mov_b32_e32 v38, v0
	v_mov_b32_e32 v39, v0
	v_mov_b32_e32 v40, v0
	v_mov_b32_e32 v41, v0
	v_mov_b32_e32 v42, v0
	v_mov_b32_e32 v43, v0
	v_mov_b32_e32 v44, v0
	v_mov_b32_e32 v45, v0
	v_mov_b32_e32 v46, v0
	v_mov_b32_e32 v47, v0
	v_mov_b32_e32 v48, v0
	v_mov_b32_e32 v49, v0
	v_mov_b32_e32 v50, v0
	v_mov_b32_e32 v51, v0
	v_mov_b32_e32 v52, v0
	v_mov_b32_e32 v53, v0
	v_mov_b32_e32 v54, v0
	v_mov_b32_e32 v55, v0
	v_mov_b32_e32 v56, v0
	v_mov_b32_e32 v57, v0
	v_mov_b32_e32 v58, v0
	v_mov_b32_e32 v59, v0
	v_mov_b32_e32 v60, v0
	v_mov_b32_e32 v61, v0
	v_mov_b32_e32 v62, v0
	v_mov_b32_e32 v63, v0
	v_mov_b32_e32 v64, v0
	v_mov_b32_e32 v65, v0
	v_mov_b32_e32 v66, v0
	v_mov_b32_e32 v67, v0
	v_mov_b32_e32 v68, v0
	v_mov_b32_e32 v69, v0
	v_mov_b32_e32 v70, v0
	v_mov_b32_e32 v71, v0
	v_mov_b32_e32 v72, v0
	v_mov_b32_e32 v73, v0
	v_mov_b32_e32 v74, v0
	v_mov_b32_e32 v75, v0
	v_mov_b32_e32 v76, v0
	v_mov_b32_e32 v77, v0
	v_mov_b32_e32 v78, v0
	v_mov_b32_e32 v79, v0
	v_mov_b32_e32 v80, v0
	v_mov_b32_e32 v81, v0
	v_mov_b32_e32 v82, v0
	v_mov_b32_e32 v83, v0
	v_mov_b32_e32 v84, v0
	v_mov_b32_e32 v85, v0
	v_mov_b32_e32 v86, v0
	v_mov_b32_e32 v87, v0
	v_mov_b32_e32 v88, v0
	v_mov_b32_e32 v89, v0
	v_mov_b32_e32 v90, v0
	v_mov_b32_e32 v91, v0
	v_mov_b32_e32 v92, v0
	v_mov_b32_e32 v93, v0
	v_mov_b32_e32 v94, v0
	v_mov_b32_e32 v95, v0
	v_mov_b32_e32 v96, v0
	v_mov_b32_e32 v97, v0
	v_mov_b32_e32 v98, v0
	v_mov_b32_e32 v99, v0
	v_mov_b32_e32 v100, v0
	v_mov_b32_e32 v101, v0
	v_mov_b32_e32 v102, v0
	v_mov_b32_e32 v103, v0
	v_mov_b32_e32 v104, v0
	v_mov_b32_e32 v105, v0
	v_mov_b32_e32 v106, v0
	v_mov_b32_e32 v107, v0
	v_mov_b32_e32 v108, v0
	v_mov_b32_e32 v109, v0
	v_mov_b32_e32 v110, v0
	v_mov_b32_e32 v111, v0
	v_mov_b32_e32 v112, v0
	v_mov_b32_e32 v113, v0
	v_mov_b32_e32 v114, v0
	v_mov_b32_e32 v115, v0
	v_mov_b32_e32 v116, v0
	v_mov_b32_e32 v117, v0
	v_mov_b32_e32 v118, v0
	v_mov_b32_e32 v119, v0
	v_mov_b32_e32 v120, v0
	v_mov_b32_e32 v121, v0
	v_mov_b32_e32 v122, v0
	v_mov_b32_e32 v123, v0
	v_mov_b32_e32 v124, v0
	v_mov_b32_e32 v125, v0
	v_mov_b32_e32 v126, v0
	v_mov_b32_e32 v127, v0
	s_mov_b64 s[52:53], 0x4300100
	s_mov_b64 s[54:55], 0x4380100
	s_mov_b64 s[56:57], 0x4300180
	s_mov_b64 s[58:59], 0x4380180
.Lkrot_236:
	s_barrier
.LBB0_236:
	ds_read_b128 v[174:177], v170
	ds_read_b128 v[178:181], v170 offset:1024
	ds_read_b128 v[182:185], v170 offset:2048
	ds_read_b128 v[186:189], v170 offset:3072
	v_add_u32_e32 v171, 0xc000, v157
	v_lshl_add_u64 v[136:137], s[92:93], 0, v[150:151]
	v_readfirstlane_b32 s18, v171
	v_lshl_add_u64 v[138:139], v[136:137], 0, s[88:89]
	s_mov_b32 m0, s18
	v_add_u32_e32 v172, 0xe000, v157
	ds_read_b128 v[190:193], v162
	ds_read_b128 v[194:197], v162 offset:1024
	ds_read_b128 v[198:201], v161
	ds_read_b128 v[202:205], v161 offset:1024
	ds_read_b128 v[218:221], v160
	ds_read_b128 v[222:225], v160 offset:1024
	ds_read_b128 v[226:229], v159
	ds_read_b128 v[230:233], v159 offset:1024
	global_load_lds_dwordx4 v[138:139], off
	v_lshl_add_u64 v[138:139], s[92:93], 0, v[152:153]
	v_readfirstlane_b32 s18, v172
	v_lshl_add_u64 v[208:209], v[138:139], 0, s[88:89]
	s_mov_b32 m0, s18
	s_nop 0
	global_load_lds_dwordx4 v[208:209], off
	s_waitcnt lgkmcnt(8)
	s_barrier
	s_waitcnt lgkmcnt(0)
	s_waitcnt lgkmcnt(0)
	v_mfma_f32_16x16x32_bf16 v[124:127], v[174:177], v[190:193], v[124:127]
	v_mfma_f32_16x16x32_bf16 v[120:123], v[182:185], v[190:193], v[120:123]
	v_mfma_f32_16x16x32_bf16 v[116:119], v[174:177], v[198:201], v[116:119]
	v_mfma_f32_16x16x32_bf16 v[112:115], v[182:185], v[198:201], v[112:115]
	v_mfma_f32_16x16x32_bf16 v[108:111], v[174:177], v[218:221], v[108:111]
	v_mfma_f32_16x16x32_bf16 v[104:107], v[182:185], v[218:221], v[104:107]
	v_mfma_f32_16x16x32_bf16 v[100:103], v[174:177], v[226:229], v[100:103]
	v_mfma_f32_16x16x32_bf16 v[96:99], v[182:185], v[226:229], v[96:99]
	v_mfma_f32_16x16x32_bf16 v[124:127], v[178:181], v[194:197], v[124:127]
	v_mfma_f32_16x16x32_bf16 v[120:123], v[186:189], v[194:197], v[120:123]
	v_mfma_f32_16x16x32_bf16 v[116:119], v[178:181], v[202:205], v[116:119]
	v_mfma_f32_16x16x32_bf16 v[112:115], v[186:189], v[202:205], v[112:115]
	v_mfma_f32_16x16x32_bf16 v[108:111], v[178:181], v[222:225], v[108:111]
	v_mfma_f32_16x16x32_bf16 v[104:107], v[186:189], v[222:225], v[104:107]
	v_mfma_f32_16x16x32_bf16 v[100:103], v[178:181], v[230:233], v[100:103]
	v_mfma_f32_16x16x32_bf16 v[96:99], v[186:189], v[230:233], v[96:99]
	s_barrier
; #define STAGE(P, BASE, br, kt) STAGET(tid_, P, BASE, br, kt)
; #define LDA(dst, b, h) UFOR(m, 4) UFOR(k, 2) \
;     dst[m][k] = *reinterpret_cast<const bf16x8*>((char*)SA(b, h) + lds_byte(wr * 64 + m * 16 + fr, k * 32 + fq * 8))
; #define LDB(dst, b, h) UFOR(n, 2) UFOR(k, 2) \
;     dst[n][k] = *reinterpret_cast<const bf16x8*>((char*)SB(b, h) + lds_byte(wc * 32 + n * 16 + fr, k * 32 + fq * 8))
; #define MMA(ai, bj, At, Bq) do { __builtin_amdgcn_s_setprio(1); \
;     UFOR(m, 4) UFOR(n, 2) UFOR(k, 2) \
;       acc[ai][bj][m][n] = __builtin_amdgcn_mfma_f32_16x16x32_bf16(Bq[n][k], At[m][k], acc[ai][bj][m][n], 0, 0, 0); \
;     __builtin_amdgcn_s_setprio(0); } while (0)
; #define WAIT_V(n) asm volatile("s_waitcnt vmcnt(" #n ")" ::: "memory")
; #define WAIT_L(n) asm volatile("s_waitcnt lgkmcnt(" #n ")" ::: "memory")
; #define BAR __builtin_amdgcn_s_barrier()
; #define SCHED __builtin_amdgcn_sched_barrier(0)
; template <int EPI, int K, int KL> ...
;     ...
;     LDB(B1, 0, 1); STAGE(SB(0, 0), Bt, bcol, t + 2);
;     BAR; WAIT_L(0); MMA(0, 1, At, B1); BAR;
;     LDA(At, 0, 1); STAGE(SA(0, 0), A, brow, t + 2);
;     BAR; WAIT_L(0); MMA(1, 0, At, B0); BAR; SCHED;
;     STAGE(SB(0, 1), Bt, bcol + HALF, t + 2);
;     WAIT_V(6); BAR; MMA(1, 1, At, B1); BAR;
;     LDB(B0, 1, 0); SCHED; LDA(At, 1, 0); STAGE(SA(0, 1), A, brow + HALF, t + 2);
;     WAIT_L(8); BAR; WAIT_L(0); MMA(0, 0, At, B0); BAR; SCHED;
	v_lshl_add_u64 v[208:209], s[92:93], 0, v[146:147]
	v_readfirstlane_b32 s18, v156
	v_lshl_add_u64 v[210:211], v[208:209], 0, s[52:53]
	s_mov_b32 m0, s18
	v_add_u32_e32 v134, 0x2000, v156
	ds_read_b128 v[234:237], v168
	ds_read_b128 v[238:241], v168 offset:1024
	ds_read_b128 v[242:245], v168 offset:2048
	ds_read_b128 v[246:249], v168 offset:3072
	global_load_lds_dwordx4 v[210:211], off
	v_lshl_add_u64 v[210:211], s[92:93], 0, v[148:149]
	v_readfirstlane_b32 s18, v134
	v_lshl_add_u64 v[214:215], v[210:211], 0, s[52:53]
	s_mov_b32 m0, s18
	s_nop 0
	global_load_lds_dwordx4 v[214:215], off
	s_barrier
	s_waitcnt lgkmcnt(0)
	s_waitcnt lgkmcnt(0)
	v_mfma_f32_16x16x32_bf16 v[92:95], v[234:237], v[190:193], v[92:95]
	v_mfma_f32_16x16x32_bf16 v[88:91], v[242:245], v[190:193], v[88:91]
	v_mfma_f32_16x16x32_bf16 v[84:87], v[234:237], v[198:201], v[84:87]
	v_mfma_f32_16x16x32_bf16 v[80:83], v[242:245], v[198:201], v[80:83]
	v_mfma_f32_16x16x32_bf16 v[76:79], v[234:237], v[218:221], v[76:79]
	v_mfma_f32_16x16x32_bf16 v[72:75], v[242:245], v[218:221], v[72:75]
	v_mfma_f32_16x16x32_bf16 v[68:71], v[234:237], v[226:229], v[68:71]
	v_mfma_f32_16x16x32_bf16 v[64:67], v[242:245], v[226:229], v[64:67]
	v_mfma_f32_16x16x32_bf16 v[92:95], v[238:241], v[194:197], v[92:95]
	v_mfma_f32_16x16x32_bf16 v[88:91], v[246:249], v[194:197], v[88:91]
	v_mfma_f32_16x16x32_bf16 v[84:87], v[238:241], v[202:205], v[84:87]
	v_mfma_f32_16x16x32_bf16 v[80:83], v[246:249], v[202:205], v[80:83]
	v_mfma_f32_16x16x32_bf16 v[76:79], v[238:241], v[222:225], v[76:79]
	v_mfma_f32_16x16x32_bf16 v[72:75], v[246:249], v[222:225], v[72:75]
	v_mfma_f32_16x16x32_bf16 v[68:71], v[238:241], v[230:233], v[68:71]
	v_mfma_f32_16x16x32_bf16 v[64:67], v[246:249], v[230:233], v[64:67]
	v_readfirstlane_b32 s18, v157
	v_add_u32_e32 v134, 0x2000, v157
	v_lshl_add_u64 v[214:215], v[136:137], 0, s[8:9]
	s_mov_b32 m0, s18
	v_readfirstlane_b32 s18, v134
	s_barrier
	ds_read_b128 v[190:193], v162 offset:16384
	ds_read_b128 v[194:197], v162 offset:17408
	ds_read_b128 v[198:201], v161 offset:16384
	ds_read_b128 v[202:205], v161 offset:17408
	ds_read_b128 v[218:221], v160 offset:16384
	ds_read_b128 v[222:225], v160 offset:17408
	ds_read_b128 v[226:229], v159 offset:16384
	ds_read_b128 v[230:233], v159 offset:17408
	global_load_lds_dwordx4 v[214:215], off
	v_lshl_add_u64 v[214:215], v[138:139], 0, s[8:9]
	s_mov_b32 m0, s18
	s_nop 0
	global_load_lds_dwordx4 v[214:215], off
	s_barrier
	s_waitcnt lgkmcnt(0)
	s_waitcnt lgkmcnt(0)
	v_mfma_f32_16x16x32_bf16 v[60:63], v[174:177], v[190:193], v[60:63]
	v_mfma_f32_16x16x32_bf16 v[56:59], v[182:185], v[190:193], v[56:59]
	v_mfma_f32_16x16x32_bf16 v[52:55], v[174:177], v[198:201], v[52:55]
	v_mfma_f32_16x16x32_bf16 v[48:51], v[182:185], v[198:201], v[48:51]
	v_mfma_f32_16x16x32_bf16 v[44:47], v[174:177], v[218:221], v[44:47]
	v_mfma_f32_16x16x32_bf16 v[40:43], v[182:185], v[218:221], v[40:43]
	v_mfma_f32_16x16x32_bf16 v[36:39], v[174:177], v[226:229], v[36:39]
	v_mfma_f32_16x16x32_bf16 v[32:35], v[182:185], v[226:229], v[32:35]
	v_mfma_f32_16x16x32_bf16 v[60:63], v[178:181], v[194:197], v[60:63]
	v_mfma_f32_16x16x32_bf16 v[56:59], v[186:189], v[194:197], v[56:59]
	v_mfma_f32_16x16x32_bf16 v[52:55], v[178:181], v[202:205], v[52:55]
	v_mfma_f32_16x16x32_bf16 v[48:51], v[186:189], v[202:205], v[48:51]
	v_mfma_f32_16x16x32_bf16 v[44:47], v[178:181], v[222:225], v[44:47]
	v_mfma_f32_16x16x32_bf16 v[40:43], v[186:189], v[222:225], v[40:43]
	v_mfma_f32_16x16x32_bf16 v[36:39], v[178:181], v[230:233], v[36:39]
	v_mfma_f32_16x16x32_bf16 v[32:35], v[186:189], v[230:233], v[32:35]
	s_barrier
	v_readfirstlane_b32 s18, v158
	v_add_u32_e32 v134, 0x2000, v158
	v_lshl_add_u64 v[174:175], v[208:209], 0, s[54:55]
	s_mov_b32 m0, s18
	v_readfirstlane_b32 s18, v134
	global_load_lds_dwordx4 v[174:175], off
	v_lshl_add_u64 v[174:175], v[210:211], 0, s[54:55]
	s_mov_b32 m0, s18
	s_nop 0
	global_load_lds_dwordx4 v[174:175], off
	s_waitcnt vmcnt(6)
	s_barrier
	v_mfma_f32_16x16x32_bf16 v[28:31], v[234:237], v[190:193], v[28:31]
	v_mfma_f32_16x16x32_bf16 v[24:27], v[242:245], v[190:193], v[24:27]
	v_mfma_f32_16x16x32_bf16 v[20:23], v[234:237], v[198:201], v[20:23]
	v_mfma_f32_16x16x32_bf16 v[16:19], v[242:245], v[198:201], v[16:19]
	v_mfma_f32_16x16x32_bf16 v[12:15], v[234:237], v[218:221], v[12:15]
	v_mfma_f32_16x16x32_bf16 v[8:11], v[242:245], v[218:221], v[8:11]
	v_mfma_f32_16x16x32_bf16 v[4:7], v[234:237], v[226:229], v[4:7]
	v_mfma_f32_16x16x32_bf16 v[0:3], v[242:245], v[226:229], v[0:3]
	v_mfma_f32_16x16x32_bf16 v[28:31], v[238:241], v[194:197], v[28:31]
	v_mfma_f32_16x16x32_bf16 v[24:27], v[246:249], v[194:197], v[24:27]
	v_mfma_f32_16x16x32_bf16 v[20:23], v[238:241], v[202:205], v[20:23]
	v_mfma_f32_16x16x32_bf16 v[16:19], v[246:249], v[202:205], v[16:19]
	v_mfma_f32_16x16x32_bf16 v[12:15], v[238:241], v[222:225], v[12:15]
	v_mfma_f32_16x16x32_bf16 v[8:11], v[246:249], v[222:225], v[8:11]
	v_mfma_f32_16x16x32_bf16 v[4:7], v[238:241], v[230:233], v[4:7]
	v_mfma_f32_16x16x32_bf16 v[0:3], v[246:249], v[230:233], v[0:3]
	s_barrier
	ds_read_b128 v[174:177], v164
	ds_read_b128 v[178:181], v164 offset:1024
	ds_read_b128 v[182:185], v164 offset:2048
	ds_read_b128 v[186:189], v164 offset:3072
	v_add_u32_e32 v134, 0x4000, v157
	v_lshl_add_u64 v[214:215], v[136:137], 0, s[12:13]
	v_readfirstlane_b32 s18, v134
	v_add_u32_e32 v134, 0x6000, v157
	s_mov_b32 m0, s18
	v_readfirstlane_b32 s18, v134
	ds_read_b128 v[190:193], v162 offset:32768
	ds_read_b128 v[194:197], v162 offset:33792
	ds_read_b128 v[198:201], v161 offset:32768
	ds_read_b128 v[202:205], v161 offset:33792
	ds_read_b128 v[218:221], v160 offset:32768
	ds_read_b128 v[222:225], v160 offset:33792
	ds_read_b128 v[226:229], v159 offset:32768
	ds_read_b128 v[230:233], v159 offset:33792
	global_load_lds_dwordx4 v[214:215], off
	v_lshl_add_u64 v[214:215], v[138:139], 0, s[12:13]
	s_mov_b32 m0, s18
	s_nop 0
	global_load_lds_dwordx4 v[214:215], off
	s_waitcnt lgkmcnt(8)
	s_barrier
; #define STAGE(P, BASE, br, kt) STAGET(tid_, P, BASE, br, kt)
; #define LDA(dst, b, h) UFOR(m, 4) UFOR(k, 2) \
;     dst[m][k] = *reinterpret_cast<const bf16x8*>((char*)SA(b, h) + lds_byte(wr * 64 + m * 16 + fr, k * 32 + fq * 8))
; #define LDB(dst, b, h) UFOR(n, 2) UFOR(k, 2) \
;     dst[n][k] = *reinterpret_cast<const bf16x8*>((char*)SB(b, h) + lds_byte(wc * 32 + n * 16 + fr, k * 32 + fq * 8))
; #define MMA(ai, bj, At, Bq) do { __builtin_amdgcn_s_setprio(1); \
;     UFOR(m, 4) UFOR(n, 2) UFOR(k, 2) \
;       acc[ai][bj][m][n] = __builtin_amdgcn_mfma_f32_16x16x32_bf16(Bq[n][k], At[m][k], acc[ai][bj][m][n], 0, 0, 0); \
;     __builtin_amdgcn_s_setprio(0); } while (0)
; #define WAIT_V(n) asm volatile("s_waitcnt vmcnt(" #n ")" ::: "memory")
; #define WAIT_L(n) asm volatile("s_waitcnt lgkmcnt(" #n ")" ::: "memory")
; #define BAR __builtin_amdgcn_s_barrier()
; #define SCHED __builtin_amdgcn_sched_barrier(0)
; template <int EPI, int K, int KL> ...
;     ...
;     WAIT_L(8); BAR; WAIT_L(0); MMA(0, 0, At, B0); BAR; SCHED;
;     LDB(B1, 1, 1); STAGE(SB(1, 0), Bt, bcol, t + 3);
;     BAR; WAIT_L(0); MMA(0, 1, At, B1); BAR;
;     LDA(At, 1, 1); STAGE(SA(1, 0), A, brow, t + 3);
;     BAR; WAIT_L(0); MMA(1, 0, At, B0); BAR; SCHED;
;     STAGE(SB(1, 1), Bt, bcol + HALF, t + 3);
;     WAIT_V(6); BAR; MMA(1, 1, At, B1); BAR;
	s_waitcnt lgkmcnt(0)
	s_waitcnt lgkmcnt(0)
	v_mfma_f32_16x16x32_bf16 v[124:127], v[174:177], v[190:193], v[124:127]
	v_mfma_f32_16x16x32_bf16 v[120:123], v[182:185], v[190:193], v[120:123]
	v_mfma_f32_16x16x32_bf16 v[116:119], v[174:177], v[198:201], v[116:119]
	v_mfma_f32_16x16x32_bf16 v[112:115], v[182:185], v[198:201], v[112:115]
	v_mfma_f32_16x16x32_bf16 v[108:111], v[174:177], v[218:221], v[108:111]
	v_mfma_f32_16x16x32_bf16 v[104:107], v[182:185], v[218:221], v[104:107]
	v_mfma_f32_16x16x32_bf16 v[100:103], v[174:177], v[226:229], v[100:103]
	v_mfma_f32_16x16x32_bf16 v[96:99], v[182:185], v[226:229], v[96:99]
	v_mfma_f32_16x16x32_bf16 v[124:127], v[178:181], v[194:197], v[124:127]
	v_mfma_f32_16x16x32_bf16 v[120:123], v[186:189], v[194:197], v[120:123]
	v_mfma_f32_16x16x32_bf16 v[116:119], v[178:181], v[202:205], v[116:119]
	v_mfma_f32_16x16x32_bf16 v[112:115], v[186:189], v[202:205], v[112:115]
	v_mfma_f32_16x16x32_bf16 v[108:111], v[178:181], v[222:225], v[108:111]
	v_mfma_f32_16x16x32_bf16 v[104:107], v[186:189], v[222:225], v[104:107]
	v_mfma_f32_16x16x32_bf16 v[100:103], v[178:181], v[230:233], v[100:103]
	v_mfma_f32_16x16x32_bf16 v[96:99], v[186:189], v[230:233], v[96:99]
	s_barrier
	v_readfirstlane_b32 s18, v165
	v_add_u32_e32 v134, 0x2000, v165
	v_lshl_add_u64 v[214:215], v[208:209], 0, s[56:57]
	s_mov_b32 m0, s18
	v_readfirstlane_b32 s18, v134
	ds_read_b128 v[234:237], v163
	ds_read_b128 v[238:241], v163 offset:1024
	ds_read_b128 v[242:245], v163 offset:2048
	ds_read_b128 v[246:249], v163 offset:3072
	global_load_lds_dwordx4 v[214:215], off
	v_lshl_add_u64 v[214:215], v[210:211], 0, s[56:57]
	s_mov_b32 m0, s18
	s_nop 0
	global_load_lds_dwordx4 v[214:215], off
	s_barrier
	s_waitcnt lgkmcnt(0)
	s_waitcnt lgkmcnt(0)
	v_mfma_f32_16x16x32_bf16 v[92:95], v[234:237], v[190:193], v[92:95]
	v_mfma_f32_16x16x32_bf16 v[88:91], v[242:245], v[190:193], v[88:91]
	v_mfma_f32_16x16x32_bf16 v[84:87], v[234:237], v[198:201], v[84:87]
	v_mfma_f32_16x16x32_bf16 v[80:83], v[242:245], v[198:201], v[80:83]
	v_mfma_f32_16x16x32_bf16 v[76:79], v[234:237], v[218:221], v[76:79]
	v_mfma_f32_16x16x32_bf16 v[72:75], v[242:245], v[218:221], v[72:75]
	v_mfma_f32_16x16x32_bf16 v[68:71], v[234:237], v[226:229], v[68:71]
	v_mfma_f32_16x16x32_bf16 v[64:67], v[242:245], v[226:229], v[64:67]
	v_mfma_f32_16x16x32_bf16 v[92:95], v[238:241], v[194:197], v[92:95]
	v_mfma_f32_16x16x32_bf16 v[88:91], v[246:249], v[194:197], v[88:91]
	v_mfma_f32_16x16x32_bf16 v[84:87], v[238:241], v[202:205], v[84:87]
	v_mfma_f32_16x16x32_bf16 v[80:83], v[246:249], v[202:205], v[80:83]
	v_mfma_f32_16x16x32_bf16 v[76:79], v[238:241], v[222:225], v[76:79]
	v_mfma_f32_16x16x32_bf16 v[72:75], v[246:249], v[222:225], v[72:75]
	v_mfma_f32_16x16x32_bf16 v[68:71], v[238:241], v[230:233], v[68:71]
	v_mfma_f32_16x16x32_bf16 v[64:67], v[246:249], v[230:233], v[64:67]
	v_readfirstlane_b32 s18, v166
	v_lshl_add_u64 v[136:137], v[136:137], 0, s[16:17]
	s_mov_b32 m0, s18
	v_readfirstlane_b32 s18, v167
	s_barrier
	ds_read_b128 v[190:193], v162 offset:49152
	ds_read_b128 v[194:197], v162 offset:50176
	ds_read_b128 v[198:201], v161 offset:49152
	ds_read_b128 v[202:205], v161 offset:50176
	ds_read_b128 v[218:221], v160 offset:49152
	ds_read_b128 v[222:225], v160 offset:50176
	ds_read_b128 v[226:229], v159 offset:49152
	ds_read_b128 v[230:233], v159 offset:50176
	global_load_lds_dwordx4 v[136:137], off
	v_lshl_add_u64 v[136:137], v[138:139], 0, s[16:17]
	s_mov_b32 m0, s18
	s_nop 0
	global_load_lds_dwordx4 v[136:137], off
	s_barrier
	s_waitcnt lgkmcnt(0)
	s_waitcnt lgkmcnt(0)
	v_mfma_f32_16x16x32_bf16 v[60:63], v[174:177], v[190:193], v[60:63]
	v_mfma_f32_16x16x32_bf16 v[56:59], v[182:185], v[190:193], v[56:59]
	v_mfma_f32_16x16x32_bf16 v[52:55], v[174:177], v[198:201], v[52:55]
	v_mfma_f32_16x16x32_bf16 v[48:51], v[182:185], v[198:201], v[48:51]
	v_mfma_f32_16x16x32_bf16 v[44:47], v[174:177], v[218:221], v[44:47]
	v_mfma_f32_16x16x32_bf16 v[40:43], v[182:185], v[218:221], v[40:43]
	v_mfma_f32_16x16x32_bf16 v[36:39], v[174:177], v[226:229], v[36:39]
	v_mfma_f32_16x16x32_bf16 v[32:35], v[182:185], v[226:229], v[32:35]
	v_mfma_f32_16x16x32_bf16 v[60:63], v[178:181], v[194:197], v[60:63]
	v_mfma_f32_16x16x32_bf16 v[56:59], v[186:189], v[194:197], v[56:59]
	v_mfma_f32_16x16x32_bf16 v[52:55], v[178:181], v[202:205], v[52:55]
	v_mfma_f32_16x16x32_bf16 v[48:51], v[186:189], v[202:205], v[48:51]
	v_mfma_f32_16x16x32_bf16 v[44:47], v[178:181], v[222:225], v[44:47]
	v_mfma_f32_16x16x32_bf16 v[40:43], v[186:189], v[222:225], v[40:43]
	v_mfma_f32_16x16x32_bf16 v[36:39], v[178:181], v[230:233], v[36:39]
	v_mfma_f32_16x16x32_bf16 v[32:35], v[186:189], v[230:233], v[32:35]
	s_barrier
	v_readfirstlane_b32 s18, v169
	v_add_u32_e32 v134, 0x2000, v169
	v_lshl_add_u64 v[136:137], v[208:209], 0, s[58:59]
	s_mov_b32 m0, s18
	v_readfirstlane_b32 s18, v134
	global_load_lds_dwordx4 v[136:137], off
	v_lshl_add_u64 v[136:137], v[210:211], 0, s[58:59]
	s_mov_b32 m0, s18
	s_nop 0
	global_load_lds_dwordx4 v[136:137], off
	s_waitcnt vmcnt(6)
	s_barrier
; #define STAGE(P, BASE, br, kt) STAGET(tid_, P, BASE, br, kt)
; #define LDA(dst, b, h) UFOR(m, 4) UFOR(k, 2) \
;     dst[m][k] = *reinterpret_cast<const bf16x8*>((char*)SA(b, h) + lds_byte(wr * 64 + m * 16 + fr, k * 32 + fq * 8))
; #define LDB(dst, b, h) UFOR(n, 2) UFOR(k, 2) \
;     dst[n][k] = *reinterpret_cast<const bf16x8*>((char*)SB(b, h) + lds_byte(wc * 32 + n * 16 + fr, k * 32 + fq * 8))
; #define MMA(ai, bj, At, Bq) do { __builtin_amdgcn_s_setprio(1); \
;     UFOR(m, 4) UFOR(n, 2) UFOR(k, 2) \
;       acc[ai][bj][m][n] = __builtin_amdgcn_mfma_f32_16x16x32_bf16(Bq[n][k], At[m][k], acc[ai][bj][m][n], 0, 0, 0); \
;     __builtin_amdgcn_s_setprio(0); } while (0)
; #define WAIT_V(n) asm volatile("s_waitcnt vmcnt(" #n ")" ::: "memory")
; #define WAIT_L(n) asm volatile("s_waitcnt lgkmcnt(" #n ")" ::: "memory")
; #define BAR __builtin_amdgcn_s_barrier()
; template <int EPI, int K, int KL> ...
;     ...
;     WAIT_V(6); BAR; MMA(1, 1, At, B1); BAR;
;   }
;   { LDB(B0, 0, 0); LDA(At, 0, 0); STAGE(SA(1, 1), A, brow + HALF, nt - 1);
;     BAR; WAIT_L(0); MMA(0, 0, At, B0); BAR;
;     LDB(B1, 0, 1); BAR; WAIT_L(0); MMA(0, 1, At, B1); BAR;
;     LDA(At, 0, 1); WAIT_V(4); BAR; WAIT_L(0); MMA(1, 0, At, B0); MMA(1, 1, At, B1); BAR; }
	v_mfma_f32_16x16x32_bf16 v[28:31], v[234:237], v[190:193], v[28:31]
	v_mfma_f32_16x16x32_bf16 v[24:27], v[242:245], v[190:193], v[24:27]
	v_mfma_f32_16x16x32_bf16 v[20:23], v[234:237], v[198:201], v[20:23]
	v_mfma_f32_16x16x32_bf16 v[16:19], v[242:245], v[198:201], v[16:19]
	v_mfma_f32_16x16x32_bf16 v[12:15], v[234:237], v[218:221], v[12:15]
	v_mfma_f32_16x16x32_bf16 v[8:11], v[242:245], v[218:221], v[8:11]
	v_mfma_f32_16x16x32_bf16 v[4:7], v[234:237], v[226:229], v[4:7]
	v_mfma_f32_16x16x32_bf16 v[0:3], v[242:245], v[226:229], v[0:3]
	v_mfma_f32_16x16x32_bf16 v[28:31], v[238:241], v[194:197], v[28:31]
	v_mfma_f32_16x16x32_bf16 v[24:27], v[246:249], v[194:197], v[24:27]
	v_mfma_f32_16x16x32_bf16 v[20:23], v[238:241], v[202:205], v[20:23]
	v_mfma_f32_16x16x32_bf16 v[16:19], v[246:249], v[202:205], v[16:19]
	v_mfma_f32_16x16x32_bf16 v[12:15], v[238:241], v[222:225], v[12:15]
	v_mfma_f32_16x16x32_bf16 v[8:11], v[246:249], v[222:225], v[8:11]
	v_mfma_f32_16x16x32_bf16 v[4:7], v[238:241], v[230:233], v[4:7]
	v_mfma_f32_16x16x32_bf16 v[0:3], v[246:249], v[230:233], v[0:3]
	s_add_i32 s15, s15, 2
	v_lshl_add_u64 v[146:147], v[146:147], 0, s[20:21]
	v_lshl_add_u64 v[148:149], v[148:149], 0, s[20:21]
	v_lshl_add_u64 v[150:151], v[150:151], 0, s[20:21]
	s_cmp_lt_u32 s15, 28
	v_lshl_add_u64 v[152:153], v[152:153], 0, s[20:21]
	s_cbranch_scc1 .Lkrot_236
	s_barrier
	s_add_u32 s18, s50, 0x80f80
	s_addc_u32 s19, s51, 0
	v_lshl_add_u64 v[136:137], s[18:19], 0, v[140:141]
	v_readfirstlane_b32 s15, v171
	v_lshl_add_u64 v[130:131], v[130:131], 1, v[136:137]
	s_mov_b32 m0, s15
	ds_read_b128 v[146:149], v170
	ds_read_b128 v[150:153], v170 offset:1024
	ds_read_b128 v[174:177], v170 offset:2048
	ds_read_b128 v[178:181], v170 offset:3072
	ds_read_b128 v[182:185], v162
	ds_read_b128 v[186:189], v162 offset:1024
	ds_read_b128 v[190:193], v161
	ds_read_b128 v[194:197], v161 offset:1024
	ds_read_b128 v[198:201], v160
	ds_read_b128 v[202:205], v160 offset:1024
	ds_read_b128 v[218:221], v159
	ds_read_b128 v[222:225], v159 offset:1024
	global_load_lds_dwordx4 v[130:131], off
	v_lshl_add_u64 v[130:131], s[18:19], 0, v[144:145]
	v_readfirstlane_b32 s15, v172
	v_lshl_add_u64 v[130:131], v[142:143], 1, v[130:131]
	s_mov_b32 m0, s15
	s_nop 0
	global_load_lds_dwordx4 v[130:131], off
	s_barrier
	s_waitcnt lgkmcnt(0)
	s_waitcnt lgkmcnt(0)
	v_mfma_f32_16x16x32_bf16 v[124:127], v[146:149], v[182:185], v[124:127]
	v_mfma_f32_16x16x32_bf16 v[120:123], v[174:177], v[182:185], v[120:123]
	v_mfma_f32_16x16x32_bf16 v[116:119], v[146:149], v[190:193], v[116:119]
	v_mfma_f32_16x16x32_bf16 v[112:115], v[174:177], v[190:193], v[112:115]
	v_mfma_f32_16x16x32_bf16 v[108:111], v[146:149], v[198:201], v[108:111]
	v_mfma_f32_16x16x32_bf16 v[104:107], v[174:177], v[198:201], v[104:107]
	v_mfma_f32_16x16x32_bf16 v[100:103], v[146:149], v[218:221], v[100:103]
	v_mfma_f32_16x16x32_bf16 v[96:99], v[174:177], v[218:221], v[96:99]
	v_mfma_f32_16x16x32_bf16 v[124:127], v[150:153], v[186:189], v[124:127]
	v_mfma_f32_16x16x32_bf16 v[120:123], v[178:181], v[186:189], v[120:123]
	v_mfma_f32_16x16x32_bf16 v[116:119], v[150:153], v[194:197], v[116:119]
	v_mfma_f32_16x16x32_bf16 v[112:115], v[178:181], v[194:197], v[112:115]
	v_mfma_f32_16x16x32_bf16 v[108:111], v[150:153], v[202:205], v[108:111]
	v_mfma_f32_16x16x32_bf16 v[104:107], v[178:181], v[202:205], v[104:107]
	v_mfma_f32_16x16x32_bf16 v[100:103], v[150:153], v[222:225], v[100:103]
	v_mfma_f32_16x16x32_bf16 v[96:99], v[178:181], v[222:225], v[96:99]
	s_barrier
	ds_read_b128 v[140:143], v168
	ds_read_b128 v[170:173], v168 offset:1024
	ds_read_b128 v[226:229], v168 offset:2048
	ds_read_b128 v[166:169], v168 offset:3072
	s_barrier
	s_waitcnt lgkmcnt(0)
	s_waitcnt lgkmcnt(0)
	v_mfma_f32_16x16x32_bf16 v[92:95], v[140:143], v[182:185], v[92:95]
	v_mfma_f32_16x16x32_bf16 v[88:91], v[226:229], v[182:185], v[88:91]
	v_mfma_f32_16x16x32_bf16 v[84:87], v[140:143], v[190:193], v[84:87]
	v_mfma_f32_16x16x32_bf16 v[80:83], v[226:229], v[190:193], v[80:83]
	v_mfma_f32_16x16x32_bf16 v[76:79], v[140:143], v[198:201], v[76:79]
	v_mfma_f32_16x16x32_bf16 v[72:75], v[226:229], v[198:201], v[72:75]
	v_mfma_f32_16x16x32_bf16 v[68:71], v[140:143], v[218:221], v[68:71]
	v_mfma_f32_16x16x32_bf16 v[64:67], v[226:229], v[218:221], v[64:67]
	v_mfma_f32_16x16x32_bf16 v[92:95], v[170:173], v[186:189], v[92:95]
	v_mfma_f32_16x16x32_bf16 v[88:91], v[166:169], v[186:189], v[88:91]
	v_mfma_f32_16x16x32_bf16 v[84:87], v[170:173], v[194:197], v[84:87]
	v_mfma_f32_16x16x32_bf16 v[80:83], v[166:169], v[194:197], v[80:83]
	v_mfma_f32_16x16x32_bf16 v[76:79], v[170:173], v[202:205], v[76:79]
	v_mfma_f32_16x16x32_bf16 v[72:75], v[166:169], v[202:205], v[72:75]
	v_mfma_f32_16x16x32_bf16 v[68:71], v[170:173], v[222:225], v[68:71]
	v_mfma_f32_16x16x32_bf16 v[64:67], v[166:169], v[222:225], v[64:67]
	s_barrier
	ds_read_b128 v[182:185], v162 offset:16384
	ds_read_b128 v[186:189], v162 offset:17408
	ds_read_b128 v[190:193], v161 offset:16384
	ds_read_b128 v[194:197], v161 offset:17408
	ds_read_b128 v[198:201], v160 offset:16384
	ds_read_b128 v[202:205], v160 offset:17408
	ds_read_b128 v[218:221], v159 offset:16384
	ds_read_b128 v[222:225], v159 offset:17408
	s_waitcnt vmcnt(4)
	s_barrier
; #define LDA(dst, b, h) UFOR(m, 4) UFOR(k, 2) \
;     dst[m][k] = *reinterpret_cast<const bf16x8*>((char*)SA(b, h) + lds_byte(wr * 64 + m * 16 + fr, k * 32 + fq * 8))
; #define LDB(dst, b, h) UFOR(n, 2) UFOR(k, 2) \
;     dst[n][k] = *reinterpret_cast<const bf16x8*>((char*)SB(b, h) + lds_byte(wc * 32 + n * 16 + fr, k * 32 + fq * 8))
; #define MMA(ai, bj, At, Bq) do { __builtin_amdgcn_s_setprio(1); \
;     UFOR(m, 4) UFOR(n, 2) UFOR(k, 2) \
;       acc[ai][bj][m][n] = __builtin_amdgcn_mfma_f32_16x16x32_bf16(Bq[n][k], At[m][k], acc[ai][bj][m][n], 0, 0, 0); \
;     __builtin_amdgcn_s_setprio(0); } while (0)
; #define WAIT_V(n) asm volatile("s_waitcnt vmcnt(" #n ")" ::: "memory")
; #define WAIT_L(n) asm volatile("s_waitcnt lgkmcnt(" #n ")" ::: "memory")
; #define BAR __builtin_amdgcn_s_barrier()
; template <int EPI, int K, int KL> ...
;     ...
;     LDA(At, 0, 1); WAIT_V(4); BAR; WAIT_L(0); MMA(1, 0, At, B0); MMA(1, 1, At, B1); BAR; }
;   { LDB(B0, 1, 0); LDA(At, 1, 0); WAIT_V(2); BAR; WAIT_L(0); MMA(0, 0, At, B0); BAR;
	s_waitcnt lgkmcnt(0)
	s_waitcnt lgkmcnt(0)
	v_mfma_f32_16x16x32_bf16 v[60:63], v[146:149], v[182:185], v[60:63]
	v_mfma_f32_16x16x32_bf16 v[56:59], v[174:177], v[182:185], v[56:59]
	v_mfma_f32_16x16x32_bf16 v[52:55], v[146:149], v[190:193], v[52:55]
	v_mfma_f32_16x16x32_bf16 v[48:51], v[174:177], v[190:193], v[48:51]
	v_mfma_f32_16x16x32_bf16 v[44:47], v[146:149], v[198:201], v[44:47]
	v_mfma_f32_16x16x32_bf16 v[40:43], v[174:177], v[198:201], v[40:43]
	v_mfma_f32_16x16x32_bf16 v[36:39], v[146:149], v[218:221], v[36:39]
	v_mfma_f32_16x16x32_bf16 v[32:35], v[174:177], v[218:221], v[32:35]
	v_mfma_f32_16x16x32_bf16 v[60:63], v[150:153], v[186:189], v[60:63]
	v_mfma_f32_16x16x32_bf16 v[56:59], v[178:181], v[186:189], v[56:59]
	v_mfma_f32_16x16x32_bf16 v[52:55], v[150:153], v[194:197], v[52:55]
	v_mfma_f32_16x16x32_bf16 v[48:51], v[178:181], v[194:197], v[48:51]
	v_mfma_f32_16x16x32_bf16 v[44:47], v[150:153], v[202:205], v[44:47]
	v_mfma_f32_16x16x32_bf16 v[40:43], v[178:181], v[202:205], v[40:43]
	v_mfma_f32_16x16x32_bf16 v[36:39], v[150:153], v[222:225], v[36:39]
	v_mfma_f32_16x16x32_bf16 v[32:35], v[178:181], v[222:225], v[32:35]
	v_mfma_f32_16x16x32_bf16 v[28:31], v[140:143], v[182:185], v[28:31]
	v_mfma_f32_16x16x32_bf16 v[24:27], v[226:229], v[182:185], v[24:27]
	v_mfma_f32_16x16x32_bf16 v[20:23], v[140:143], v[190:193], v[20:23]
	v_mfma_f32_16x16x32_bf16 v[16:19], v[226:229], v[190:193], v[16:19]
	v_mfma_f32_16x16x32_bf16 v[12:15], v[140:143], v[198:201], v[12:15]
	v_mfma_f32_16x16x32_bf16 v[8:11], v[226:229], v[198:201], v[8:11]
	v_mfma_f32_16x16x32_bf16 v[4:7], v[140:143], v[218:221], v[4:7]
	v_mfma_f32_16x16x32_bf16 v[0:3], v[226:229], v[218:221], v[0:3]
	v_mfma_f32_16x16x32_bf16 v[28:31], v[170:173], v[186:189], v[28:31]
	v_mfma_f32_16x16x32_bf16 v[24:27], v[166:169], v[186:189], v[24:27]
	v_mfma_f32_16x16x32_bf16 v[20:23], v[170:173], v[194:197], v[20:23]
	v_mfma_f32_16x16x32_bf16 v[16:19], v[166:169], v[194:197], v[16:19]
	v_mfma_f32_16x16x32_bf16 v[12:15], v[170:173], v[202:205], v[12:15]
	v_mfma_f32_16x16x32_bf16 v[8:11], v[166:169], v[202:205], v[8:11]
	v_mfma_f32_16x16x32_bf16 v[4:7], v[170:173], v[222:225], v[4:7]
	v_mfma_f32_16x16x32_bf16 v[0:3], v[166:169], v[222:225], v[0:3]
	s_barrier
	ds_read_b128 v[140:143], v164
	ds_read_b128 v[144:147], v164 offset:1024
	ds_read_b128 v[148:151], v164 offset:2048
	ds_read_b128 v[164:167], v164 offset:3072
	ds_read_b128 v[168:171], v162 offset:32768
	ds_read_b128 v[172:175], v162 offset:33792
	ds_read_b128 v[176:179], v161 offset:32768
	ds_read_b128 v[180:183], v161 offset:33792
	ds_read_b128 v[184:187], v160 offset:32768
	ds_read_b128 v[188:191], v160 offset:33792
	ds_read_b128 v[192:195], v159 offset:32768
	ds_read_b128 v[196:199], v159 offset:33792
	s_waitcnt vmcnt(2)
	s_barrier
	s_waitcnt lgkmcnt(0)
	s_waitcnt lgkmcnt(0)
	v_mfma_f32_16x16x32_bf16 v[124:127], v[140:143], v[168:171], v[124:127]
	v_mfma_f32_16x16x32_bf16 v[120:123], v[148:151], v[168:171], v[120:123]
	v_mfma_f32_16x16x32_bf16 v[116:119], v[140:143], v[176:179], v[116:119]
	v_mfma_f32_16x16x32_bf16 v[112:115], v[148:151], v[176:179], v[112:115]
	v_mfma_f32_16x16x32_bf16 v[108:111], v[140:143], v[184:187], v[108:111]
	v_mfma_f32_16x16x32_bf16 v[104:107], v[148:151], v[184:187], v[104:107]
	v_mfma_f32_16x16x32_bf16 v[100:103], v[140:143], v[192:195], v[100:103]
	v_mfma_f32_16x16x32_bf16 v[96:99], v[148:151], v[192:195], v[96:99]
	v_mfma_f32_16x16x32_bf16 v[124:127], v[144:147], v[172:175], v[124:127]
	v_mfma_f32_16x16x32_bf16 v[120:123], v[164:167], v[172:175], v[120:123]
	v_mfma_f32_16x16x32_bf16 v[116:119], v[144:147], v[180:183], v[116:119]
	v_mfma_f32_16x16x32_bf16 v[112:115], v[164:167], v[180:183], v[112:115]
	v_mfma_f32_16x16x32_bf16 v[108:111], v[144:147], v[188:191], v[108:111]
	v_mfma_f32_16x16x32_bf16 v[104:107], v[164:167], v[188:191], v[104:107]
	v_mfma_f32_16x16x32_bf16 v[100:103], v[144:147], v[196:199], v[100:103]
	v_mfma_f32_16x16x32_bf16 v[96:99], v[164:167], v[196:199], v[96:99]
	s_barrier
; #define LDA(dst, b, h) UFOR(m, 4) UFOR(k, 2) \
;     dst[m][k] = *reinterpret_cast<const bf16x8*>((char*)SA(b, h) + lds_byte(wr * 64 + m * 16 + fr, k * 32 + fq * 8))
; #define LDB(dst, b, h) UFOR(n, 2) UFOR(k, 2) \
;     dst[n][k] = *reinterpret_cast<const bf16x8*>((char*)SB(b, h) + lds_byte(wc * 32 + n * 16 + fr, k * 32 + fq * 8))
; #define MMA(ai, bj, At, Bq) do { __builtin_amdgcn_s_setprio(1); \
;     UFOR(m, 4) UFOR(n, 2) UFOR(k, 2) \
;       acc[ai][bj][m][n] = __builtin_amdgcn_mfma_f32_16x16x32_bf16(Bq[n][k], At[m][k], acc[ai][bj][m][n], 0, 0, 0); \
;     __builtin_amdgcn_s_setprio(0); } while (0)
; #define WAIT_V(n) asm volatile("s_waitcnt vmcnt(" #n ")" ::: "memory")
; #define WAIT_L(n) asm volatile("s_waitcnt lgkmcnt(" #n ")" ::: "memory")
; #define BAR __builtin_amdgcn_s_barrier()
; template <int EPI, int K, int KL> ...
;     ...
;     LDB(B1, 1, 1); WAIT_V(0); BAR; WAIT_L(0); MMA(0, 1, At, B1); BAR;
;     LDA(At, 1, 1); BAR; WAIT_L(0); MMA(1, 0, At, B0); MMA(1, 1, At, B1); BAR; }
;   if (wr == 0) BAR;
	ds_read_b128 v[200:203], v163
	ds_read_b128 v[218:221], v163 offset:1024
	ds_read_b128 v[222:225], v163 offset:2048
	ds_read_b128 v[226:229], v163 offset:3072
	s_waitcnt vmcnt(0)
	s_barrier
	s_waitcnt lgkmcnt(0)
	s_waitcnt lgkmcnt(0)
	v_mfma_f32_16x16x32_bf16 v[92:95], v[200:203], v[168:171], v[92:95]
	v_mfma_f32_16x16x32_bf16 v[88:91], v[222:225], v[168:171], v[88:91]
	v_mfma_f32_16x16x32_bf16 v[84:87], v[200:203], v[176:179], v[84:87]
	v_mfma_f32_16x16x32_bf16 v[80:83], v[222:225], v[176:179], v[80:83]
	v_mfma_f32_16x16x32_bf16 v[76:79], v[200:203], v[184:187], v[76:79]
	v_mfma_f32_16x16x32_bf16 v[72:75], v[222:225], v[184:187], v[72:75]
	v_mfma_f32_16x16x32_bf16 v[68:71], v[200:203], v[192:195], v[68:71]
	v_mfma_f32_16x16x32_bf16 v[64:67], v[222:225], v[192:195], v[64:67]
	v_mfma_f32_16x16x32_bf16 v[92:95], v[218:221], v[172:175], v[92:95]
	v_mfma_f32_16x16x32_bf16 v[88:91], v[226:229], v[172:175], v[88:91]
	v_mfma_f32_16x16x32_bf16 v[84:87], v[218:221], v[180:183], v[84:87]
	v_mfma_f32_16x16x32_bf16 v[80:83], v[226:229], v[180:183], v[80:83]
	v_mfma_f32_16x16x32_bf16 v[76:79], v[218:221], v[188:191], v[76:79]
	v_mfma_f32_16x16x32_bf16 v[72:75], v[226:229], v[188:191], v[72:75]
	v_mfma_f32_16x16x32_bf16 v[68:71], v[218:221], v[196:199], v[68:71]
	v_mfma_f32_16x16x32_bf16 v[64:67], v[226:229], v[196:199], v[64:67]
	s_barrier
	ds_read_b128 v[168:171], v162 offset:49152
	ds_read_b128 v[172:175], v162 offset:50176
	ds_read_b128 v[176:179], v161 offset:49152
	ds_read_b128 v[180:183], v161 offset:50176
	ds_read_b128 v[184:187], v160 offset:49152
	ds_read_b128 v[160:163], v160 offset:50176
	ds_read_b128 v[188:191], v159 offset:49152
	ds_read_b128 v[156:159], v159 offset:50176
	s_barrier
	s_waitcnt lgkmcnt(0)
	s_waitcnt lgkmcnt(0)
	v_mfma_f32_16x16x32_bf16 v[60:63], v[140:143], v[168:171], v[60:63]
	v_mfma_f32_16x16x32_bf16 v[56:59], v[148:151], v[168:171], v[56:59]
	v_mfma_f32_16x16x32_bf16 v[52:55], v[140:143], v[176:179], v[52:55]
	v_mfma_f32_16x16x32_bf16 v[48:51], v[148:151], v[176:179], v[48:51]
	v_mfma_f32_16x16x32_bf16 v[44:47], v[140:143], v[184:187], v[44:47]
	v_mfma_f32_16x16x32_bf16 v[40:43], v[148:151], v[184:187], v[40:43]
	v_mfma_f32_16x16x32_bf16 v[36:39], v[140:143], v[188:191], v[36:39]
	v_mfma_f32_16x16x32_bf16 v[32:35], v[148:151], v[188:191], v[32:35]
	v_mfma_f32_16x16x32_bf16 v[60:63], v[144:147], v[172:175], v[60:63]
	v_mfma_f32_16x16x32_bf16 v[56:59], v[164:167], v[172:175], v[56:59]
	v_mfma_f32_16x16x32_bf16 v[52:55], v[144:147], v[180:183], v[52:55]
	v_mfma_f32_16x16x32_bf16 v[48:51], v[164:167], v[180:183], v[48:51]
	v_mfma_f32_16x16x32_bf16 v[44:47], v[144:147], v[160:163], v[44:47]
	v_mfma_f32_16x16x32_bf16 v[40:43], v[164:167], v[160:163], v[40:43]
	v_mfma_f32_16x16x32_bf16 v[36:39], v[144:147], v[156:159], v[36:39]
	v_mfma_f32_16x16x32_bf16 v[32:35], v[164:167], v[156:159], v[32:35]
	v_mfma_f32_16x16x32_bf16 v[28:31], v[200:203], v[168:171], v[28:31]
	v_mfma_f32_16x16x32_bf16 v[24:27], v[222:225], v[168:171], v[24:27]
	v_mfma_f32_16x16x32_bf16 v[20:23], v[200:203], v[176:179], v[20:23]
	v_mfma_f32_16x16x32_bf16 v[16:19], v[222:225], v[176:179], v[16:19]
	v_mfma_f32_16x16x32_bf16 v[12:15], v[200:203], v[184:187], v[12:15]
	v_mfma_f32_16x16x32_bf16 v[8:11], v[222:225], v[184:187], v[8:11]
	v_mfma_f32_16x16x32_bf16 v[4:7], v[200:203], v[188:191], v[4:7]
	v_mfma_f32_16x16x32_bf16 v[0:3], v[222:225], v[188:191], v[0:3]
	v_mfma_f32_16x16x32_bf16 v[28:31], v[218:221], v[172:175], v[28:31]
	v_mfma_f32_16x16x32_bf16 v[24:27], v[226:229], v[172:175], v[24:27]
	v_mfma_f32_16x16x32_bf16 v[20:23], v[218:221], v[180:183], v[20:23]
	v_mfma_f32_16x16x32_bf16 v[16:19], v[226:229], v[180:183], v[16:19]
	v_mfma_f32_16x16x32_bf16 v[12:15], v[218:221], v[160:163], v[12:15]
	v_mfma_f32_16x16x32_bf16 v[8:11], v[226:229], v[160:163], v[8:11]
	v_mfma_f32_16x16x32_bf16 v[4:7], v[218:221], v[156:159], v[4:7]
	v_mfma_f32_16x16x32_bf16 v[0:3], v[226:229], v[156:159], v[0:3]
	s_movk_i32 s15, 0x100
	v_cmp_gt_u32_e32 vcc, s15, v129
	s_barrier
	s_and_saveexec_b64 s[50:51], vcc
	s_cbranch_execz .LBB0_239
	s_barrier

; #define STAGE(P, BASE, br, kt) STAGET(tid_, P, BASE, br, kt)
; #define WAIT_V(n) asm volatile("s_waitcnt vmcnt(" #n ")" ::: "memory")
; #define BAR __builtin_amdgcn_s_barrier()
; template <int EPI, int K, int KL> ...
;     ...
;   if (wr == 1) BAR;
;   WAIT_V(4); BAR;
;   STAGE(SB(1, 0), Bt, bcol, 1); STAGE(SA(1, 0), A, brow, 1); STAGE(SB(1, 1), Bt, bcol + HALF, 1);
;   WAIT_V(6); BAR;
.LBB0_939:
	s_or_b64 exec, exec, s[58:59]
	v_add_u32_e32 v2, v1, v2
	v_and_b32_e32 v2, 0xfffffc00, v2
	v_sub_u32_e32 v2, v1, v2
	v_lshrrev_b32_e32 v5, 4, v2
	v_add_u32_e32 v3, v154, v3
	v_bitop3_b32 v5, v5, v2, 32 bitop3:0x6c
	v_ashrrev_i32_e32 v2, 31, v2
	v_ashrrev_i32_e32 v3, 6, v3
	v_lshrrev_b32_e32 v2, 26, v2
	v_lshlrev_b32_e32 v6, 3, v3
	v_add_u32_e32 v2, v5, v2
	v_and_b32_e32 v6, -16, v6
	v_ashrrev_i32_e32 v7, 6, v2
	v_add_u32_e32 v2, v7, v6
	v_mul_i32_i24_e32 v6, 64, v7
	s_ashr_i32 s55, s54, 31
	v_lshlrev_b32_e32 v3, 5, v3
	v_sub_u32_e32 v5, v5, v6
	s_lshl_b64 s[60:61], s[54:55], 12
	v_readlane_b32 s70, v254, 24
	v_and_b32_e32 v3, 32, v3
	v_ashrrev_i16_sdwa v5, v207, sext(v5) dst_sel:DWORD dst_unused:UNUSED_PAD src0_sel:DWORD src1_sel:BYTE_0
	v_readlane_b32 s71, v254, 25
	s_add_u32 s58, s70, s60
	v_add_u32_sdwa v128, v3, sext(v5) dst_sel:DWORD dst_unused:UNUSED_PAD src0_sel:DWORD src1_sel:WORD_0
	v_ashrrev_i32_e32 v3, 31, v2
	s_addc_u32 s59, s71, s61
	v_lshlrev_b64 v[130:131], 12, v[2:3]
	v_ashrrev_i32_e32 v129, 31, v128
	v_readlane_b32 s73, v254, 45
	v_lshl_add_u64 v[2:3], s[58:59], 0, v[130:131]
	v_lshlrev_b64 v[6:7], 1, v[128:129]
	v_add_u32_e32 v164, s73, v1
	v_lshl_add_u64 v[2:3], v[2:3], 0, v[6:7]
	s_mov_b64 s[74:75], 0x80
	v_readfirstlane_b32 s55, v164
	v_lshl_add_u64 v[2:3], v[2:3], 0, s[74:75]
	s_mov_b32 m0, s55
	s_waitcnt vmcnt(4)
	s_barrier
	global_load_lds_dwordx4 v[2:3], off
	v_ashrrev_i32_e32 v2, 31, v0
	v_lshrrev_b32_e32 v2, 22, v2
	v_add_u32_e32 v2, v0, v2
	v_ashrrev_i32_e32 v3, 10, v2
	v_mul_i32_i24_e32 v2, 0x400, v3
	v_sub_u32_e32 v2, v0, v2
	v_lshrrev_b32_e32 v5, 4, v2
	v_bitop3_b32 v5, v5, v2, 32 bitop3:0x6c
	v_ashrrev_i32_e32 v8, 31, v5
	v_lshrrev_b32_e32 v8, 26, v8
	v_add_u32_e32 v8, v5, v8
	v_lshlrev_b32_e32 v2, 3, v3
	v_ashrrev_i32_e32 v9, 6, v8
	v_and_b32_e32 v8, 0xc0, v8
	v_and_b32_e32 v2, -16, v2
	v_lshlrev_b32_e32 v3, 5, v3
	v_sub_u32_e32 v5, v5, v8
	v_add_u32_e32 v2, v9, v2
	v_and_b32_e32 v3, 32, v3
	v_ashrrev_i16_sdwa v5, v207, sext(v5) dst_sel:DWORD dst_unused:UNUSED_PAD src0_sel:DWORD src1_sel:BYTE_0
	v_add_u32_sdwa v140, v3, sext(v5) dst_sel:DWORD dst_unused:UNUSED_PAD src0_sel:DWORD src1_sel:WORD_0
	v_ashrrev_i32_e32 v3, 31, v2
	v_lshlrev_b64 v[142:143], 12, v[2:3]
	v_ashrrev_i32_e32 v141, 31, v140
	v_lshl_add_u64 v[2:3], s[58:59], 0, v[142:143]
	v_lshlrev_b64 v[8:9], 1, v[140:141]
	v_add_u32_e32 v5, s73, v0
	s_lshl_b64 s[62:63], s[52:53], 12
	v_lshl_add_u64 v[2:3], v[2:3], 0, v[8:9]
	v_readfirstlane_b32 s55, v5
	s_add_u32 s58, s66, s62
	v_lshl_add_u64 v[2:3], v[2:3], 0, s[74:75]
	s_mov_b32 m0, s55
	s_addc_u32 s59, s67, s63
	global_load_lds_dwordx4 v[2:3], off
	v_lshl_add_u64 v[2:3], s[58:59], 0, v[130:131]
	v_add_u32_e32 v166, 0x8000, v157
	v_lshl_add_u64 v[2:3], v[2:3], 0, v[6:7]
	v_readfirstlane_b32 s55, v166
	s_or_b32 s66, s54, 0x80
	v_lshl_add_u64 v[2:3], v[2:3], 0, s[74:75]
	s_mov_b32 m0, s55
	s_ashr_i32 s67, s66, 31
	global_load_lds_dwordx4 v[2:3], off
	v_lshl_add_u64 v[2:3], s[58:59], 0, v[142:143]
	v_add_u32_e32 v167, 0xa000, v157
	s_lshl_b64 s[66:67], s[66:67], 12
	v_lshl_add_u64 v[2:3], v[2:3], 0, v[8:9]
	v_readfirstlane_b32 s55, v167
	s_add_u32 s66, s70, s66
	v_lshl_add_u64 v[2:3], v[2:3], 0, s[74:75]
	s_mov_b32 m0, s55
	s_addc_u32 s67, s71, s67
	v_readlane_b32 s70, v254, 46
	global_load_lds_dwordx4 v[2:3], off
	v_lshl_add_u64 v[2:3], s[66:67], 0, v[130:131]
	v_add_u32_e32 v169, s70, v1
	v_lshl_add_u64 v[2:3], v[2:3], 0, v[6:7]
	v_readfirstlane_b32 s55, v169
	v_lshl_add_u64 v[2:3], v[2:3], 0, s[74:75]
	s_mov_b32 m0, s55
	v_add_u32_e32 v0, s70, v0
	global_load_lds_dwordx4 v[2:3], off
	v_lshl_add_u64 v[2:3], s[66:67], 0, v[142:143]
	v_lshl_add_u64 v[2:3], v[2:3], 0, v[8:9]
	v_readfirstlane_b32 s55, v0
	v_lshl_add_u64 v[2:3], v[2:3], 0, s[74:75]
	s_mov_b32 m0, s55
	v_and_b32_e32 v132, 15, v154
	global_load_lds_dwordx4 v[2:3], off
	v_bfe_u32 v153, v154, 4, 2
	v_lshlrev_b32_e32 v3, 2, v154
	v_lshlrev_b32_e32 v0, 4, v153
	v_lshlrev_b32_e32 v1, 6, v132
	v_and_b32_e32 v3, 32, v3
	v_bitop3_b32 v1, v0, v3, v1 bitop3:0x36
	v_readlane_b32 s55, v254, 43
	v_add_u32_e32 v11, s73, v1
	v_add_u32_e32 v12, s70, v1
	v_add_u32_e32 v5, s55, v1
	v_readlane_b32 s55, v254, 44
	v_add_u32_e32 v13, 0, v1
	v_bfe_u32 v152, v154, 6, 2
	v_add_u32_e32 v10, s55, v1
	v_lshlrev_b32_e32 v1, 6, v154
	s_movk_i32 s55, 0x3c0
	v_and_or_b32 v0, v1, s55, v0
	v_xad_u32 v3, v0, v3, 0
	v_lshl_add_u64 v[0:1], s[60:61], 0, v[130:131]
	v_lshl_add_u64 v[144:145], v[0:1], 0, v[6:7]
	v_lshl_add_u64 v[0:1], s[60:61], 0, v[142:143]
	v_lshl_add_u64 v[146:147], v[0:1], 0, v[8:9]
	v_lshl_add_u64 v[0:1], s[62:63], 0, v[130:131]
	s_waitcnt vmcnt(6)
; #define STAGE(P, BASE, br, kt) STAGET(tid_, P, BASE, br, kt)
; #define LDA(dst, b, h) UFOR(m, 4) UFOR(k, 2) \
;     dst[m][k] = *reinterpret_cast<const bf16x8*>((char*)SA(b, h) + lds_byte(wr * 64 + m * 16 + fr, k * 32 + fq * 8))
; #define LDB(dst, b, h) UFOR(n, 2) UFOR(k, 2) \
;     dst[n][k] = *reinterpret_cast<const bf16x8*>((char*)SB(b, h) + lds_byte(wc * 32 + n * 16 + fr, k * 32 + fq * 8))
; #define MMA(ai, bj, At, Bq) do { __builtin_amdgcn_s_setprio(1); \
;     UFOR(m, 4) UFOR(n, 2) UFOR(k, 2) \
;       acc[ai][bj][m][n] = __builtin_amdgcn_mfma_f32_16x16x32_bf16(Bq[n][k], At[m][k], acc[ai][bj][m][n], 0, 0, 0); \
;     __builtin_amdgcn_s_setprio(0); } while (0)
; #define WAIT_V(n) asm volatile("s_waitcnt vmcnt(" #n ")" ::: "memory")
; #define WAIT_L(n) asm volatile("s_waitcnt lgkmcnt(" #n ")" ::: "memory")
; #define BAR __builtin_amdgcn_s_barrier()
; #define SCHED __builtin_amdgcn_sched_barrier(0)
; template <int EPI, int K, int KL> ...
;     ...
;   f32x4 acc[2][2][4][2] = {};
;   bf16x8 At[4][2], B0[2][2], B1[2][2];
;   const int nt = KL / BK;
;   if (own_prologue) {
;     STAGE(SB(0, 0), Bt, bcol, 0); STAGE(SA(0, 0), A, brow, 0);
;     STAGE(SB(0, 1), Bt, bcol + HALF, 0); STAGE(SA(0, 1), A, brow + HALF, 0);
;   }
;   if (wr == 1) BAR;
;   WAIT_V(4); BAR;
;   STAGE(SB(1, 0), Bt, bcol, 1); STAGE(SA(1, 0), A, brow, 1); STAGE(SB(1, 1), Bt, bcol + HALF, 1);
;   WAIT_V(6); BAR;
;   for (int t = 0; t < nt - 2; t += 2) {
;     LDB(B0, 0, 0); SCHED; LDA(At, 0, 0); STAGE(SA(1, 1), A, brow + HALF, t + 1);
;     WAIT_L(8); BAR; WAIT_L(0); MMA(0, 0, At, B0); BAR; SCHED;
	v_lshlrev_b32_e32 v155, 6, v4
	v_lshlrev_b32_e32 v4, 13, v4
	v_lshl_add_u64 v[148:149], v[0:1], 0, v[6:7]
	v_lshl_add_u64 v[0:1], s[62:63], 0, v[142:143]
	v_lshlrev_b32_e32 v2, 12, v152
	v_or_b32_e32 v14, 0x800, v4
	v_or_b32_e32 v15, 0x1000, v4
	v_or_b32_e32 v16, 0x1800, v4
	v_lshl_add_u64 v[150:151], v[0:1], 0, v[8:9]
	v_mov_b32_e32 v0, 0
	s_mov_b32 s55, -2
	v_add_u32_e32 v170, v5, v2
	v_add_u32_e32 v162, v13, v4
	v_add_u32_e32 v161, v3, v14
	v_add_u32_e32 v160, v3, v15
	v_add_u32_e32 v159, v3, v16
	v_add_u32_e32 v168, v10, v2
	v_add_u32_e32 v165, v11, v2
	v_add_u32_e32 v163, v12, v2
	v_mov_b32_e32 v1, v0
	v_mov_b32_e32 v2, v0
	v_mov_b32_e32 v3, v0
	v_mov_b32_e32 v4, v0
	v_mov_b32_e32 v5, v0
	v_mov_b32_e32 v6, v0
	v_mov_b32_e32 v7, v0
	v_mov_b32_e32 v8, v0
	v_mov_b32_e32 v9, v0
	v_mov_b32_e32 v10, v0
	v_mov_b32_e32 v11, v0
	v_mov_b32_e32 v12, v0
	v_mov_b32_e32 v13, v0
	v_mov_b32_e32 v14, v0
	v_mov_b32_e32 v15, v0
	v_mov_b32_e32 v16, v0
	v_mov_b32_e32 v17, v0
	v_mov_b32_e32 v18, v0
	v_mov_b32_e32 v19, v0
	v_mov_b32_e32 v20, v0
	v_mov_b32_e32 v21, v0
	v_mov_b32_e32 v22, v0
	v_mov_b32_e32 v23, v0
	v_mov_b32_e32 v24, v0
	v_mov_b32_e32 v25, v0
	v_mov_b32_e32 v26, v0
	v_mov_b32_e32 v27, v0
	v_mov_b32_e32 v28, v0
	v_mov_b32_e32 v29, v0
	v_mov_b32_e32 v30, v0
	v_mov_b32_e32 v31, v0
	v_mov_b32_e32 v32, v0
	v_mov_b32_e32 v33, v0
	v_mov_b32_e32 v34, v0
	v_mov_b32_e32 v35, v0
	v_mov_b32_e32 v36, v0
	v_mov_b32_e32 v37, v0
	v_mov_b32_e32 v38, v0
	v_mov_b32_e32 v39, v0
	v_mov_b32_e32 v40, v0
	v_mov_b32_e32 v41, v0
	v_mov_b32_e32 v42, v0
	v_mov_b32_e32 v43, v0
	v_mov_b32_e32 v44, v0
	v_mov_b32_e32 v45, v0
	v_mov_b32_e32 v46, v0
	v_mov_b32_e32 v47, v0
	v_mov_b32_e32 v48, v0
	v_mov_b32_e32 v49, v0
	v_mov_b32_e32 v50, v0
	v_mov_b32_e32 v51, v0
	v_mov_b32_e32 v52, v0
	v_mov_b32_e32 v53, v0
	v_mov_b32_e32 v54, v0
	v_mov_b32_e32 v55, v0
	v_mov_b32_e32 v56, v0
	v_mov_b32_e32 v57, v0
	v_mov_b32_e32 v58, v0
	v_mov_b32_e32 v59, v0
	v_mov_b32_e32 v60, v0
	v_mov_b32_e32 v61, v0
	v_mov_b32_e32 v62, v0
	v_mov_b32_e32 v63, v0
	v_mov_b32_e32 v64, v0
	v_mov_b32_e32 v65, v0
	v_mov_b32_e32 v66, v0
	v_mov_b32_e32 v67, v0
	v_mov_b32_e32 v68, v0
	v_mov_b32_e32 v69, v0
	v_mov_b32_e32 v70, v0
	v_mov_b32_e32 v71, v0
	v_mov_b32_e32 v72, v0
	v_mov_b32_e32 v73, v0
	v_mov_b32_e32 v74, v0
	v_mov_b32_e32 v75, v0
	v_mov_b32_e32 v76, v0
	v_mov_b32_e32 v77, v0
	v_mov_b32_e32 v78, v0
	v_mov_b32_e32 v79, v0
	v_mov_b32_e32 v80, v0
	v_mov_b32_e32 v81, v0
	v_mov_b32_e32 v82, v0
	v_mov_b32_e32 v83, v0
	v_mov_b32_e32 v84, v0
	v_mov_b32_e32 v85, v0
	v_mov_b32_e32 v86, v0
	v_mov_b32_e32 v87, v0
	v_mov_b32_e32 v88, v0
	v_mov_b32_e32 v89, v0
	v_mov_b32_e32 v90, v0
	v_mov_b32_e32 v91, v0
	v_mov_b32_e32 v92, v0
	v_mov_b32_e32 v93, v0
	v_mov_b32_e32 v94, v0
	v_mov_b32_e32 v95, v0
	v_mov_b32_e32 v96, v0
	v_mov_b32_e32 v97, v0
	v_mov_b32_e32 v98, v0
	v_mov_b32_e32 v99, v0
	v_mov_b32_e32 v100, v0
	v_mov_b32_e32 v101, v0
	v_mov_b32_e32 v102, v0
	v_mov_b32_e32 v103, v0
	v_mov_b32_e32 v104, v0
	v_mov_b32_e32 v105, v0
	v_mov_b32_e32 v106, v0
	v_mov_b32_e32 v107, v0
	v_mov_b32_e32 v108, v0
	v_mov_b32_e32 v109, v0
	v_mov_b32_e32 v110, v0
	v_mov_b32_e32 v111, v0
	v_mov_b32_e32 v112, v0
	v_mov_b32_e32 v113, v0
	v_mov_b32_e32 v114, v0
	v_mov_b32_e32 v115, v0
	v_mov_b32_e32 v116, v0
	v_mov_b32_e32 v117, v0
	v_mov_b32_e32 v118, v0
	v_mov_b32_e32 v119, v0
	v_mov_b32_e32 v120, v0
	v_mov_b32_e32 v121, v0
	v_mov_b32_e32 v122, v0
	v_mov_b32_e32 v123, v0
	v_mov_b32_e32 v124, v0
	v_mov_b32_e32 v125, v0
	v_mov_b32_e32 v126, v0
	v_mov_b32_e32 v127, v0
	s_mov_b64 s[62:63], 0x5f00100
	s_mov_b64 s[66:67], 0x5f80100
	s_mov_b64 s[70:71], 0x5f00180
	s_mov_b64 s[74:75], 0x5f80180
.Lkrot_940:
	s_barrier
.LBB0_940:
	ds_read_b128 v[174:177], v170
	ds_read_b128 v[178:181], v170 offset:1024
	ds_read_b128 v[182:185], v170 offset:2048
	ds_read_b128 v[186:189], v170 offset:3072
	v_add_u32_e32 v171, 0xc000, v157
	v_lshl_add_u64 v[136:137], s[92:93], 0, v[148:149]
	v_readfirstlane_b32 s60, v171
	v_lshl_add_u64 v[138:139], v[136:137], 0, s[88:89]
	s_mov_b32 m0, s60
	v_add_u32_e32 v172, 0xe000, v157
	ds_read_b128 v[190:193], v162
	ds_read_b128 v[194:197], v162 offset:1024
	ds_read_b128 v[198:201], v161
	ds_read_b128 v[202:205], v161 offset:1024
	ds_read_b128 v[218:221], v160
	ds_read_b128 v[222:225], v160 offset:1024
	ds_read_b128 v[226:229], v159
	ds_read_b128 v[230:233], v159 offset:1024
	global_load_lds_dwordx4 v[138:139], off
	v_lshl_add_u64 v[138:139], s[92:93], 0, v[150:151]
	v_readfirstlane_b32 s60, v172
	v_lshl_add_u64 v[208:209], v[138:139], 0, s[88:89]
	s_mov_b32 m0, s60
	s_nop 0
	global_load_lds_dwordx4 v[208:209], off
	s_waitcnt lgkmcnt(8)
	s_barrier
	s_waitcnt lgkmcnt(0)
	s_waitcnt lgkmcnt(0)
	v_mfma_f32_16x16x32_bf16 v[124:127], v[174:177], v[190:193], v[124:127]
	v_mfma_f32_16x16x32_bf16 v[120:123], v[182:185], v[190:193], v[120:123]
	v_mfma_f32_16x16x32_bf16 v[116:119], v[174:177], v[198:201], v[116:119]
	v_mfma_f32_16x16x32_bf16 v[112:115], v[182:185], v[198:201], v[112:115]
	v_mfma_f32_16x16x32_bf16 v[108:111], v[174:177], v[218:221], v[108:111]
	v_mfma_f32_16x16x32_bf16 v[104:107], v[182:185], v[218:221], v[104:107]
	v_mfma_f32_16x16x32_bf16 v[100:103], v[174:177], v[226:229], v[100:103]
	v_mfma_f32_16x16x32_bf16 v[96:99], v[182:185], v[226:229], v[96:99]
	v_mfma_f32_16x16x32_bf16 v[124:127], v[178:181], v[194:197], v[124:127]
	v_mfma_f32_16x16x32_bf16 v[120:123], v[186:189], v[194:197], v[120:123]
	v_mfma_f32_16x16x32_bf16 v[116:119], v[178:181], v[202:205], v[116:119]
	v_mfma_f32_16x16x32_bf16 v[112:115], v[186:189], v[202:205], v[112:115]
	v_mfma_f32_16x16x32_bf16 v[108:111], v[178:181], v[222:225], v[108:111]
	v_mfma_f32_16x16x32_bf16 v[104:107], v[186:189], v[222:225], v[104:107]
	v_mfma_f32_16x16x32_bf16 v[100:103], v[178:181], v[230:233], v[100:103]
	v_mfma_f32_16x16x32_bf16 v[96:99], v[186:189], v[230:233], v[96:99]
	s_barrier
; #define STAGE(P, BASE, br, kt) STAGET(tid_, P, BASE, br, kt)
; #define LDA(dst, b, h) UFOR(m, 4) UFOR(k, 2) \
;     dst[m][k] = *reinterpret_cast<const bf16x8*>((char*)SA(b, h) + lds_byte(wr * 64 + m * 16 + fr, k * 32 + fq * 8))
; #define LDB(dst, b, h) UFOR(n, 2) UFOR(k, 2) \
;     dst[n][k] = *reinterpret_cast<const bf16x8*>((char*)SB(b, h) + lds_byte(wc * 32 + n * 16 + fr, k * 32 + fq * 8))
; #define MMA(ai, bj, At, Bq) do { __builtin_amdgcn_s_setprio(1); \
;     UFOR(m, 4) UFOR(n, 2) UFOR(k, 2) \
;       acc[ai][bj][m][n] = __builtin_amdgcn_mfma_f32_16x16x32_bf16(Bq[n][k], At[m][k], acc[ai][bj][m][n], 0, 0, 0); \
;     __builtin_amdgcn_s_setprio(0); } while (0)
; #define WAIT_V(n) asm volatile("s_waitcnt vmcnt(" #n ")" ::: "memory")
; #define WAIT_L(n) asm volatile("s_waitcnt lgkmcnt(" #n ")" ::: "memory")
; #define BAR __builtin_amdgcn_s_barrier()
; #define SCHED __builtin_amdgcn_sched_barrier(0)
; template <int EPI, int K, int KL> ...
;     ...
;     LDB(B1, 0, 1); STAGE(SB(0, 0), Bt, bcol, t + 2);
;     BAR; WAIT_L(0); MMA(0, 1, At, B1); BAR;
;     LDA(At, 0, 1); STAGE(SA(0, 0), A, brow, t + 2);
;     BAR; WAIT_L(0); MMA(1, 0, At, B0); BAR; SCHED;
;     STAGE(SB(0, 1), Bt, bcol + HALF, t + 2);
;     WAIT_V(6); BAR; MMA(1, 1, At, B1); BAR;
;     LDB(B0, 1, 0); SCHED; LDA(At, 1, 0); STAGE(SA(0, 1), A, brow + HALF, t + 2);
;     WAIT_L(8); BAR; WAIT_L(0); MMA(0, 0, At, B0); BAR; SCHED;
	v_lshl_add_u64 v[208:209], s[92:93], 0, v[144:145]
	v_readfirstlane_b32 s60, v156
	v_lshl_add_u64 v[210:211], v[208:209], 0, s[62:63]
	s_mov_b32 m0, s60
	v_add_u32_e32 v134, 0x2000, v156
	ds_read_b128 v[234:237], v168
	ds_read_b128 v[238:241], v168 offset:1024
	ds_read_b128 v[242:245], v168 offset:2048
	ds_read_b128 v[246:249], v168 offset:3072
	global_load_lds_dwordx4 v[210:211], off
	v_lshl_add_u64 v[210:211], s[92:93], 0, v[146:147]
	v_readfirstlane_b32 s60, v134
	v_lshl_add_u64 v[214:215], v[210:211], 0, s[62:63]
	s_mov_b32 m0, s60
	s_nop 0
	global_load_lds_dwordx4 v[214:215], off
	s_barrier
	s_waitcnt lgkmcnt(0)
	s_waitcnt lgkmcnt(0)
	v_mfma_f32_16x16x32_bf16 v[92:95], v[234:237], v[190:193], v[92:95]
	v_mfma_f32_16x16x32_bf16 v[88:91], v[242:245], v[190:193], v[88:91]
	v_mfma_f32_16x16x32_bf16 v[84:87], v[234:237], v[198:201], v[84:87]
	v_mfma_f32_16x16x32_bf16 v[80:83], v[242:245], v[198:201], v[80:83]
	v_mfma_f32_16x16x32_bf16 v[76:79], v[234:237], v[218:221], v[76:79]
	v_mfma_f32_16x16x32_bf16 v[72:75], v[242:245], v[218:221], v[72:75]
	v_mfma_f32_16x16x32_bf16 v[68:71], v[234:237], v[226:229], v[68:71]
	v_mfma_f32_16x16x32_bf16 v[64:67], v[242:245], v[226:229], v[64:67]
	v_mfma_f32_16x16x32_bf16 v[92:95], v[238:241], v[194:197], v[92:95]
	v_mfma_f32_16x16x32_bf16 v[88:91], v[246:249], v[194:197], v[88:91]
	v_mfma_f32_16x16x32_bf16 v[84:87], v[238:241], v[202:205], v[84:87]
	v_mfma_f32_16x16x32_bf16 v[80:83], v[246:249], v[202:205], v[80:83]
	v_mfma_f32_16x16x32_bf16 v[76:79], v[238:241], v[222:225], v[76:79]
	v_mfma_f32_16x16x32_bf16 v[72:75], v[246:249], v[222:225], v[72:75]
	v_mfma_f32_16x16x32_bf16 v[68:71], v[238:241], v[230:233], v[68:71]
	v_mfma_f32_16x16x32_bf16 v[64:67], v[246:249], v[230:233], v[64:67]
	v_readfirstlane_b32 s60, v157
	v_add_u32_e32 v134, 0x2000, v157
	v_lshl_add_u64 v[214:215], v[136:137], 0, s[8:9]
	s_mov_b32 m0, s60
	v_readfirstlane_b32 s60, v134
	s_barrier
	ds_read_b128 v[190:193], v162 offset:16384
	ds_read_b128 v[194:197], v162 offset:17408
	ds_read_b128 v[198:201], v161 offset:16384
	ds_read_b128 v[202:205], v161 offset:17408
	ds_read_b128 v[218:221], v160 offset:16384
	ds_read_b128 v[222:225], v160 offset:17408
	ds_read_b128 v[226:229], v159 offset:16384
	ds_read_b128 v[230:233], v159 offset:17408
	global_load_lds_dwordx4 v[214:215], off
	v_lshl_add_u64 v[214:215], v[138:139], 0, s[8:9]
	s_mov_b32 m0, s60
	s_nop 0
	global_load_lds_dwordx4 v[214:215], off
	s_barrier
	s_waitcnt lgkmcnt(0)
	s_waitcnt lgkmcnt(0)
	v_mfma_f32_16x16x32_bf16 v[60:63], v[174:177], v[190:193], v[60:63]
	v_mfma_f32_16x16x32_bf16 v[56:59], v[182:185], v[190:193], v[56:59]
	v_mfma_f32_16x16x32_bf16 v[52:55], v[174:177], v[198:201], v[52:55]
	v_mfma_f32_16x16x32_bf16 v[48:51], v[182:185], v[198:201], v[48:51]
	v_mfma_f32_16x16x32_bf16 v[44:47], v[174:177], v[218:221], v[44:47]
	v_mfma_f32_16x16x32_bf16 v[40:43], v[182:185], v[218:221], v[40:43]
	v_mfma_f32_16x16x32_bf16 v[36:39], v[174:177], v[226:229], v[36:39]
	v_mfma_f32_16x16x32_bf16 v[32:35], v[182:185], v[226:229], v[32:35]
	v_mfma_f32_16x16x32_bf16 v[60:63], v[178:181], v[194:197], v[60:63]
	v_mfma_f32_16x16x32_bf16 v[56:59], v[186:189], v[194:197], v[56:59]
	v_mfma_f32_16x16x32_bf16 v[52:55], v[178:181], v[202:205], v[52:55]
	v_mfma_f32_16x16x32_bf16 v[48:51], v[186:189], v[202:205], v[48:51]
	v_mfma_f32_16x16x32_bf16 v[44:47], v[178:181], v[222:225], v[44:47]
	v_mfma_f32_16x16x32_bf16 v[40:43], v[186:189], v[222:225], v[40:43]
	v_mfma_f32_16x16x32_bf16 v[36:39], v[178:181], v[230:233], v[36:39]
	v_mfma_f32_16x16x32_bf16 v[32:35], v[186:189], v[230:233], v[32:35]
	s_barrier
	v_readfirstlane_b32 s60, v158
	v_add_u32_e32 v134, 0x2000, v158
	v_lshl_add_u64 v[174:175], v[208:209], 0, s[66:67]
	s_mov_b32 m0, s60
	v_readfirstlane_b32 s60, v134
	global_load_lds_dwordx4 v[174:175], off
	v_lshl_add_u64 v[174:175], v[210:211], 0, s[66:67]
	s_mov_b32 m0, s60
	s_nop 0
	global_load_lds_dwordx4 v[174:175], off
	s_waitcnt vmcnt(6)
	s_barrier
	v_mfma_f32_16x16x32_bf16 v[28:31], v[234:237], v[190:193], v[28:31]
	v_mfma_f32_16x16x32_bf16 v[24:27], v[242:245], v[190:193], v[24:27]
	v_mfma_f32_16x16x32_bf16 v[20:23], v[234:237], v[198:201], v[20:23]
	v_mfma_f32_16x16x32_bf16 v[16:19], v[242:245], v[198:201], v[16:19]
	v_mfma_f32_16x16x32_bf16 v[12:15], v[234:237], v[218:221], v[12:15]
	v_mfma_f32_16x16x32_bf16 v[8:11], v[242:245], v[218:221], v[8:11]
	v_mfma_f32_16x16x32_bf16 v[4:7], v[234:237], v[226:229], v[4:7]
	v_mfma_f32_16x16x32_bf16 v[0:3], v[242:245], v[226:229], v[0:3]
	v_mfma_f32_16x16x32_bf16 v[28:31], v[238:241], v[194:197], v[28:31]
	v_mfma_f32_16x16x32_bf16 v[24:27], v[246:249], v[194:197], v[24:27]
	v_mfma_f32_16x16x32_bf16 v[20:23], v[238:241], v[202:205], v[20:23]
	v_mfma_f32_16x16x32_bf16 v[16:19], v[246:249], v[202:205], v[16:19]
	v_mfma_f32_16x16x32_bf16 v[12:15], v[238:241], v[222:225], v[12:15]
	v_mfma_f32_16x16x32_bf16 v[8:11], v[246:249], v[222:225], v[8:11]
	v_mfma_f32_16x16x32_bf16 v[4:7], v[238:241], v[230:233], v[4:7]
	v_mfma_f32_16x16x32_bf16 v[0:3], v[246:249], v[230:233], v[0:3]
	s_barrier
	ds_read_b128 v[174:177], v165
	ds_read_b128 v[178:181], v165 offset:1024
	ds_read_b128 v[182:185], v165 offset:2048
	ds_read_b128 v[186:189], v165 offset:3072
	v_add_u32_e32 v134, 0x4000, v157
	v_lshl_add_u64 v[214:215], v[136:137], 0, s[12:13]
	v_readfirstlane_b32 s60, v134
	v_add_u32_e32 v134, 0x6000, v157
	s_mov_b32 m0, s60
	v_readfirstlane_b32 s60, v134
	ds_read_b128 v[190:193], v162 offset:32768
	ds_read_b128 v[194:197], v162 offset:33792
	ds_read_b128 v[198:201], v161 offset:32768
	ds_read_b128 v[202:205], v161 offset:33792
	ds_read_b128 v[218:221], v160 offset:32768
	ds_read_b128 v[222:225], v160 offset:33792
	ds_read_b128 v[226:229], v159 offset:32768
	ds_read_b128 v[230:233], v159 offset:33792
	global_load_lds_dwordx4 v[214:215], off
	v_lshl_add_u64 v[214:215], v[138:139], 0, s[12:13]
	s_mov_b32 m0, s60
	s_nop 0
	global_load_lds_dwordx4 v[214:215], off
	s_waitcnt lgkmcnt(8)
	s_barrier
; #define STAGE(P, BASE, br, kt) STAGET(tid_, P, BASE, br, kt)
; #define LDA(dst, b, h) UFOR(m, 4) UFOR(k, 2) \
;     dst[m][k] = *reinterpret_cast<const bf16x8*>((char*)SA(b, h) + lds_byte(wr * 64 + m * 16 + fr, k * 32 + fq * 8))
; #define LDB(dst, b, h) UFOR(n, 2) UFOR(k, 2) \
;     dst[n][k] = *reinterpret_cast<const bf16x8*>((char*)SB(b, h) + lds_byte(wc * 32 + n * 16 + fr, k * 32 + fq * 8))
; #define MMA(ai, bj, At, Bq) do { __builtin_amdgcn_s_setprio(1); \
;     UFOR(m, 4) UFOR(n, 2) UFOR(k, 2) \
;       acc[ai][bj][m][n] = __builtin_amdgcn_mfma_f32_16x16x32_bf16(Bq[n][k], At[m][k], acc[ai][bj][m][n], 0, 0, 0); \
;     __builtin_amdgcn_s_setprio(0); } while (0)
; #define WAIT_V(n) asm volatile("s_waitcnt vmcnt(" #n ")" ::: "memory")
; #define WAIT_L(n) asm volatile("s_waitcnt lgkmcnt(" #n ")" ::: "memory")
; #define BAR __builtin_amdgcn_s_barrier()
; #define SCHED __builtin_amdgcn_sched_barrier(0)
; template <int EPI, int K, int KL> ...
;     ...
;     WAIT_L(8); BAR; WAIT_L(0); MMA(0, 0, At, B0); BAR; SCHED;
;     LDB(B1, 1, 1); STAGE(SB(1, 0), Bt, bcol, t + 3);
;     BAR; WAIT_L(0); MMA(0, 1, At, B1); BAR;
;     LDA(At, 1, 1); STAGE(SA(1, 0), A, brow, t + 3);
;     BAR; WAIT_L(0); MMA(1, 0, At, B0); BAR; SCHED;
;     STAGE(SB(1, 1), Bt, bcol + HALF, t + 3);
;     WAIT_V(6); BAR; MMA(1, 1, At, B1); BAR;
	s_waitcnt lgkmcnt(0)
	s_waitcnt lgkmcnt(0)
	v_mfma_f32_16x16x32_bf16 v[124:127], v[174:177], v[190:193], v[124:127]
	v_mfma_f32_16x16x32_bf16 v[120:123], v[182:185], v[190:193], v[120:123]
	v_mfma_f32_16x16x32_bf16 v[116:119], v[174:177], v[198:201], v[116:119]
	v_mfma_f32_16x16x32_bf16 v[112:115], v[182:185], v[198:201], v[112:115]
	v_mfma_f32_16x16x32_bf16 v[108:111], v[174:177], v[218:221], v[108:111]
	v_mfma_f32_16x16x32_bf16 v[104:107], v[182:185], v[218:221], v[104:107]
	v_mfma_f32_16x16x32_bf16 v[100:103], v[174:177], v[226:229], v[100:103]
	v_mfma_f32_16x16x32_bf16 v[96:99], v[182:185], v[226:229], v[96:99]
	v_mfma_f32_16x16x32_bf16 v[124:127], v[178:181], v[194:197], v[124:127]
	v_mfma_f32_16x16x32_bf16 v[120:123], v[186:189], v[194:197], v[120:123]
	v_mfma_f32_16x16x32_bf16 v[116:119], v[178:181], v[202:205], v[116:119]
	v_mfma_f32_16x16x32_bf16 v[112:115], v[186:189], v[202:205], v[112:115]
	v_mfma_f32_16x16x32_bf16 v[108:111], v[178:181], v[222:225], v[108:111]
	v_mfma_f32_16x16x32_bf16 v[104:107], v[186:189], v[222:225], v[104:107]
	v_mfma_f32_16x16x32_bf16 v[100:103], v[178:181], v[230:233], v[100:103]
	v_mfma_f32_16x16x32_bf16 v[96:99], v[186:189], v[230:233], v[96:99]
	s_barrier
	v_readfirstlane_b32 s60, v164
	v_add_u32_e32 v134, 0x2000, v164
	v_lshl_add_u64 v[214:215], v[208:209], 0, s[70:71]
	s_mov_b32 m0, s60
	v_readfirstlane_b32 s60, v134
	ds_read_b128 v[234:237], v163
	ds_read_b128 v[238:241], v163 offset:1024
	ds_read_b128 v[242:245], v163 offset:2048
	ds_read_b128 v[246:249], v163 offset:3072
	global_load_lds_dwordx4 v[214:215], off
	v_lshl_add_u64 v[214:215], v[210:211], 0, s[70:71]
	s_mov_b32 m0, s60
	s_nop 0
	global_load_lds_dwordx4 v[214:215], off
	s_barrier
	s_waitcnt lgkmcnt(0)
	s_waitcnt lgkmcnt(0)
	v_mfma_f32_16x16x32_bf16 v[92:95], v[234:237], v[190:193], v[92:95]
	v_mfma_f32_16x16x32_bf16 v[88:91], v[242:245], v[190:193], v[88:91]
	v_mfma_f32_16x16x32_bf16 v[84:87], v[234:237], v[198:201], v[84:87]
	v_mfma_f32_16x16x32_bf16 v[80:83], v[242:245], v[198:201], v[80:83]
	v_mfma_f32_16x16x32_bf16 v[76:79], v[234:237], v[218:221], v[76:79]
	v_mfma_f32_16x16x32_bf16 v[72:75], v[242:245], v[218:221], v[72:75]
	v_mfma_f32_16x16x32_bf16 v[68:71], v[234:237], v[226:229], v[68:71]
	v_mfma_f32_16x16x32_bf16 v[64:67], v[242:245], v[226:229], v[64:67]
	v_mfma_f32_16x16x32_bf16 v[92:95], v[238:241], v[194:197], v[92:95]
	v_mfma_f32_16x16x32_bf16 v[88:91], v[246:249], v[194:197], v[88:91]
	v_mfma_f32_16x16x32_bf16 v[84:87], v[238:241], v[202:205], v[84:87]
	v_mfma_f32_16x16x32_bf16 v[80:83], v[246:249], v[202:205], v[80:83]
	v_mfma_f32_16x16x32_bf16 v[76:79], v[238:241], v[222:225], v[76:79]
	v_mfma_f32_16x16x32_bf16 v[72:75], v[246:249], v[222:225], v[72:75]
	v_mfma_f32_16x16x32_bf16 v[68:71], v[238:241], v[230:233], v[68:71]
	v_mfma_f32_16x16x32_bf16 v[64:67], v[246:249], v[230:233], v[64:67]
	v_readfirstlane_b32 s60, v166
	v_lshl_add_u64 v[136:137], v[136:137], 0, s[16:17]
	s_mov_b32 m0, s60
	v_readfirstlane_b32 s60, v167
	s_barrier
	ds_read_b128 v[190:193], v162 offset:49152
	ds_read_b128 v[194:197], v162 offset:50176
	ds_read_b128 v[198:201], v161 offset:49152
	ds_read_b128 v[202:205], v161 offset:50176
	ds_read_b128 v[218:221], v160 offset:49152
	ds_read_b128 v[222:225], v160 offset:50176
	ds_read_b128 v[226:229], v159 offset:49152
	ds_read_b128 v[230:233], v159 offset:50176
	global_load_lds_dwordx4 v[136:137], off
	v_lshl_add_u64 v[136:137], v[138:139], 0, s[16:17]
	s_mov_b32 m0, s60
	s_nop 0
	global_load_lds_dwordx4 v[136:137], off
	s_barrier
	s_waitcnt lgkmcnt(0)
	s_waitcnt lgkmcnt(0)
	v_mfma_f32_16x16x32_bf16 v[60:63], v[174:177], v[190:193], v[60:63]
	v_mfma_f32_16x16x32_bf16 v[56:59], v[182:185], v[190:193], v[56:59]
	v_mfma_f32_16x16x32_bf16 v[52:55], v[174:177], v[198:201], v[52:55]
	v_mfma_f32_16x16x32_bf16 v[48:51], v[182:185], v[198:201], v[48:51]
	v_mfma_f32_16x16x32_bf16 v[44:47], v[174:177], v[218:221], v[44:47]
	v_mfma_f32_16x16x32_bf16 v[40:43], v[182:185], v[218:221], v[40:43]
	v_mfma_f32_16x16x32_bf16 v[36:39], v[174:177], v[226:229], v[36:39]
	v_mfma_f32_16x16x32_bf16 v[32:35], v[182:185], v[226:229], v[32:35]
	v_mfma_f32_16x16x32_bf16 v[60:63], v[178:181], v[194:197], v[60:63]
	v_mfma_f32_16x16x32_bf16 v[56:59], v[186:189], v[194:197], v[56:59]
	v_mfma_f32_16x16x32_bf16 v[52:55], v[178:181], v[202:205], v[52:55]
	v_mfma_f32_16x16x32_bf16 v[48:51], v[186:189], v[202:205], v[48:51]
	v_mfma_f32_16x16x32_bf16 v[44:47], v[178:181], v[222:225], v[44:47]
	v_mfma_f32_16x16x32_bf16 v[40:43], v[186:189], v[222:225], v[40:43]
	v_mfma_f32_16x16x32_bf16 v[36:39], v[178:181], v[230:233], v[36:39]
	v_mfma_f32_16x16x32_bf16 v[32:35], v[186:189], v[230:233], v[32:35]
	s_barrier
	v_readfirstlane_b32 s60, v169
	v_add_u32_e32 v134, 0x2000, v169
	v_lshl_add_u64 v[136:137], v[208:209], 0, s[74:75]
	s_mov_b32 m0, s60
	v_readfirstlane_b32 s60, v134
	global_load_lds_dwordx4 v[136:137], off
	v_lshl_add_u64 v[136:137], v[210:211], 0, s[74:75]
	s_mov_b32 m0, s60
	s_nop 0
	global_load_lds_dwordx4 v[136:137], off
	s_waitcnt vmcnt(6)
	s_barrier
; #define STAGE(P, BASE, br, kt) STAGET(tid_, P, BASE, br, kt)
; #define LDA(dst, b, h) UFOR(m, 4) UFOR(k, 2) \
;     dst[m][k] = *reinterpret_cast<const bf16x8*>((char*)SA(b, h) + lds_byte(wr * 64 + m * 16 + fr, k * 32 + fq * 8))
; #define LDB(dst, b, h) UFOR(n, 2) UFOR(k, 2) \
;     dst[n][k] = *reinterpret_cast<const bf16x8*>((char*)SB(b, h) + lds_byte(wc * 32 + n * 16 + fr, k * 32 + fq * 8))
; #define MMA(ai, bj, At, Bq) do { __builtin_amdgcn_s_setprio(1); \
;     UFOR(m, 4) UFOR(n, 2) UFOR(k, 2) \
;       acc[ai][bj][m][n] = __builtin_amdgcn_mfma_f32_16x16x32_bf16(Bq[n][k], At[m][k], acc[ai][bj][m][n], 0, 0, 0); \
;     __builtin_amdgcn_s_setprio(0); } while (0)
; #define WAIT_V(n) asm volatile("s_waitcnt vmcnt(" #n ")" ::: "memory")
; #define WAIT_L(n) asm volatile("s_waitcnt lgkmcnt(" #n ")" ::: "memory")
; #define BAR __builtin_amdgcn_s_barrier()
; template <int EPI, int K, int KL> ...
;     ...
;     WAIT_V(6); BAR; MMA(1, 1, At, B1); BAR;
;   }
;   { LDB(B0, 0, 0); LDA(At, 0, 0); STAGE(SA(1, 1), A, brow + HALF, nt - 1);
;     BAR; WAIT_L(0); MMA(0, 0, At, B0); BAR;
;     LDB(B1, 0, 1); BAR; WAIT_L(0); MMA(0, 1, At, B1); BAR;
;     LDA(At, 0, 1); WAIT_V(4); BAR; WAIT_L(0); MMA(1, 0, At, B0); MMA(1, 1, At, B1); BAR; }
	v_mfma_f32_16x16x32_bf16 v[28:31], v[234:237], v[190:193], v[28:31]
	v_mfma_f32_16x16x32_bf16 v[24:27], v[242:245], v[190:193], v[24:27]
	v_mfma_f32_16x16x32_bf16 v[20:23], v[234:237], v[198:201], v[20:23]
	v_mfma_f32_16x16x32_bf16 v[16:19], v[242:245], v[198:201], v[16:19]
	v_mfma_f32_16x16x32_bf16 v[12:15], v[234:237], v[218:221], v[12:15]
	v_mfma_f32_16x16x32_bf16 v[8:11], v[242:245], v[218:221], v[8:11]
	v_mfma_f32_16x16x32_bf16 v[4:7], v[234:237], v[226:229], v[4:7]
	v_mfma_f32_16x16x32_bf16 v[0:3], v[242:245], v[226:229], v[0:3]
	v_mfma_f32_16x16x32_bf16 v[28:31], v[238:241], v[194:197], v[28:31]
	v_mfma_f32_16x16x32_bf16 v[24:27], v[246:249], v[194:197], v[24:27]
	v_mfma_f32_16x16x32_bf16 v[20:23], v[238:241], v[202:205], v[20:23]
	v_mfma_f32_16x16x32_bf16 v[16:19], v[246:249], v[202:205], v[16:19]
	v_mfma_f32_16x16x32_bf16 v[12:15], v[238:241], v[222:225], v[12:15]
	v_mfma_f32_16x16x32_bf16 v[8:11], v[246:249], v[222:225], v[8:11]
	v_mfma_f32_16x16x32_bf16 v[4:7], v[238:241], v[230:233], v[4:7]
	v_mfma_f32_16x16x32_bf16 v[0:3], v[246:249], v[230:233], v[0:3]
	s_add_i32 s55, s55, 2
	v_lshl_add_u64 v[144:145], v[144:145], 0, s[20:21]
	v_lshl_add_u64 v[146:147], v[146:147], 0, s[20:21]
	v_lshl_add_u64 v[148:149], v[148:149], 0, s[20:21]
	s_cmp_lt_u32 s55, 28
	v_lshl_add_u64 v[150:151], v[150:151], 0, s[20:21]
	s_cbranch_scc1 .Lkrot_940
	s_barrier
	s_add_u32 s58, s58, 0x80f80
	s_addc_u32 s59, s59, 0
	v_lshl_add_u64 v[130:131], s[58:59], 0, v[130:131]
	v_readfirstlane_b32 s55, v171
	v_lshl_add_u64 v[128:129], v[128:129], 1, v[130:131]
	s_mov_b32 m0, s55
	ds_read_b128 v[144:147], v170
	ds_read_b128 v[148:151], v170 offset:1024
	ds_read_b128 v[174:177], v170 offset:2048
	ds_read_b128 v[178:181], v170 offset:3072
	ds_read_b128 v[182:185], v162
	ds_read_b128 v[186:189], v162 offset:1024
	ds_read_b128 v[190:193], v161
	ds_read_b128 v[194:197], v161 offset:1024
	ds_read_b128 v[198:201], v160
	ds_read_b128 v[202:205], v160 offset:1024
	ds_read_b128 v[218:221], v159
	ds_read_b128 v[222:225], v159 offset:1024
	global_load_lds_dwordx4 v[128:129], off
	v_lshl_add_u64 v[128:129], s[58:59], 0, v[142:143]
	v_readfirstlane_b32 s55, v172
	v_lshl_add_u64 v[128:129], v[140:141], 1, v[128:129]
	s_mov_b32 m0, s55
	s_nop 0
	global_load_lds_dwordx4 v[128:129], off
	s_barrier
	s_waitcnt lgkmcnt(0)
	s_waitcnt lgkmcnt(0)
	v_mfma_f32_16x16x32_bf16 v[124:127], v[144:147], v[182:185], v[124:127]
	v_mfma_f32_16x16x32_bf16 v[120:123], v[174:177], v[182:185], v[120:123]
	v_mfma_f32_16x16x32_bf16 v[116:119], v[144:147], v[190:193], v[116:119]
	v_mfma_f32_16x16x32_bf16 v[112:115], v[174:177], v[190:193], v[112:115]
	v_mfma_f32_16x16x32_bf16 v[108:111], v[144:147], v[198:201], v[108:111]
	v_mfma_f32_16x16x32_bf16 v[104:107], v[174:177], v[198:201], v[104:107]
	v_mfma_f32_16x16x32_bf16 v[100:103], v[144:147], v[218:221], v[100:103]
	v_mfma_f32_16x16x32_bf16 v[96:99], v[174:177], v[218:221], v[96:99]
	v_mfma_f32_16x16x32_bf16 v[124:127], v[148:151], v[186:189], v[124:127]
	v_mfma_f32_16x16x32_bf16 v[120:123], v[178:181], v[186:189], v[120:123]
	v_mfma_f32_16x16x32_bf16 v[116:119], v[148:151], v[194:197], v[116:119]
	v_mfma_f32_16x16x32_bf16 v[112:115], v[178:181], v[194:197], v[112:115]
	v_mfma_f32_16x16x32_bf16 v[108:111], v[148:151], v[202:205], v[108:111]
	v_mfma_f32_16x16x32_bf16 v[104:107], v[178:181], v[202:205], v[104:107]
	v_mfma_f32_16x16x32_bf16 v[100:103], v[148:151], v[222:225], v[100:103]
	v_mfma_f32_16x16x32_bf16 v[96:99], v[178:181], v[222:225], v[96:99]
	s_barrier
	ds_read_b128 v[128:131], v168
	ds_read_b128 v[140:143], v168 offset:1024
	ds_read_b128 v[170:173], v168 offset:2048
	ds_read_b128 v[166:169], v168 offset:3072
	s_barrier
	s_waitcnt lgkmcnt(0)
	s_waitcnt lgkmcnt(0)
	v_mfma_f32_16x16x32_bf16 v[80:83], v[170:173], v[190:193], v[80:83]
	v_mfma_f32_16x16x32_bf16 v[72:75], v[170:173], v[198:201], v[72:75]
	v_mfma_f32_16x16x32_bf16 v[68:71], v[128:131], v[218:221], v[68:71]
	v_mfma_f32_16x16x32_bf16 v[64:67], v[170:173], v[218:221], v[64:67]
	v_mfma_f32_16x16x32_bf16 v[92:95], v[128:131], v[182:185], v[92:95]
	v_mfma_f32_16x16x32_bf16 v[88:91], v[170:173], v[182:185], v[88:91]
	v_mfma_f32_16x16x32_bf16 v[84:87], v[128:131], v[190:193], v[84:87]
	v_mfma_f32_16x16x32_bf16 v[80:83], v[166:169], v[194:197], v[80:83]
	v_mfma_f32_16x16x32_bf16 v[76:79], v[128:131], v[198:201], v[76:79]
	v_mfma_f32_16x16x32_bf16 v[72:75], v[166:169], v[202:205], v[72:75]
	v_mfma_f32_16x16x32_bf16 v[68:71], v[140:143], v[222:225], v[68:71]
	v_mfma_f32_16x16x32_bf16 v[64:67], v[166:169], v[222:225], v[64:67]
	v_mfma_f32_16x16x32_bf16 v[226:229], v[140:143], v[186:189], v[92:95]
	v_mfma_f32_16x16x32_bf16 v[182:185], v[166:169], v[186:189], v[88:91]
	v_mfma_f32_16x16x32_bf16 v[186:189], v[140:143], v[194:197], v[84:87]
	v_mfma_f32_16x16x32_bf16 v[190:193], v[140:143], v[202:205], v[76:79]
	s_barrier
	s_nop 0
	ds_read_b128 v[76:79], v162 offset:16384
	ds_read_b128 v[84:87], v162 offset:17408
	ds_read_b128 v[88:91], v161 offset:16384
	ds_read_b128 v[92:95], v161 offset:17408
	ds_read_b128 v[194:197], v160 offset:16384
	ds_read_b128 v[198:201], v160 offset:17408
	ds_read_b128 v[202:205], v159 offset:16384
	ds_read_b128 v[218:221], v159 offset:17408
	s_waitcnt vmcnt(4)
	s_barrier
; #define LDA(dst, b, h) UFOR(m, 4) UFOR(k, 2) \
;     dst[m][k] = *reinterpret_cast<const bf16x8*>((char*)SA(b, h) + lds_byte(wr * 64 + m * 16 + fr, k * 32 + fq * 8))
; #define LDB(dst, b, h) UFOR(n, 2) UFOR(k, 2) \
;     dst[n][k] = *reinterpret_cast<const bf16x8*>((char*)SB(b, h) + lds_byte(wc * 32 + n * 16 + fr, k * 32 + fq * 8))
; #define MMA(ai, bj, At, Bq) do { __builtin_amdgcn_s_setprio(1); \
;     UFOR(m, 4) UFOR(n, 2) UFOR(k, 2) \
;       acc[ai][bj][m][n] = __builtin_amdgcn_mfma_f32_16x16x32_bf16(Bq[n][k], At[m][k], acc[ai][bj][m][n], 0, 0, 0); \
;     __builtin_amdgcn_s_setprio(0); } while (0)
; #define WAIT_V(n) asm volatile("s_waitcnt vmcnt(" #n ")" ::: "memory")
; #define WAIT_L(n) asm volatile("s_waitcnt lgkmcnt(" #n ")" ::: "memory")
; #define BAR __builtin_amdgcn_s_barrier()
; template <int EPI, int K, int KL> ...
;     ...
;     LDA(At, 0, 1); WAIT_V(4); BAR; WAIT_L(0); MMA(1, 0, At, B0); MMA(1, 1, At, B1); BAR; }
;   { LDB(B0, 1, 0); LDA(At, 1, 0); WAIT_V(2); BAR; WAIT_L(0); MMA(0, 0, At, B0); BAR;
	s_waitcnt lgkmcnt(0)
	s_waitcnt lgkmcnt(0)
	v_mfma_f32_16x16x32_bf16 v[48:51], v[174:177], v[88:91], v[48:51]
	v_mfma_f32_16x16x32_bf16 v[40:43], v[174:177], v[194:197], v[40:43]
	v_mfma_f32_16x16x32_bf16 v[36:39], v[144:147], v[202:205], v[36:39]
	v_mfma_f32_16x16x32_bf16 v[32:35], v[174:177], v[202:205], v[32:35]
	v_mfma_f32_16x16x32_bf16 v[60:63], v[144:147], v[76:79], v[60:63]
	v_mfma_f32_16x16x32_bf16 v[56:59], v[174:177], v[76:79], v[56:59]
	v_mfma_f32_16x16x32_bf16 v[52:55], v[144:147], v[88:91], v[52:55]
	v_mfma_f32_16x16x32_bf16 v[48:51], v[178:181], v[92:95], v[48:51]
	v_mfma_f32_16x16x32_bf16 v[44:47], v[144:147], v[194:197], v[44:47]
	v_mfma_f32_16x16x32_bf16 v[40:43], v[178:181], v[198:201], v[40:43]
	v_mfma_f32_16x16x32_bf16 v[36:39], v[148:151], v[218:221], v[36:39]
	v_mfma_f32_16x16x32_bf16 v[32:35], v[178:181], v[218:221], v[32:35]
	v_mfma_f32_16x16x32_bf16 v[222:225], v[148:151], v[84:87], v[60:63]
	v_mfma_f32_16x16x32_bf16 v[230:233], v[178:181], v[84:87], v[56:59]
	v_mfma_f32_16x16x32_bf16 v[234:237], v[148:151], v[92:95], v[52:55]
	v_mfma_f32_16x16x32_bf16 v[238:241], v[148:151], v[198:201], v[44:47]
	v_mfma_f32_16x16x32_bf16 v[0:3], v[170:173], v[202:205], v[0:3]
	v_mfma_f32_16x16x32_bf16 v[28:31], v[128:131], v[76:79], v[28:31]
	v_mfma_f32_16x16x32_bf16 v[24:27], v[170:173], v[76:79], v[24:27]
	v_mfma_f32_16x16x32_bf16 v[20:23], v[128:131], v[88:91], v[20:23]
	v_mfma_f32_16x16x32_bf16 v[16:19], v[170:173], v[88:91], v[16:19]
	v_mfma_f32_16x16x32_bf16 v[12:15], v[128:131], v[194:197], v[12:15]
	v_mfma_f32_16x16x32_bf16 v[8:11], v[170:173], v[194:197], v[8:11]
	v_mfma_f32_16x16x32_bf16 v[4:7], v[128:131], v[202:205], v[4:7]
	v_mfma_f32_16x16x32_bf16 v[0:3], v[166:169], v[218:221], v[0:3]
	v_mfma_f32_16x16x32_bf16 v[144:147], v[140:143], v[84:87], v[28:31]
	v_mfma_f32_16x16x32_bf16 v[148:151], v[166:169], v[84:87], v[24:27]
	v_mfma_f32_16x16x32_bf16 v[174:177], v[140:143], v[92:95], v[20:23]
	v_mfma_f32_16x16x32_bf16 v[178:181], v[166:169], v[92:95], v[16:19]
	v_mfma_f32_16x16x32_bf16 v[242:245], v[140:143], v[198:201], v[12:15]
	v_mfma_f32_16x16x32_bf16 v[194:197], v[166:169], v[198:201], v[8:11]
	v_mfma_f32_16x16x32_bf16 v[128:131], v[140:143], v[218:221], v[4:7]
	s_barrier
	s_nop 0
	ds_read_b128 v[4:7], v165
	ds_read_b128 v[8:11], v165 offset:1024
	ds_read_b128 v[16:19], v165 offset:2048
	ds_read_b128 v[140:143], v165 offset:3072
	ds_read_b128 v[12:15], v162 offset:32768
	ds_read_b128 v[20:23], v162 offset:33792
	ds_read_b128 v[24:27], v161 offset:32768
	ds_read_b128 v[44:47], v161 offset:33792
	ds_read_b128 v[164:167], v160 offset:32768
	ds_read_b128 v[168:171], v160 offset:33792
	ds_read_b128 v[198:201], v159 offset:32768
	ds_read_b128 v[202:205], v159 offset:33792
	s_waitcnt vmcnt(2)
	s_barrier
	s_waitcnt lgkmcnt(0)
	s_waitcnt lgkmcnt(0)
	v_mfma_f32_16x16x32_bf16 v[28:31], v[4:7], v[12:15], v[124:127]
	v_mfma_f32_16x16x32_bf16 v[124:127], v[8:11], v[20:23], v[28:31]
	v_mfma_f32_16x16x32_bf16 v[28:31], v[16:19], v[12:15], v[120:123]
	v_mfma_f32_16x16x32_bf16 v[92:95], v[140:143], v[20:23], v[28:31]
	v_mfma_f32_16x16x32_bf16 v[28:31], v[4:7], v[24:27], v[116:119]
	v_mfma_f32_16x16x32_bf16 v[120:123], v[8:11], v[44:47], v[28:31]
	v_mfma_f32_16x16x32_bf16 v[28:31], v[16:19], v[24:27], v[112:115]
	v_mfma_f32_16x16x32_bf16 v[88:91], v[140:143], v[44:47], v[28:31]
	v_mfma_f32_16x16x32_bf16 v[28:31], v[4:7], v[164:167], v[108:111]
	v_mfma_f32_16x16x32_bf16 v[116:119], v[8:11], v[168:171], v[28:31]
	v_mfma_f32_16x16x32_bf16 v[28:31], v[16:19], v[164:167], v[104:107]
	v_mfma_f32_16x16x32_bf16 v[84:87], v[140:143], v[168:171], v[28:31]
	v_mfma_f32_16x16x32_bf16 v[28:31], v[4:7], v[198:201], v[100:103]
	v_mfma_f32_16x16x32_bf16 v[108:111], v[8:11], v[202:205], v[28:31]
	v_mfma_f32_16x16x32_bf16 v[28:31], v[16:19], v[198:201], v[96:99]
	v_mfma_f32_16x16x32_bf16 v[76:79], v[140:143], v[202:205], v[28:31]
	s_barrier
; #define LDA(dst, b, h) UFOR(m, 4) UFOR(k, 2) \
;     dst[m][k] = *reinterpret_cast<const bf16x8*>((char*)SA(b, h) + lds_byte(wr * 64 + m * 16 + fr, k * 32 + fq * 8))
; #define LDB(dst, b, h) UFOR(n, 2) UFOR(k, 2) \
;     dst[n][k] = *reinterpret_cast<const bf16x8*>((char*)SB(b, h) + lds_byte(wc * 32 + n * 16 + fr, k * 32 + fq * 8))
; #define MMA(ai, bj, At, Bq) do { __builtin_amdgcn_s_setprio(1); \
;     UFOR(m, 4) UFOR(n, 2) UFOR(k, 2) \
;       acc[ai][bj][m][n] = __builtin_amdgcn_mfma_f32_16x16x32_bf16(Bq[n][k], At[m][k], acc[ai][bj][m][n], 0, 0, 0); \
;     __builtin_amdgcn_s_setprio(0); } while (0)
; #define WAIT_V(n) asm volatile("s_waitcnt vmcnt(" #n ")" ::: "memory")
; #define WAIT_L(n) asm volatile("s_waitcnt lgkmcnt(" #n ")" ::: "memory")
; #define BAR __builtin_amdgcn_s_barrier()
; template <int EPI, int K, int KL> ...
;     ...
;     LDB(B1, 1, 1); WAIT_V(0); BAR; WAIT_L(0); MMA(0, 1, At, B1); BAR;
;     LDA(At, 1, 1); BAR; WAIT_L(0); MMA(1, 0, At, B0); MMA(1, 1, At, B1); BAR; }
;   if (wr == 0) BAR;
	ds_read_b128 v[218:221], v163
	ds_read_b128 v[246:249], v163 offset:1024
	ds_read_b128 v[136:139], v163 offset:2048
	ds_read_b128 v[208:211], v163 offset:3072
	s_waitcnt vmcnt(0)
	s_barrier
	s_waitcnt lgkmcnt(0)
	s_waitcnt lgkmcnt(0)
	v_mfma_f32_16x16x32_bf16 v[28:31], v[218:221], v[12:15], v[226:229]
	v_mfma_f32_16x16x32_bf16 v[12:15], v[136:139], v[12:15], v[182:185]
	v_mfma_f32_16x16x32_bf16 v[60:63], v[246:249], v[20:23], v[28:31]
	v_mfma_f32_16x16x32_bf16 v[28:31], v[208:211], v[20:23], v[12:15]
	v_mfma_f32_16x16x32_bf16 v[12:15], v[218:221], v[24:27], v[186:189]
	v_mfma_f32_16x16x32_bf16 v[56:59], v[246:249], v[44:47], v[12:15]
	v_mfma_f32_16x16x32_bf16 v[12:15], v[136:139], v[24:27], v[80:83]
	v_mfma_f32_16x16x32_bf16 v[24:27], v[208:211], v[44:47], v[12:15]
	v_mfma_f32_16x16x32_bf16 v[12:15], v[218:221], v[164:167], v[190:193]
	v_mfma_f32_16x16x32_bf16 v[52:55], v[246:249], v[168:171], v[12:15]
	v_mfma_f32_16x16x32_bf16 v[12:15], v[136:139], v[164:167], v[72:75]
	v_mfma_f32_16x16x32_bf16 v[20:23], v[208:211], v[168:171], v[12:15]
	v_mfma_f32_16x16x32_bf16 v[12:15], v[218:221], v[198:201], v[68:71]
	v_mfma_f32_16x16x32_bf16 v[44:47], v[246:249], v[202:205], v[12:15]
	v_mfma_f32_16x16x32_bf16 v[12:15], v[136:139], v[198:201], v[64:67]
	v_mfma_f32_16x16x32_bf16 v[12:15], v[208:211], v[202:205], v[12:15]
	s_barrier
	ds_read_b128 v[164:167], v162 offset:49152
	ds_read_b128 v[168:171], v162 offset:50176
	ds_read_b128 v[182:185], v161 offset:49152
	ds_read_b128 v[186:189], v161 offset:50176
	ds_read_b128 v[190:193], v160 offset:49152
	ds_read_b128 v[160:163], v160 offset:50176
	ds_read_b128 v[198:201], v159 offset:49152
	ds_read_b128 v[156:159], v159 offset:50176
	s_barrier
	s_waitcnt lgkmcnt(0)
	s_waitcnt lgkmcnt(0)
	v_mfma_f32_16x16x32_bf16 v[64:67], v[4:7], v[164:167], v[222:225]
	v_mfma_f32_16x16x32_bf16 v[112:115], v[8:11], v[168:171], v[64:67]
	v_mfma_f32_16x16x32_bf16 v[64:67], v[16:19], v[164:167], v[230:233]
	v_mfma_f32_16x16x32_bf16 v[48:51], v[16:19], v[182:185], v[48:51]
	v_mfma_f32_16x16x32_bf16 v[80:83], v[140:143], v[168:171], v[64:67]
	v_mfma_f32_16x16x32_bf16 v[64:67], v[4:7], v[182:185], v[234:237]
	v_mfma_f32_16x16x32_bf16 v[72:75], v[140:143], v[186:189], v[48:51]
	v_mfma_f32_16x16x32_bf16 v[48:51], v[4:7], v[190:193], v[238:241]
	v_mfma_f32_16x16x32_bf16 v[4:7], v[4:7], v[198:201], v[36:39]
	v_mfma_f32_16x16x32_bf16 v[40:43], v[16:19], v[190:193], v[40:43]
	v_mfma_f32_16x16x32_bf16 v[96:99], v[8:11], v[156:159], v[4:7]
	v_mfma_f32_16x16x32_bf16 v[4:7], v[16:19], v[198:201], v[32:35]
	v_mfma_f32_16x16x32_bf16 v[104:107], v[8:11], v[186:189], v[64:67]
	v_mfma_f32_16x16x32_bf16 v[100:103], v[8:11], v[160:163], v[48:51]
	v_mfma_f32_16x16x32_bf16 v[68:71], v[140:143], v[160:163], v[40:43]
	v_mfma_f32_16x16x32_bf16 v[64:67], v[140:143], v[156:159], v[4:7]
	v_mfma_f32_16x16x32_bf16 v[4:7], v[218:221], v[164:167], v[144:147]
	v_mfma_f32_16x16x32_bf16 v[48:51], v[246:249], v[168:171], v[4:7]
	v_mfma_f32_16x16x32_bf16 v[4:7], v[136:139], v[164:167], v[148:151]
	v_mfma_f32_16x16x32_bf16 v[16:19], v[208:211], v[168:171], v[4:7]
	v_mfma_f32_16x16x32_bf16 v[4:7], v[218:221], v[182:185], v[174:177]
	v_mfma_f32_16x16x32_bf16 v[40:43], v[246:249], v[186:189], v[4:7]
	v_mfma_f32_16x16x32_bf16 v[4:7], v[136:139], v[182:185], v[178:181]
	v_mfma_f32_16x16x32_bf16 v[8:11], v[208:211], v[186:189], v[4:7]
	v_mfma_f32_16x16x32_bf16 v[4:7], v[218:221], v[190:193], v[242:245]
	v_mfma_f32_16x16x32_bf16 v[36:39], v[246:249], v[160:163], v[4:7]
	v_mfma_f32_16x16x32_bf16 v[4:7], v[136:139], v[190:193], v[194:197]
	v_mfma_f32_16x16x32_bf16 v[32:35], v[218:221], v[198:201], v[128:131]
	v_mfma_f32_16x16x32_bf16 v[0:3], v[136:139], v[198:201], v[0:3]
	v_mfma_f32_16x16x32_bf16 v[4:7], v[208:211], v[160:163], v[4:7]
	v_mfma_f32_16x16x32_bf16 v[32:35], v[246:249], v[156:159], v[32:35]
	v_mfma_f32_16x16x32_bf16 v[0:3], v[208:211], v[156:159], v[0:3]
	s_movk_i32 s55, 0x100
	v_cmp_gt_u32_e32 vcc, s55, v154
	s_barrier
	s_and_saveexec_b64 s[58:59], vcc
	s_cbranch_execz .LBB0_943
	s_barrier

; #define STAGE(P, BASE, br, kt) STAGET(tid_, P, BASE, br, kt)
; #define WAIT_V(n) asm volatile("s_waitcnt vmcnt(" #n ")" ::: "memory")
; #define BAR __builtin_amdgcn_s_barrier()
; template <int EPI, int K, int KL> ...
;     ...
;   if (wr == 1) BAR;
;   WAIT_V(4); BAR;
;   STAGE(SB(1, 0), Bt, bcol, 1); STAGE(SA(1, 0), A, brow, 1); STAGE(SB(1, 1), Bt, bcol + HALF, 1);
;   WAIT_V(6); BAR;
.LBB0_1106:
	s_or_b64 exec, exec, s[40:41]
	v_add_u32_e32 v2, v1, v2
	v_and_b32_e32 v2, 0xfffffc00, v2
	v_sub_u32_e32 v2, v1, v2
	s_waitcnt vmcnt(0)
	v_lshrrev_b32_e32 v4, 4, v2
	v_add_u32_e32 v3, v152, v3
	v_bitop3_b32 v4, v4, v2, 32 bitop3:0x6c
	v_ashrrev_i32_e32 v2, 31, v2
	v_ashrrev_i32_e32 v3, 6, v3
	v_lshrrev_b32_e32 v2, 26, v2
	v_lshlrev_b32_e32 v5, 3, v3
	v_add_u32_e32 v2, v4, v2
	v_and_b32_e32 v5, -16, v5
	v_ashrrev_i32_e32 v6, 6, v2
	v_add_u32_e32 v2, v6, v5
	v_mul_i32_i24_e32 v5, 64, v6
	s_ashr_i32 s57, s56, 31
	v_lshlrev_b32_e32 v3, 5, v3
	v_sub_u32_e32 v4, v4, v5
	s_lshl_b64 s[58:59], s[56:57], 12
	v_readlane_b32 s70, v254, 20
	v_and_b32_e32 v3, 32, v3
	v_ashrrev_i16_sdwa v4, v207, sext(v4) dst_sel:DWORD dst_unused:UNUSED_PAD src0_sel:DWORD src1_sel:BYTE_0
	v_readlane_b32 s71, v254, 21
	s_add_u32 s40, s70, s58
	v_add_u32_sdwa v128, v3, sext(v4) dst_sel:DWORD dst_unused:UNUSED_PAD src0_sel:DWORD src1_sel:WORD_0
	v_ashrrev_i32_e32 v3, 31, v2
	s_addc_u32 s41, s71, s59
	v_lshlrev_b64 v[130:131], 12, v[2:3]
	v_ashrrev_i32_e32 v129, 31, v128
	v_readlane_b32 s61, v254, 45
	v_lshl_add_u64 v[2:3], s[40:41], 0, v[130:131]
	v_lshlrev_b64 v[4:5], 1, v[128:129]
	v_add_u32_e32 v165, s61, v1
	v_lshl_add_u64 v[2:3], v[2:3], 0, v[4:5]
	s_mov_b64 s[74:75], 0x80
	v_readfirstlane_b32 s53, v165
	v_lshl_add_u64 v[2:3], v[2:3], 0, s[74:75]
	s_mov_b32 m0, s53
	s_waitcnt vmcnt(4)
	s_barrier
	global_load_lds_dwordx4 v[2:3], off
	v_ashrrev_i32_e32 v2, 31, v0
	v_lshrrev_b32_e32 v2, 22, v2
	v_add_u32_e32 v2, v0, v2
	v_ashrrev_i32_e32 v3, 10, v2
	v_mul_i32_i24_e32 v2, 0x400, v3
	v_sub_u32_e32 v2, v0, v2
	v_lshrrev_b32_e32 v6, 4, v2
	v_bitop3_b32 v6, v6, v2, 32 bitop3:0x6c
	v_ashrrev_i32_e32 v7, 31, v6
	v_lshrrev_b32_e32 v7, 26, v7
	v_add_u32_e32 v7, v6, v7
	v_lshlrev_b32_e32 v2, 3, v3
	v_ashrrev_i32_e32 v8, 6, v7
	v_and_b32_e32 v7, 0xc0, v7
	v_and_b32_e32 v2, -16, v2
	v_lshlrev_b32_e32 v3, 5, v3
	v_sub_u32_e32 v6, v6, v7
	v_add_u32_e32 v2, v8, v2
	v_and_b32_e32 v3, 32, v3
	v_ashrrev_i16_sdwa v6, v207, sext(v6) dst_sel:DWORD dst_unused:UNUSED_PAD src0_sel:DWORD src1_sel:BYTE_0
	v_add_u32_sdwa v140, v3, sext(v6) dst_sel:DWORD dst_unused:UNUSED_PAD src0_sel:DWORD src1_sel:WORD_0
	v_ashrrev_i32_e32 v3, 31, v2
	v_lshlrev_b64 v[142:143], 12, v[2:3]
	v_ashrrev_i32_e32 v141, 31, v140
	v_add_u32_e32 v8, s61, v0
	v_lshl_add_u64 v[2:3], s[40:41], 0, v[142:143]
	v_lshlrev_b64 v[6:7], 1, v[140:141]
	v_readfirstlane_b32 s40, v8
	s_lshl_b64 s[62:63], s[42:43], 12
	v_lshl_add_u64 v[2:3], v[2:3], 0, v[6:7]
	s_mov_b32 m0, s40
	s_add_u32 s40, s66, s62
	v_lshl_add_u64 v[2:3], v[2:3], 0, s[74:75]
	s_addc_u32 s41, s67, s63
	global_load_lds_dwordx4 v[2:3], off
	v_lshl_add_u64 v[2:3], s[40:41], 0, v[130:131]
	v_add_u32_e32 v167, 0x8000, v158
	v_lshl_add_u64 v[2:3], v[2:3], 0, v[4:5]
	v_readfirstlane_b32 s53, v167
	s_bitset1_b32 s56, 7
	v_lshl_add_u64 v[2:3], v[2:3], 0, s[74:75]
	s_mov_b32 m0, s53
	s_ashr_i32 s57, s56, 31
	global_load_lds_dwordx4 v[2:3], off
	v_lshl_add_u64 v[2:3], s[40:41], 0, v[142:143]
	v_add_u32_e32 v168, 0xa000, v158
	s_lshl_b64 s[56:57], s[56:57], 12
	v_lshl_add_u64 v[2:3], v[2:3], 0, v[6:7]
	v_readfirstlane_b32 s53, v168
	s_add_u32 s56, s70, s56
	v_lshl_add_u64 v[2:3], v[2:3], 0, s[74:75]
	s_mov_b32 m0, s53
	s_addc_u32 s57, s71, s57
	v_readlane_b32 s70, v254, 46
	global_load_lds_dwordx4 v[2:3], off
	v_lshl_add_u64 v[2:3], s[56:57], 0, v[130:131]
	v_add_u32_e32 v170, s70, v1
	v_lshl_add_u64 v[2:3], v[2:3], 0, v[4:5]
	v_readfirstlane_b32 s53, v170
	v_lshl_add_u64 v[2:3], v[2:3], 0, s[74:75]
	s_mov_b32 m0, s53
	v_add_u32_e32 v0, s70, v0
	global_load_lds_dwordx4 v[2:3], off
	v_lshl_add_u64 v[2:3], s[56:57], 0, v[142:143]
	v_lshl_add_u64 v[2:3], v[2:3], 0, v[6:7]
	v_readfirstlane_b32 s53, v0
	v_lshl_add_u64 v[2:3], v[2:3], 0, s[74:75]
	s_mov_b32 m0, s53
	v_and_b32_e32 v154, 15, v152
	global_load_lds_dwordx4 v[2:3], off
	v_lshlrev_b32_e32 v132, 2, v152
	v_and_b32_e32 v156, 48, v152
	v_lshlrev_b32_e32 v0, 6, v154
	v_and_b32_e32 v1, 32, v132
	v_bitop3_b32 v0, v0, v1, v156 bitop3:0x36
	v_readlane_b32 s53, v254, 43
	v_add_u32_e32 v9, s61, v0
	v_add_u32_e32 v10, s70, v0
	v_add_u32_e32 v3, s53, v0
	v_readlane_b32 s53, v254, 44
	v_add_u32_e32 v12, 0, v0
	v_bfe_u32 v155, v152, 6, 2
	v_add_u32_e32 v8, s53, v0
	v_lshlrev_b32_e32 v0, 6, v152
	s_movk_i32 s53, 0x3c0
	v_and_or_b32 v0, v0, s53, v156
	v_xad_u32 v13, v0, v1, 0
	v_lshl_add_u64 v[0:1], s[58:59], 0, v[130:131]
	v_lshl_add_u64 v[144:145], v[0:1], 0, v[4:5]
	v_lshl_add_u64 v[0:1], s[58:59], 0, v[142:143]
	v_lshl_add_u64 v[146:147], v[0:1], 0, v[6:7]
	v_lshl_add_u64 v[0:1], s[62:63], 0, v[130:131]
	s_waitcnt vmcnt(6)
; #define STAGE(P, BASE, br, kt) STAGET(tid_, P, BASE, br, kt)
; #define LDA(dst, b, h) UFOR(m, 4) UFOR(k, 2) \
;     dst[m][k] = *reinterpret_cast<const bf16x8*>((char*)SA(b, h) + lds_byte(wr * 64 + m * 16 + fr, k * 32 + fq * 8))
; #define LDB(dst, b, h) UFOR(n, 2) UFOR(k, 2) \
;     dst[n][k] = *reinterpret_cast<const bf16x8*>((char*)SB(b, h) + lds_byte(wc * 32 + n * 16 + fr, k * 32 + fq * 8))
; #define MMA(ai, bj, At, Bq) do { __builtin_amdgcn_s_setprio(1); \
;     UFOR(m, 4) UFOR(n, 2) UFOR(k, 2) \
;       acc[ai][bj][m][n] = __builtin_amdgcn_mfma_f32_16x16x32_bf16(Bq[n][k], At[m][k], acc[ai][bj][m][n], 0, 0, 0); \
;     __builtin_amdgcn_s_setprio(0); } while (0)
; #define WAIT_V(n) asm volatile("s_waitcnt vmcnt(" #n ")" ::: "memory")
; #define WAIT_L(n) asm volatile("s_waitcnt lgkmcnt(" #n ")" ::: "memory")
; #define BAR __builtin_amdgcn_s_barrier()
; #define SCHED __builtin_amdgcn_sched_barrier(0)
; template <int EPI, int K, int KL> ...
;     ...
;   f32x4 acc[2][2][4][2] = {};
;   bf16x8 At[4][2], B0[2][2], B1[2][2];
;   const int nt = KL / BK;
;   if (own_prologue) {
;     STAGE(SB(0, 0), Bt, bcol, 0); STAGE(SA(0, 0), A, brow, 0);
;     STAGE(SB(0, 1), Bt, bcol + HALF, 0); STAGE(SA(0, 1), A, brow + HALF, 0);
;   }
;   if (wr == 1) BAR;
;   WAIT_V(4); BAR;
;   STAGE(SB(1, 0), Bt, bcol, 1); STAGE(SA(1, 0), A, brow, 1); STAGE(SB(1, 1), Bt, bcol + HALF, 1);
;   WAIT_V(6); BAR;
;   for (int t = 0; t < nt - 2; t += 2) {
;     LDB(B0, 0, 0); SCHED; LDA(At, 0, 0); STAGE(SA(1, 1), A, brow + HALF, t + 1);
;     WAIT_L(8); BAR; WAIT_L(0); MMA(0, 0, At, B0); BAR; SCHED;
	v_lshlrev_b32_e32 v11, 13, v153
	v_lshl_add_u64 v[148:149], v[0:1], 0, v[4:5]
	v_lshl_add_u64 v[0:1], s[62:63], 0, v[142:143]
	v_lshlrev_b32_e32 v2, 12, v155
	v_or_b32_e32 v14, 0x800, v11
	v_or_b32_e32 v15, 0x1000, v11
	v_or_b32_e32 v16, 0x1800, v11
	v_lshl_add_u64 v[150:151], v[0:1], 0, v[6:7]
	v_mov_b32_e32 v0, 0
	s_mov_b32 s53, -2
	v_add_u32_e32 v171, v3, v2
	v_add_u32_e32 v163, v12, v11
	v_add_u32_e32 v162, v13, v14
	v_add_u32_e32 v161, v13, v15
	v_add_u32_e32 v160, v13, v16
	v_add_u32_e32 v169, v8, v2
	v_add_u32_e32 v166, v9, v2
	v_add_u32_e32 v164, v10, v2
	v_mov_b32_e32 v1, v0
	v_mov_b32_e32 v2, v0
	v_mov_b32_e32 v3, v0
	v_mov_b32_e32 v4, v0
	v_mov_b32_e32 v5, v0
	v_mov_b32_e32 v6, v0
	v_mov_b32_e32 v7, v0
	v_mov_b32_e32 v8, v0
	v_mov_b32_e32 v9, v0
	v_mov_b32_e32 v10, v0
	v_mov_b32_e32 v11, v0
	v_mov_b32_e32 v16, v0
	v_mov_b32_e32 v17, v0
	v_mov_b32_e32 v18, v0
	v_mov_b32_e32 v19, v0
	v_mov_b32_e32 v28, v0
	v_mov_b32_e32 v29, v0
	v_mov_b32_e32 v30, v0
	v_mov_b32_e32 v31, v0
	v_mov_b32_e32 v40, v0
	v_mov_b32_e32 v41, v0
	v_mov_b32_e32 v42, v0
	v_mov_b32_e32 v43, v0
	v_mov_b32_e32 v52, v0
	v_mov_b32_e32 v53, v0
	v_mov_b32_e32 v54, v0
	v_mov_b32_e32 v55, v0
	v_mov_b32_e32 v64, v0
	v_mov_b32_e32 v65, v0
	v_mov_b32_e32 v66, v0
	v_mov_b32_e32 v67, v0
	v_mov_b32_e32 v12, v0
	v_mov_b32_e32 v13, v0
	v_mov_b32_e32 v14, v0
	v_mov_b32_e32 v15, v0
	v_mov_b32_e32 v24, v0
	v_mov_b32_e32 v25, v0
	v_mov_b32_e32 v26, v0
	v_mov_b32_e32 v27, v0
	v_mov_b32_e32 v36, v0
	v_mov_b32_e32 v37, v0
	v_mov_b32_e32 v38, v0
	v_mov_b32_e32 v39, v0
	v_mov_b32_e32 v48, v0
	v_mov_b32_e32 v49, v0
	v_mov_b32_e32 v50, v0
	v_mov_b32_e32 v51, v0
	v_mov_b32_e32 v60, v0
	v_mov_b32_e32 v61, v0
	v_mov_b32_e32 v62, v0
	v_mov_b32_e32 v63, v0
	v_mov_b32_e32 v72, v0
	v_mov_b32_e32 v73, v0
	v_mov_b32_e32 v74, v0
	v_mov_b32_e32 v75, v0
	v_mov_b32_e32 v80, v0
	v_mov_b32_e32 v81, v0
	v_mov_b32_e32 v82, v0
	v_mov_b32_e32 v83, v0
	v_mov_b32_e32 v88, v0
	v_mov_b32_e32 v89, v0
	v_mov_b32_e32 v90, v0
	v_mov_b32_e32 v91, v0
	v_mov_b32_e32 v20, v0
	v_mov_b32_e32 v21, v0
	v_mov_b32_e32 v22, v0
	v_mov_b32_e32 v23, v0
	v_mov_b32_e32 v32, v0
	v_mov_b32_e32 v33, v0
	v_mov_b32_e32 v34, v0
	v_mov_b32_e32 v35, v0
	v_mov_b32_e32 v44, v0
	v_mov_b32_e32 v45, v0
	v_mov_b32_e32 v46, v0
	v_mov_b32_e32 v47, v0
	v_mov_b32_e32 v56, v0
	v_mov_b32_e32 v57, v0
	v_mov_b32_e32 v58, v0
	v_mov_b32_e32 v59, v0
	v_mov_b32_e32 v68, v0
	v_mov_b32_e32 v69, v0
	v_mov_b32_e32 v70, v0
	v_mov_b32_e32 v71, v0
	v_mov_b32_e32 v76, v0
	v_mov_b32_e32 v77, v0
	v_mov_b32_e32 v78, v0
	v_mov_b32_e32 v79, v0
	v_mov_b32_e32 v84, v0
	v_mov_b32_e32 v85, v0
	v_mov_b32_e32 v86, v0
	v_mov_b32_e32 v87, v0
	v_mov_b32_e32 v92, v0
	v_mov_b32_e32 v93, v0
	v_mov_b32_e32 v94, v0
	v_mov_b32_e32 v95, v0
	v_mov_b32_e32 v96, v0
	v_mov_b32_e32 v97, v0
	v_mov_b32_e32 v98, v0
	v_mov_b32_e32 v99, v0
	v_mov_b32_e32 v100, v0
	v_mov_b32_e32 v101, v0
	v_mov_b32_e32 v102, v0
	v_mov_b32_e32 v103, v0
	v_mov_b32_e32 v104, v0
	v_mov_b32_e32 v105, v0
	v_mov_b32_e32 v106, v0
	v_mov_b32_e32 v107, v0
	v_mov_b32_e32 v108, v0
	v_mov_b32_e32 v109, v0
	v_mov_b32_e32 v110, v0
	v_mov_b32_e32 v111, v0
	v_mov_b32_e32 v112, v0
	v_mov_b32_e32 v113, v0
	v_mov_b32_e32 v114, v0
	v_mov_b32_e32 v115, v0
	v_mov_b32_e32 v116, v0
	v_mov_b32_e32 v117, v0
	v_mov_b32_e32 v118, v0
	v_mov_b32_e32 v119, v0
	v_mov_b32_e32 v120, v0
	v_mov_b32_e32 v121, v0
	v_mov_b32_e32 v122, v0
	v_mov_b32_e32 v123, v0
	v_mov_b32_e32 v124, v0
	v_mov_b32_e32 v125, v0
	v_mov_b32_e32 v126, v0
	v_mov_b32_e32 v127, v0
.Lkrot_1107:
	s_barrier
.LBB0_1107:
	ds_read_b128 v[136:139], v171
	ds_read_b128 v[174:177], v171 offset:1024
	ds_read_b128 v[178:181], v171 offset:2048
	ds_read_b128 v[182:185], v171 offset:3072
	v_add_u32_e32 v172, 0xc000, v158
	v_lshl_add_u64 v[214:215], s[92:93], 0, v[148:149]
	v_readfirstlane_b32 s56, v172
	v_lshl_add_u64 v[216:217], v[214:215], 0, s[88:89]
	s_mov_b32 m0, s56
	v_add_u32_e32 v173, 0xe000, v158
	ds_read_b128 v[186:189], v163
	ds_read_b128 v[190:193], v163 offset:1024
	ds_read_b128 v[194:197], v162
	ds_read_b128 v[198:201], v162 offset:1024
	ds_read_b128 v[202:205], v161
	ds_read_b128 v[208:211], v161 offset:1024
	ds_read_b128 v[218:221], v160
	ds_read_b128 v[222:225], v160 offset:1024
	global_load_lds_dwordx4 v[216:217], off
	v_lshl_add_u64 v[216:217], s[92:93], 0, v[150:151]
	v_readfirstlane_b32 s56, v173
	v_lshl_add_u64 v[226:227], v[216:217], 0, s[88:89]
	s_mov_b32 m0, s56
	s_nop 0
	global_load_lds_dwordx4 v[226:227], off
	s_waitcnt lgkmcnt(8)
	s_barrier
	s_waitcnt lgkmcnt(0)
	s_waitcnt lgkmcnt(0)
	v_mfma_f32_16x16x32_bf16 v[0:3], v[136:139], v[186:189], v[0:3]
	v_mfma_f32_16x16x32_bf16 v[4:7], v[178:181], v[186:189], v[4:7]
	v_mfma_f32_16x16x32_bf16 v[8:11], v[136:139], v[194:197], v[8:11]
	v_mfma_f32_16x16x32_bf16 v[16:19], v[178:181], v[194:197], v[16:19]
	v_mfma_f32_16x16x32_bf16 v[28:31], v[136:139], v[202:205], v[28:31]
	v_mfma_f32_16x16x32_bf16 v[40:43], v[178:181], v[202:205], v[40:43]
	v_mfma_f32_16x16x32_bf16 v[52:55], v[136:139], v[218:221], v[52:55]
	v_mfma_f32_16x16x32_bf16 v[64:67], v[178:181], v[218:221], v[64:67]
	v_mfma_f32_16x16x32_bf16 v[0:3], v[174:177], v[190:193], v[0:3]
	v_mfma_f32_16x16x32_bf16 v[4:7], v[182:185], v[190:193], v[4:7]
	v_mfma_f32_16x16x32_bf16 v[8:11], v[174:177], v[198:201], v[8:11]
	v_mfma_f32_16x16x32_bf16 v[16:19], v[182:185], v[198:201], v[16:19]
	v_mfma_f32_16x16x32_bf16 v[28:31], v[174:177], v[208:211], v[28:31]
	v_mfma_f32_16x16x32_bf16 v[40:43], v[182:185], v[208:211], v[40:43]
	v_mfma_f32_16x16x32_bf16 v[52:55], v[174:177], v[222:225], v[52:55]
	v_mfma_f32_16x16x32_bf16 v[64:67], v[182:185], v[222:225], v[64:67]
	s_barrier
; #define STAGE(P, BASE, br, kt) STAGET(tid_, P, BASE, br, kt)
; #define LDA(dst, b, h) UFOR(m, 4) UFOR(k, 2) \
;     dst[m][k] = *reinterpret_cast<const bf16x8*>((char*)SA(b, h) + lds_byte(wr * 64 + m * 16 + fr, k * 32 + fq * 8))
; #define LDB(dst, b, h) UFOR(n, 2) UFOR(k, 2) \
;     dst[n][k] = *reinterpret_cast<const bf16x8*>((char*)SB(b, h) + lds_byte(wc * 32 + n * 16 + fr, k * 32 + fq * 8))
; #define MMA(ai, bj, At, Bq) do { __builtin_amdgcn_s_setprio(1); \
;     UFOR(m, 4) UFOR(n, 2) UFOR(k, 2) \
;       acc[ai][bj][m][n] = __builtin_amdgcn_mfma_f32_16x16x32_bf16(Bq[n][k], At[m][k], acc[ai][bj][m][n], 0, 0, 0); \
;     __builtin_amdgcn_s_setprio(0); } while (0)
; #define WAIT_V(n) asm volatile("s_waitcnt vmcnt(" #n ")" ::: "memory")
; #define WAIT_L(n) asm volatile("s_waitcnt lgkmcnt(" #n ")" ::: "memory")
; #define BAR __builtin_amdgcn_s_barrier()
; #define SCHED __builtin_amdgcn_sched_barrier(0)
; template <int EPI, int K, int KL> ...
;     ...
;     LDB(B1, 0, 1); STAGE(SB(0, 0), Bt, bcol, t + 2);
;     BAR; WAIT_L(0); MMA(0, 1, At, B1); BAR;
;     LDA(At, 0, 1); STAGE(SA(0, 0), A, brow, t + 2);
;     BAR; WAIT_L(0); MMA(1, 0, At, B0); BAR; SCHED;
;     STAGE(SB(0, 1), Bt, bcol + HALF, t + 2);
;     WAIT_V(6); BAR; MMA(1, 1, At, B1); BAR;
;     LDB(B0, 1, 0); SCHED; LDA(At, 1, 0); STAGE(SA(0, 1), A, brow + HALF, t + 2);
;     WAIT_L(8); BAR; WAIT_L(0); MMA(0, 0, At, B0); BAR; SCHED;
	v_lshl_add_u64 v[242:243], s[92:93], 0, v[144:145]
	v_readfirstlane_b32 s56, v157
	v_lshl_add_u64 v[244:245], v[242:243], 0, s[2:3]
	s_mov_b32 m0, s56
	v_add_u32_e32 v134, 0x2000, v157
	ds_read_b128 v[226:229], v169
	ds_read_b128 v[230:233], v169 offset:1024
	ds_read_b128 v[234:237], v169 offset:2048
	ds_read_b128 v[238:241], v169 offset:3072
	global_load_lds_dwordx4 v[244:245], off
	v_lshl_add_u64 v[244:245], s[92:93], 0, v[146:147]
	v_readfirstlane_b32 s56, v134
	v_lshl_add_u64 v[246:247], v[244:245], 0, s[2:3]
	s_mov_b32 m0, s56
	s_nop 0
	global_load_lds_dwordx4 v[246:247], off
	s_barrier
	s_waitcnt lgkmcnt(0)
	s_waitcnt lgkmcnt(0)
	v_mfma_f32_16x16x32_bf16 v[12:15], v[226:229], v[186:189], v[12:15]
	v_mfma_f32_16x16x32_bf16 v[24:27], v[234:237], v[186:189], v[24:27]
	v_mfma_f32_16x16x32_bf16 v[36:39], v[226:229], v[194:197], v[36:39]
	v_mfma_f32_16x16x32_bf16 v[48:51], v[234:237], v[194:197], v[48:51]
	v_mfma_f32_16x16x32_bf16 v[60:63], v[226:229], v[202:205], v[60:63]
	v_mfma_f32_16x16x32_bf16 v[72:75], v[234:237], v[202:205], v[72:75]
	v_mfma_f32_16x16x32_bf16 v[80:83], v[226:229], v[218:221], v[80:83]
	v_mfma_f32_16x16x32_bf16 v[88:91], v[234:237], v[218:221], v[88:91]
	v_mfma_f32_16x16x32_bf16 v[12:15], v[230:233], v[190:193], v[12:15]
	v_mfma_f32_16x16x32_bf16 v[24:27], v[238:241], v[190:193], v[24:27]
	v_mfma_f32_16x16x32_bf16 v[36:39], v[230:233], v[198:201], v[36:39]
	v_mfma_f32_16x16x32_bf16 v[48:51], v[238:241], v[198:201], v[48:51]
	v_mfma_f32_16x16x32_bf16 v[60:63], v[230:233], v[208:211], v[60:63]
	v_mfma_f32_16x16x32_bf16 v[72:75], v[238:241], v[208:211], v[72:75]
	v_mfma_f32_16x16x32_bf16 v[80:83], v[230:233], v[222:225], v[80:83]
	v_mfma_f32_16x16x32_bf16 v[88:91], v[238:241], v[222:225], v[88:91]
	v_readfirstlane_b32 s56, v158
	v_add_u32_e32 v134, 0x2000, v158
	v_lshl_add_u64 v[246:247], v[214:215], 0, s[8:9]
	s_mov_b32 m0, s56
	v_readfirstlane_b32 s56, v134
	s_barrier
	ds_read_b128 v[186:189], v163 offset:16384
	ds_read_b128 v[190:193], v163 offset:17408
	ds_read_b128 v[194:197], v162 offset:16384
	ds_read_b128 v[198:201], v162 offset:17408
	ds_read_b128 v[202:205], v161 offset:16384
	ds_read_b128 v[208:211], v161 offset:17408
	ds_read_b128 v[218:221], v160 offset:16384
	ds_read_b128 v[222:225], v160 offset:17408
	global_load_lds_dwordx4 v[246:247], off
	v_lshl_add_u64 v[246:247], v[216:217], 0, s[8:9]
	s_mov_b32 m0, s56
	s_nop 0
	global_load_lds_dwordx4 v[246:247], off
	s_barrier
	s_waitcnt lgkmcnt(0)
	s_waitcnt lgkmcnt(0)
	v_mfma_f32_16x16x32_bf16 v[20:23], v[136:139], v[186:189], v[20:23]
	v_mfma_f32_16x16x32_bf16 v[32:35], v[178:181], v[186:189], v[32:35]
	v_mfma_f32_16x16x32_bf16 v[44:47], v[136:139], v[194:197], v[44:47]
	v_mfma_f32_16x16x32_bf16 v[56:59], v[178:181], v[194:197], v[56:59]
	v_mfma_f32_16x16x32_bf16 v[68:71], v[136:139], v[202:205], v[68:71]
	v_mfma_f32_16x16x32_bf16 v[76:79], v[178:181], v[202:205], v[76:79]
	v_mfma_f32_16x16x32_bf16 v[84:87], v[136:139], v[218:221], v[84:87]
	v_mfma_f32_16x16x32_bf16 v[92:95], v[178:181], v[218:221], v[92:95]
	v_mfma_f32_16x16x32_bf16 v[20:23], v[174:177], v[190:193], v[20:23]
	v_mfma_f32_16x16x32_bf16 v[32:35], v[182:185], v[190:193], v[32:35]
	v_mfma_f32_16x16x32_bf16 v[44:47], v[174:177], v[198:201], v[44:47]
	v_mfma_f32_16x16x32_bf16 v[56:59], v[182:185], v[198:201], v[56:59]
	v_mfma_f32_16x16x32_bf16 v[68:71], v[174:177], v[208:211], v[68:71]
	v_mfma_f32_16x16x32_bf16 v[76:79], v[182:185], v[208:211], v[76:79]
	v_mfma_f32_16x16x32_bf16 v[84:87], v[174:177], v[222:225], v[84:87]
	v_mfma_f32_16x16x32_bf16 v[92:95], v[182:185], v[222:225], v[92:95]
	s_barrier
	v_readfirstlane_b32 s56, v159
	v_add_u32_e32 v134, 0x2000, v159
	v_lshl_add_u64 v[136:137], v[242:243], 0, s[96:97]
	s_mov_b32 m0, s56
	v_readfirstlane_b32 s56, v134
	global_load_lds_dwordx4 v[136:137], off
	v_lshl_add_u64 v[136:137], v[244:245], 0, s[96:97]
	s_mov_b32 m0, s56
	s_nop 0
	global_load_lds_dwordx4 v[136:137], off
	s_waitcnt vmcnt(6)
	s_barrier
	v_mfma_f32_16x16x32_bf16 v[96:99], v[226:229], v[186:189], v[96:99]
	v_mfma_f32_16x16x32_bf16 v[100:103], v[234:237], v[186:189], v[100:103]
	v_mfma_f32_16x16x32_bf16 v[104:107], v[226:229], v[194:197], v[104:107]
	v_mfma_f32_16x16x32_bf16 v[108:111], v[234:237], v[194:197], v[108:111]
	v_mfma_f32_16x16x32_bf16 v[112:115], v[226:229], v[202:205], v[112:115]
	v_mfma_f32_16x16x32_bf16 v[116:119], v[234:237], v[202:205], v[116:119]
	v_mfma_f32_16x16x32_bf16 v[120:123], v[226:229], v[218:221], v[120:123]
	v_mfma_f32_16x16x32_bf16 v[124:127], v[234:237], v[218:221], v[124:127]
	v_mfma_f32_16x16x32_bf16 v[96:99], v[230:233], v[190:193], v[96:99]
	v_mfma_f32_16x16x32_bf16 v[100:103], v[238:241], v[190:193], v[100:103]
	v_mfma_f32_16x16x32_bf16 v[104:107], v[230:233], v[198:201], v[104:107]
	v_mfma_f32_16x16x32_bf16 v[108:111], v[238:241], v[198:201], v[108:111]
	v_mfma_f32_16x16x32_bf16 v[112:115], v[230:233], v[208:211], v[112:115]
	v_mfma_f32_16x16x32_bf16 v[116:119], v[238:241], v[208:211], v[116:119]
	v_mfma_f32_16x16x32_bf16 v[120:123], v[230:233], v[222:225], v[120:123]
	v_mfma_f32_16x16x32_bf16 v[124:127], v[238:241], v[222:225], v[124:127]
	s_barrier
	ds_read_b128 v[136:139], v166
	ds_read_b128 v[174:177], v166 offset:1024
	ds_read_b128 v[178:181], v166 offset:2048
	ds_read_b128 v[182:185], v166 offset:3072
	v_add_u32_e32 v134, 0x4000, v158
	v_lshl_add_u64 v[226:227], v[214:215], 0, s[12:13]
	v_readfirstlane_b32 s56, v134
	v_add_u32_e32 v134, 0x6000, v158
	s_mov_b32 m0, s56
	v_readfirstlane_b32 s56, v134
	ds_read_b128 v[186:189], v163 offset:32768
	ds_read_b128 v[190:193], v163 offset:33792
	ds_read_b128 v[194:197], v162 offset:32768
	ds_read_b128 v[198:201], v162 offset:33792
	ds_read_b128 v[202:205], v161 offset:32768
	ds_read_b128 v[208:211], v161 offset:33792
	ds_read_b128 v[218:221], v160 offset:32768
	ds_read_b128 v[222:225], v160 offset:33792
	global_load_lds_dwordx4 v[226:227], off
	v_lshl_add_u64 v[226:227], v[216:217], 0, s[12:13]
	s_mov_b32 m0, s56
	s_nop 0
	global_load_lds_dwordx4 v[226:227], off
	s_waitcnt lgkmcnt(8)
	s_barrier
; #define STAGE(P, BASE, br, kt) STAGET(tid_, P, BASE, br, kt)
; #define LDA(dst, b, h) UFOR(m, 4) UFOR(k, 2) \
;     dst[m][k] = *reinterpret_cast<const bf16x8*>((char*)SA(b, h) + lds_byte(wr * 64 + m * 16 + fr, k * 32 + fq * 8))
; #define LDB(dst, b, h) UFOR(n, 2) UFOR(k, 2) \
;     dst[n][k] = *reinterpret_cast<const bf16x8*>((char*)SB(b, h) + lds_byte(wc * 32 + n * 16 + fr, k * 32 + fq * 8))
; #define MMA(ai, bj, At, Bq) do { __builtin_amdgcn_s_setprio(1); \
;     UFOR(m, 4) UFOR(n, 2) UFOR(k, 2) \
;       acc[ai][bj][m][n] = __builtin_amdgcn_mfma_f32_16x16x32_bf16(Bq[n][k], At[m][k], acc[ai][bj][m][n], 0, 0, 0); \
;     __builtin_amdgcn_s_setprio(0); } while (0)
; #define WAIT_V(n) asm volatile("s_waitcnt vmcnt(" #n ")" ::: "memory")
; #define WAIT_L(n) asm volatile("s_waitcnt lgkmcnt(" #n ")" ::: "memory")
; #define BAR __builtin_amdgcn_s_barrier()
; #define SCHED __builtin_amdgcn_sched_barrier(0)
; template <int EPI, int K, int KL> ...
;     ...
;     WAIT_L(8); BAR; WAIT_L(0); MMA(0, 0, At, B0); BAR; SCHED;
;     LDB(B1, 1, 1); STAGE(SB(1, 0), Bt, bcol, t + 3);
;     BAR; WAIT_L(0); MMA(0, 1, At, B1); BAR;
;     LDA(At, 1, 1); STAGE(SA(1, 0), A, brow, t + 3);
;     BAR; WAIT_L(0); MMA(1, 0, At, B0); BAR; SCHED;
;     STAGE(SB(1, 1), Bt, bcol + HALF, t + 3);
;     WAIT_V(6); BAR; MMA(1, 1, At, B1); BAR;
	s_waitcnt lgkmcnt(0)
	s_waitcnt lgkmcnt(0)
	v_mfma_f32_16x16x32_bf16 v[0:3], v[136:139], v[186:189], v[0:3]
	v_mfma_f32_16x16x32_bf16 v[4:7], v[178:181], v[186:189], v[4:7]
	v_mfma_f32_16x16x32_bf16 v[8:11], v[136:139], v[194:197], v[8:11]
	v_mfma_f32_16x16x32_bf16 v[16:19], v[178:181], v[194:197], v[16:19]
	v_mfma_f32_16x16x32_bf16 v[28:31], v[136:139], v[202:205], v[28:31]
	v_mfma_f32_16x16x32_bf16 v[40:43], v[178:181], v[202:205], v[40:43]
	v_mfma_f32_16x16x32_bf16 v[52:55], v[136:139], v[218:221], v[52:55]
	v_mfma_f32_16x16x32_bf16 v[64:67], v[178:181], v[218:221], v[64:67]
	v_mfma_f32_16x16x32_bf16 v[0:3], v[174:177], v[190:193], v[0:3]
	v_mfma_f32_16x16x32_bf16 v[4:7], v[182:185], v[190:193], v[4:7]
	v_mfma_f32_16x16x32_bf16 v[8:11], v[174:177], v[198:201], v[8:11]
	v_mfma_f32_16x16x32_bf16 v[16:19], v[182:185], v[198:201], v[16:19]
	v_mfma_f32_16x16x32_bf16 v[28:31], v[174:177], v[208:211], v[28:31]
	v_mfma_f32_16x16x32_bf16 v[40:43], v[182:185], v[208:211], v[40:43]
	v_mfma_f32_16x16x32_bf16 v[52:55], v[174:177], v[222:225], v[52:55]
	v_mfma_f32_16x16x32_bf16 v[64:67], v[182:185], v[222:225], v[64:67]
	s_barrier
	v_readfirstlane_b32 s56, v165
	v_add_u32_e32 v134, 0x2000, v165
	v_lshl_add_u64 v[246:247], v[242:243], 0, s[80:81]
	s_mov_b32 m0, s56
	v_readfirstlane_b32 s56, v134
	ds_read_b128 v[226:229], v164
	ds_read_b128 v[230:233], v164 offset:1024
	ds_read_b128 v[234:237], v164 offset:2048
	ds_read_b128 v[238:241], v164 offset:3072
	global_load_lds_dwordx4 v[246:247], off
	v_lshl_add_u64 v[246:247], v[244:245], 0, s[80:81]
	s_mov_b32 m0, s56
	s_nop 0
	global_load_lds_dwordx4 v[246:247], off
	s_barrier
	s_waitcnt lgkmcnt(0)
	s_waitcnt lgkmcnt(0)
	v_mfma_f32_16x16x32_bf16 v[12:15], v[226:229], v[186:189], v[12:15]
	v_mfma_f32_16x16x32_bf16 v[24:27], v[234:237], v[186:189], v[24:27]
	v_mfma_f32_16x16x32_bf16 v[36:39], v[226:229], v[194:197], v[36:39]
	v_mfma_f32_16x16x32_bf16 v[48:51], v[234:237], v[194:197], v[48:51]
	v_mfma_f32_16x16x32_bf16 v[60:63], v[226:229], v[202:205], v[60:63]
	v_mfma_f32_16x16x32_bf16 v[72:75], v[234:237], v[202:205], v[72:75]
	v_mfma_f32_16x16x32_bf16 v[80:83], v[226:229], v[218:221], v[80:83]
	v_mfma_f32_16x16x32_bf16 v[88:91], v[234:237], v[218:221], v[88:91]
	v_mfma_f32_16x16x32_bf16 v[12:15], v[230:233], v[190:193], v[12:15]
	v_mfma_f32_16x16x32_bf16 v[24:27], v[238:241], v[190:193], v[24:27]
	v_mfma_f32_16x16x32_bf16 v[36:39], v[230:233], v[198:201], v[36:39]
	v_mfma_f32_16x16x32_bf16 v[48:51], v[238:241], v[198:201], v[48:51]
	v_mfma_f32_16x16x32_bf16 v[60:63], v[230:233], v[208:211], v[60:63]
	v_mfma_f32_16x16x32_bf16 v[72:75], v[238:241], v[208:211], v[72:75]
	v_mfma_f32_16x16x32_bf16 v[80:83], v[230:233], v[222:225], v[80:83]
	v_mfma_f32_16x16x32_bf16 v[88:91], v[238:241], v[222:225], v[88:91]
	v_readfirstlane_b32 s56, v167
	v_lshl_add_u64 v[214:215], v[214:215], 0, s[16:17]
	s_mov_b32 m0, s56
	v_readfirstlane_b32 s56, v168
	s_barrier
	ds_read_b128 v[186:189], v163 offset:49152
	ds_read_b128 v[190:193], v163 offset:50176
	ds_read_b128 v[194:197], v162 offset:49152
	ds_read_b128 v[198:201], v162 offset:50176
	ds_read_b128 v[202:205], v161 offset:49152
	ds_read_b128 v[208:211], v161 offset:50176
	ds_read_b128 v[218:221], v160 offset:49152
	ds_read_b128 v[222:225], v160 offset:50176
	global_load_lds_dwordx4 v[214:215], off
	v_lshl_add_u64 v[214:215], v[216:217], 0, s[16:17]
	s_mov_b32 m0, s56
	s_nop 0
	global_load_lds_dwordx4 v[214:215], off
	s_barrier
	s_waitcnt lgkmcnt(0)
	s_waitcnt lgkmcnt(0)
	v_mfma_f32_16x16x32_bf16 v[20:23], v[136:139], v[186:189], v[20:23]
	v_mfma_f32_16x16x32_bf16 v[32:35], v[178:181], v[186:189], v[32:35]
	v_mfma_f32_16x16x32_bf16 v[44:47], v[136:139], v[194:197], v[44:47]
	v_mfma_f32_16x16x32_bf16 v[56:59], v[178:181], v[194:197], v[56:59]
	v_mfma_f32_16x16x32_bf16 v[68:71], v[136:139], v[202:205], v[68:71]
	v_mfma_f32_16x16x32_bf16 v[76:79], v[178:181], v[202:205], v[76:79]
	v_mfma_f32_16x16x32_bf16 v[84:87], v[136:139], v[218:221], v[84:87]
	v_mfma_f32_16x16x32_bf16 v[92:95], v[178:181], v[218:221], v[92:95]
	v_mfma_f32_16x16x32_bf16 v[20:23], v[174:177], v[190:193], v[20:23]
	v_mfma_f32_16x16x32_bf16 v[32:35], v[182:185], v[190:193], v[32:35]
	v_mfma_f32_16x16x32_bf16 v[44:47], v[174:177], v[198:201], v[44:47]
	v_mfma_f32_16x16x32_bf16 v[56:59], v[182:185], v[198:201], v[56:59]
	v_mfma_f32_16x16x32_bf16 v[68:71], v[174:177], v[208:211], v[68:71]
	v_mfma_f32_16x16x32_bf16 v[76:79], v[182:185], v[208:211], v[76:79]
	v_mfma_f32_16x16x32_bf16 v[84:87], v[174:177], v[222:225], v[84:87]
	v_mfma_f32_16x16x32_bf16 v[92:95], v[182:185], v[222:225], v[92:95]
	s_barrier
	v_readfirstlane_b32 s56, v170
	v_add_u32_e32 v134, 0x2000, v170
	v_lshl_add_u64 v[136:137], v[242:243], 0, s[90:91]
	s_mov_b32 m0, s56
	v_readfirstlane_b32 s56, v134
	global_load_lds_dwordx4 v[136:137], off
	v_lshl_add_u64 v[136:137], v[244:245], 0, s[90:91]
	s_mov_b32 m0, s56
	s_nop 0
	global_load_lds_dwordx4 v[136:137], off
	s_waitcnt vmcnt(6)
	s_barrier
; #define STAGE(P, BASE, br, kt) STAGET(tid_, P, BASE, br, kt)
; #define LDA(dst, b, h) UFOR(m, 4) UFOR(k, 2) \
;     dst[m][k] = *reinterpret_cast<const bf16x8*>((char*)SA(b, h) + lds_byte(wr * 64 + m * 16 + fr, k * 32 + fq * 8))
; #define LDB(dst, b, h) UFOR(n, 2) UFOR(k, 2) \
;     dst[n][k] = *reinterpret_cast<const bf16x8*>((char*)SB(b, h) + lds_byte(wc * 32 + n * 16 + fr, k * 32 + fq * 8))
; #define MMA(ai, bj, At, Bq) do { __builtin_amdgcn_s_setprio(1); \
;     UFOR(m, 4) UFOR(n, 2) UFOR(k, 2) \
;       acc[ai][bj][m][n] = __builtin_amdgcn_mfma_f32_16x16x32_bf16(Bq[n][k], At[m][k], acc[ai][bj][m][n], 0, 0, 0); \
;     __builtin_amdgcn_s_setprio(0); } while (0)
; #define WAIT_V(n) asm volatile("s_waitcnt vmcnt(" #n ")" ::: "memory")
; #define WAIT_L(n) asm volatile("s_waitcnt lgkmcnt(" #n ")" ::: "memory")
; #define BAR __builtin_amdgcn_s_barrier()
; template <int EPI, int K, int KL> ...
;     ...
;     WAIT_V(6); BAR; MMA(1, 1, At, B1); BAR;
;   }
;   { LDB(B0, 0, 0); LDA(At, 0, 0); STAGE(SA(1, 1), A, brow + HALF, nt - 1);
;     BAR; WAIT_L(0); MMA(0, 0, At, B0); BAR;
;     LDB(B1, 0, 1); BAR; WAIT_L(0); MMA(0, 1, At, B1); BAR;
;     LDA(At, 0, 1); WAIT_V(4); BAR; WAIT_L(0); MMA(1, 0, At, B0); MMA(1, 1, At, B1); BAR; }
	v_mfma_f32_16x16x32_bf16 v[96:99], v[226:229], v[186:189], v[96:99]
	v_mfma_f32_16x16x32_bf16 v[100:103], v[234:237], v[186:189], v[100:103]
	v_mfma_f32_16x16x32_bf16 v[104:107], v[226:229], v[194:197], v[104:107]
	v_mfma_f32_16x16x32_bf16 v[108:111], v[234:237], v[194:197], v[108:111]
	v_mfma_f32_16x16x32_bf16 v[112:115], v[226:229], v[202:205], v[112:115]
	v_mfma_f32_16x16x32_bf16 v[116:119], v[234:237], v[202:205], v[116:119]
	v_mfma_f32_16x16x32_bf16 v[120:123], v[226:229], v[218:221], v[120:123]
	v_mfma_f32_16x16x32_bf16 v[124:127], v[234:237], v[218:221], v[124:127]
	v_mfma_f32_16x16x32_bf16 v[96:99], v[230:233], v[190:193], v[96:99]
	v_mfma_f32_16x16x32_bf16 v[100:103], v[238:241], v[190:193], v[100:103]
	v_mfma_f32_16x16x32_bf16 v[104:107], v[230:233], v[198:201], v[104:107]
	v_mfma_f32_16x16x32_bf16 v[108:111], v[238:241], v[198:201], v[108:111]
	v_mfma_f32_16x16x32_bf16 v[112:115], v[230:233], v[208:211], v[112:115]
	v_mfma_f32_16x16x32_bf16 v[116:119], v[238:241], v[208:211], v[116:119]
	v_mfma_f32_16x16x32_bf16 v[120:123], v[230:233], v[222:225], v[120:123]
	v_mfma_f32_16x16x32_bf16 v[124:127], v[238:241], v[222:225], v[124:127]
	s_add_i32 s53, s53, 2
	v_lshl_add_u64 v[144:145], v[144:145], 0, s[20:21]
	v_lshl_add_u64 v[146:147], v[146:147], 0, s[20:21]
	v_lshl_add_u64 v[148:149], v[148:149], 0, s[20:21]
	s_cmp_lt_u32 s53, 28
	v_lshl_add_u64 v[150:151], v[150:151], 0, s[20:21]
	s_cbranch_scc1 .Lkrot_1107
	s_barrier
	s_add_u32 s40, s40, 0x80f80
	s_addc_u32 s41, s41, 0
	v_lshl_add_u64 v[130:131], s[40:41], 0, v[130:131]
	v_readfirstlane_b32 s53, v172
	v_lshl_add_u64 v[128:129], v[128:129], 1, v[130:131]
	s_mov_b32 m0, s53
	ds_read_b128 v[136:139], v171
	ds_read_b128 v[144:147], v171 offset:1024
	ds_read_b128 v[148:151], v171 offset:2048
	ds_read_b128 v[174:177], v171 offset:3072
	ds_read_b128 v[178:181], v163
	ds_read_b128 v[182:185], v163 offset:1024
	ds_read_b128 v[186:189], v162
	ds_read_b128 v[190:193], v162 offset:1024
	ds_read_b128 v[194:197], v161
	ds_read_b128 v[198:201], v161 offset:1024
	ds_read_b128 v[202:205], v160
	ds_read_b128 v[208:211], v160 offset:1024
	global_load_lds_dwordx4 v[128:129], off
	v_lshl_add_u64 v[128:129], s[40:41], 0, v[142:143]
	v_readfirstlane_b32 s40, v173
	v_lshl_add_u64 v[128:129], v[140:141], 1, v[128:129]
	s_mov_b32 m0, s40
	s_nop 0
	global_load_lds_dwordx4 v[128:129], off
	s_barrier
	s_waitcnt lgkmcnt(0)
	s_waitcnt lgkmcnt(0)
	v_mfma_f32_16x16x32_bf16 v[0:3], v[136:139], v[178:181], v[0:3]
	v_mfma_f32_16x16x32_bf16 v[4:7], v[148:151], v[178:181], v[4:7]
	v_mfma_f32_16x16x32_bf16 v[8:11], v[136:139], v[186:189], v[8:11]
	v_mfma_f32_16x16x32_bf16 v[16:19], v[148:151], v[186:189], v[16:19]
	v_mfma_f32_16x16x32_bf16 v[28:31], v[136:139], v[194:197], v[28:31]
	v_mfma_f32_16x16x32_bf16 v[40:43], v[148:151], v[194:197], v[40:43]
	v_mfma_f32_16x16x32_bf16 v[52:55], v[136:139], v[202:205], v[52:55]
	v_mfma_f32_16x16x32_bf16 v[64:67], v[148:151], v[202:205], v[64:67]
	v_mfma_f32_16x16x32_bf16 v[0:3], v[144:147], v[182:185], v[0:3]
	v_mfma_f32_16x16x32_bf16 v[4:7], v[174:177], v[182:185], v[4:7]
	v_mfma_f32_16x16x32_bf16 v[8:11], v[144:147], v[190:193], v[8:11]
	v_mfma_f32_16x16x32_bf16 v[16:19], v[174:177], v[190:193], v[16:19]
	v_mfma_f32_16x16x32_bf16 v[28:31], v[144:147], v[198:201], v[28:31]
	v_mfma_f32_16x16x32_bf16 v[40:43], v[174:177], v[198:201], v[40:43]
	v_mfma_f32_16x16x32_bf16 v[52:55], v[144:147], v[208:211], v[52:55]
	v_mfma_f32_16x16x32_bf16 v[64:67], v[174:177], v[208:211], v[64:67]
	s_barrier
	ds_read_b128 v[128:131], v169
	ds_read_b128 v[140:143], v169 offset:1024
	ds_read_b128 v[170:173], v169 offset:2048
	ds_read_b128 v[218:221], v169 offset:3072
	s_barrier
	s_waitcnt lgkmcnt(0)
	s_waitcnt lgkmcnt(0)
	v_mfma_f32_16x16x32_bf16 v[12:15], v[128:131], v[178:181], v[12:15]
	v_mfma_f32_16x16x32_bf16 v[24:27], v[170:173], v[178:181], v[24:27]
	v_mfma_f32_16x16x32_bf16 v[36:39], v[128:131], v[186:189], v[36:39]
	v_mfma_f32_16x16x32_bf16 v[48:51], v[170:173], v[186:189], v[48:51]
	v_mfma_f32_16x16x32_bf16 v[60:63], v[128:131], v[194:197], v[60:63]
	v_mfma_f32_16x16x32_bf16 v[72:75], v[170:173], v[194:197], v[72:75]
	v_mfma_f32_16x16x32_bf16 v[80:83], v[128:131], v[202:205], v[80:83]
	v_mfma_f32_16x16x32_bf16 v[12:15], v[140:143], v[182:185], v[12:15]
	v_mfma_f32_16x16x32_bf16 v[24:27], v[218:221], v[182:185], v[24:27]
	v_mfma_f32_16x16x32_bf16 v[36:39], v[140:143], v[190:193], v[36:39]
	v_mfma_f32_16x16x32_bf16 v[48:51], v[218:221], v[190:193], v[48:51]
	v_mfma_f32_16x16x32_bf16 v[60:63], v[140:143], v[198:201], v[60:63]
	v_mfma_f32_16x16x32_bf16 v[72:75], v[218:221], v[198:201], v[72:75]
	v_mfma_f32_16x16x32_bf16 v[178:181], v[140:143], v[208:211], v[80:83]
	v_mfma_f32_16x16x32_bf16 v[80:83], v[170:173], v[202:205], v[88:91]
	v_mfma_f32_16x16x32_bf16 v[182:185], v[218:221], v[208:211], v[80:83]
	s_barrier
	s_nop 5
	ds_read_b128 v[80:83], v163 offset:16384
	ds_read_b128 v[88:91], v163 offset:17408
	ds_read_b128 v[186:189], v162 offset:16384
	ds_read_b128 v[190:193], v162 offset:17408
	ds_read_b128 v[194:197], v161 offset:16384
	ds_read_b128 v[198:201], v161 offset:17408
	ds_read_b128 v[202:205], v160 offset:16384
	ds_read_b128 v[208:211], v160 offset:17408
	s_waitcnt vmcnt(4)
	s_barrier
; #define LDA(dst, b, h) UFOR(m, 4) UFOR(k, 2) \
;     dst[m][k] = *reinterpret_cast<const bf16x8*>((char*)SA(b, h) + lds_byte(wr * 64 + m * 16 + fr, k * 32 + fq * 8))
; #define LDB(dst, b, h) UFOR(n, 2) UFOR(k, 2) \
;     dst[n][k] = *reinterpret_cast<const bf16x8*>((char*)SB(b, h) + lds_byte(wc * 32 + n * 16 + fr, k * 32 + fq * 8))
; #define MMA(ai, bj, At, Bq) do { __builtin_amdgcn_s_setprio(1); \
;     UFOR(m, 4) UFOR(n, 2) UFOR(k, 2) \
;       acc[ai][bj][m][n] = __builtin_amdgcn_mfma_f32_16x16x32_bf16(Bq[n][k], At[m][k], acc[ai][bj][m][n], 0, 0, 0); \
;     __builtin_amdgcn_s_setprio(0); } while (0)
; #define WAIT_V(n) asm volatile("s_waitcnt vmcnt(" #n ")" ::: "memory")
; #define WAIT_L(n) asm volatile("s_waitcnt lgkmcnt(" #n ")" ::: "memory")
; #define BAR __builtin_amdgcn_s_barrier()
; template <int EPI, int K, int KL> ...
;     ...
;     LDA(At, 0, 1); WAIT_V(4); BAR; WAIT_L(0); MMA(1, 0, At, B0); MMA(1, 1, At, B1); BAR; }
;   { LDB(B0, 1, 0); LDA(At, 1, 0); WAIT_V(2); BAR; WAIT_L(0); MMA(0, 0, At, B0); BAR;
	s_waitcnt lgkmcnt(0)
	s_waitcnt lgkmcnt(0)
	v_mfma_f32_16x16x32_bf16 v[56:59], v[148:151], v[186:189], v[56:59]
	v_mfma_f32_16x16x32_bf16 v[222:225], v[174:177], v[190:193], v[56:59]
	v_mfma_f32_16x16x32_bf16 v[56:59], v[136:139], v[194:197], v[68:71]
	v_mfma_f32_16x16x32_bf16 v[226:229], v[144:147], v[198:201], v[56:59]
	v_mfma_f32_16x16x32_bf16 v[56:59], v[148:151], v[194:197], v[76:79]
	v_mfma_f32_16x16x32_bf16 v[20:23], v[136:139], v[80:83], v[20:23]
	v_mfma_f32_16x16x32_bf16 v[32:35], v[148:151], v[80:83], v[32:35]
	v_mfma_f32_16x16x32_bf16 v[44:47], v[136:139], v[186:189], v[44:47]
	v_mfma_f32_16x16x32_bf16 v[230:233], v[174:177], v[198:201], v[56:59]
	v_mfma_f32_16x16x32_bf16 v[56:59], v[136:139], v[202:205], v[84:87]
	v_mfma_f32_16x16x32_bf16 v[20:23], v[144:147], v[88:91], v[20:23]
	v_mfma_f32_16x16x32_bf16 v[32:35], v[174:177], v[88:91], v[32:35]
	v_mfma_f32_16x16x32_bf16 v[44:47], v[144:147], v[190:193], v[44:47]
	v_mfma_f32_16x16x32_bf16 v[136:139], v[144:147], v[208:211], v[56:59]
	v_mfma_f32_16x16x32_bf16 v[56:59], v[148:151], v[202:205], v[92:95]
	v_mfma_f32_16x16x32_bf16 v[144:147], v[174:177], v[208:211], v[56:59]
	v_mfma_f32_16x16x32_bf16 v[56:59], v[128:131], v[80:83], v[96:99]
	v_mfma_f32_16x16x32_bf16 v[148:151], v[140:143], v[88:91], v[56:59]
	v_mfma_f32_16x16x32_bf16 v[56:59], v[170:173], v[80:83], v[100:103]
	v_mfma_f32_16x16x32_bf16 v[174:177], v[218:221], v[88:91], v[56:59]
	v_mfma_f32_16x16x32_bf16 v[56:59], v[128:131], v[186:189], v[104:107]
	v_mfma_f32_16x16x32_bf16 v[234:237], v[140:143], v[190:193], v[56:59]
	v_mfma_f32_16x16x32_bf16 v[56:59], v[170:173], v[186:189], v[108:111]
	v_mfma_f32_16x16x32_bf16 v[186:189], v[218:221], v[190:193], v[56:59]
	v_mfma_f32_16x16x32_bf16 v[56:59], v[128:131], v[194:197], v[112:115]
	v_mfma_f32_16x16x32_bf16 v[190:193], v[140:143], v[198:201], v[56:59]
	v_mfma_f32_16x16x32_bf16 v[56:59], v[170:173], v[194:197], v[116:119]
	v_mfma_f32_16x16x32_bf16 v[194:197], v[218:221], v[198:201], v[56:59]
	v_mfma_f32_16x16x32_bf16 v[56:59], v[128:131], v[202:205], v[120:123]
	v_mfma_f32_16x16x32_bf16 v[128:131], v[140:143], v[208:211], v[56:59]
	v_mfma_f32_16x16x32_bf16 v[56:59], v[170:173], v[202:205], v[124:127]
	v_mfma_f32_16x16x32_bf16 v[140:143], v[218:221], v[208:211], v[56:59]
	s_barrier
	ds_read_b128 v[168:171], v166
	ds_read_b128 v[198:201], v166 offset:1024
	ds_read_b128 v[202:205], v166 offset:2048
	ds_read_b128 v[208:211], v166 offset:3072
	s_nop 1
	ds_read_b128 v[56:59], v163 offset:32768
	ds_read_b128 v[68:71], v163 offset:33792
	ds_read_b128 v[76:79], v162 offset:32768
	ds_read_b128 v[80:83], v162 offset:33792
	ds_read_b128 v[218:221], v161 offset:32768
	ds_read_b128 v[238:241], v161 offset:33792
	ds_read_b128 v[242:245], v160 offset:32768
	ds_read_b128 v[246:249], v160 offset:33792
	s_waitcnt vmcnt(2)
	s_barrier
	s_waitcnt lgkmcnt(0)
	s_waitcnt lgkmcnt(0)
	v_mfma_f32_16x16x32_bf16 v[0:3], v[168:171], v[56:59], v[0:3]
	v_mfma_f32_16x16x32_bf16 v[124:127], v[198:201], v[68:71], v[0:3]
	v_mfma_f32_16x16x32_bf16 v[0:3], v[202:205], v[56:59], v[4:7]
	v_mfma_f32_16x16x32_bf16 v[120:123], v[208:211], v[68:71], v[0:3]
	v_mfma_f32_16x16x32_bf16 v[0:3], v[168:171], v[76:79], v[8:11]
	v_mfma_f32_16x16x32_bf16 v[116:119], v[198:201], v[80:83], v[0:3]
	v_mfma_f32_16x16x32_bf16 v[0:3], v[202:205], v[76:79], v[16:19]
	v_mfma_f32_16x16x32_bf16 v[112:115], v[208:211], v[80:83], v[0:3]
	v_mfma_f32_16x16x32_bf16 v[0:3], v[168:171], v[218:221], v[28:31]
	v_mfma_f32_16x16x32_bf16 v[108:111], v[198:201], v[238:241], v[0:3]
	v_mfma_f32_16x16x32_bf16 v[0:3], v[202:205], v[218:221], v[40:43]
	v_mfma_f32_16x16x32_bf16 v[104:107], v[208:211], v[238:241], v[0:3]
	v_mfma_f32_16x16x32_bf16 v[0:3], v[168:171], v[242:245], v[52:55]
	v_mfma_f32_16x16x32_bf16 v[100:103], v[198:201], v[246:249], v[0:3]
	v_mfma_f32_16x16x32_bf16 v[0:3], v[202:205], v[242:245], v[64:67]
	v_mfma_f32_16x16x32_bf16 v[96:99], v[208:211], v[246:249], v[0:3]
	s_barrier
; #define LDA(dst, b, h) UFOR(m, 4) UFOR(k, 2) \
;     dst[m][k] = *reinterpret_cast<const bf16x8*>((char*)SA(b, h) + lds_byte(wr * 64 + m * 16 + fr, k * 32 + fq * 8))
; #define LDB(dst, b, h) UFOR(n, 2) UFOR(k, 2) \
;     dst[n][k] = *reinterpret_cast<const bf16x8*>((char*)SB(b, h) + lds_byte(wc * 32 + n * 16 + fr, k * 32 + fq * 8))
; #define MMA(ai, bj, At, Bq) do { __builtin_amdgcn_s_setprio(1); \
;     UFOR(m, 4) UFOR(n, 2) UFOR(k, 2) \
;       acc[ai][bj][m][n] = __builtin_amdgcn_mfma_f32_16x16x32_bf16(Bq[n][k], At[m][k], acc[ai][bj][m][n], 0, 0, 0); \
;     __builtin_amdgcn_s_setprio(0); } while (0)
; #define WAIT_V(n) asm volatile("s_waitcnt vmcnt(" #n ")" ::: "memory")
; #define WAIT_L(n) asm volatile("s_waitcnt lgkmcnt(" #n ")" ::: "memory")
; #define BAR __builtin_amdgcn_s_barrier()
; template <int EPI, int K, int KL> ...
;     ...
;     LDB(B1, 1, 1); WAIT_V(0); BAR; WAIT_L(0); MMA(0, 1, At, B1); BAR;
;     LDA(At, 1, 1); BAR; WAIT_L(0); MMA(1, 0, At, B0); MMA(1, 1, At, B1); BAR; }
;   if (wr == 0) BAR;
	s_nop 5
	ds_read_b128 v[0:3], v164
	ds_read_b128 v[4:7], v164 offset:1024
	ds_read_b128 v[214:217], v164 offset:2048
	ds_read_b128 v[164:167], v164 offset:3072
	s_waitcnt vmcnt(0)
	s_barrier
	s_waitcnt lgkmcnt(0)
	s_waitcnt lgkmcnt(0)
	v_mfma_f32_16x16x32_bf16 v[8:11], v[0:3], v[56:59], v[12:15]
	v_mfma_f32_16x16x32_bf16 v[92:95], v[4:7], v[68:71], v[8:11]
	v_mfma_f32_16x16x32_bf16 v[8:11], v[214:217], v[56:59], v[24:27]
	v_mfma_f32_16x16x32_bf16 v[88:91], v[164:167], v[68:71], v[8:11]
	v_mfma_f32_16x16x32_bf16 v[8:11], v[0:3], v[76:79], v[36:39]
	v_mfma_f32_16x16x32_bf16 v[84:87], v[4:7], v[80:83], v[8:11]
	v_mfma_f32_16x16x32_bf16 v[8:11], v[214:217], v[76:79], v[48:51]
	v_mfma_f32_16x16x32_bf16 v[80:83], v[164:167], v[80:83], v[8:11]
	v_mfma_f32_16x16x32_bf16 v[8:11], v[0:3], v[218:221], v[60:63]
	v_mfma_f32_16x16x32_bf16 v[76:79], v[4:7], v[238:241], v[8:11]
	v_mfma_f32_16x16x32_bf16 v[8:11], v[214:217], v[218:221], v[72:75]
	v_mfma_f32_16x16x32_bf16 v[72:75], v[164:167], v[238:241], v[8:11]
	v_mfma_f32_16x16x32_bf16 v[8:11], v[0:3], v[242:245], v[178:181]
	v_mfma_f32_16x16x32_bf16 v[68:71], v[4:7], v[246:249], v[8:11]
	v_mfma_f32_16x16x32_bf16 v[8:11], v[214:217], v[242:245], v[182:185]
	v_mfma_f32_16x16x32_bf16 v[64:67], v[164:167], v[246:249], v[8:11]
	s_barrier
	s_nop 5
	ds_read_b128 v[8:11], v163 offset:49152
	ds_read_b128 v[12:15], v163 offset:50176
	ds_read_b128 v[16:19], v162 offset:49152
	ds_read_b128 v[178:181], v162 offset:50176
	ds_read_b128 v[182:185], v161 offset:49152
	ds_read_b128 v[218:221], v161 offset:50176
	ds_read_b128 v[238:241], v160 offset:49152
	ds_read_b128 v[158:161], v160 offset:50176
	s_barrier
	s_waitcnt lgkmcnt(0)
	s_waitcnt lgkmcnt(0)
	v_mfma_f32_16x16x32_bf16 v[20:23], v[168:171], v[8:11], v[20:23]
	v_mfma_f32_16x16x32_bf16 v[60:63], v[198:201], v[12:15], v[20:23]
	v_mfma_f32_16x16x32_bf16 v[20:23], v[202:205], v[8:11], v[32:35]
	v_mfma_f32_16x16x32_bf16 v[56:59], v[208:211], v[12:15], v[20:23]
	v_mfma_f32_16x16x32_bf16 v[20:23], v[168:171], v[16:19], v[44:47]
	v_mfma_f32_16x16x32_bf16 v[52:55], v[198:201], v[178:181], v[20:23]
	v_mfma_f32_16x16x32_bf16 v[20:23], v[202:205], v[16:19], v[222:225]
	v_mfma_f32_16x16x32_bf16 v[48:51], v[208:211], v[178:181], v[20:23]
	v_mfma_f32_16x16x32_bf16 v[20:23], v[168:171], v[182:185], v[226:229]
	v_mfma_f32_16x16x32_bf16 v[44:47], v[198:201], v[218:221], v[20:23]
	v_mfma_f32_16x16x32_bf16 v[20:23], v[202:205], v[182:185], v[230:233]
	v_mfma_f32_16x16x32_bf16 v[40:43], v[208:211], v[218:221], v[20:23]
	v_mfma_f32_16x16x32_bf16 v[20:23], v[168:171], v[238:241], v[136:139]
	v_mfma_f32_16x16x32_bf16 v[36:39], v[198:201], v[158:161], v[20:23]
	v_mfma_f32_16x16x32_bf16 v[20:23], v[202:205], v[238:241], v[144:147]
	v_mfma_f32_16x16x32_bf16 v[32:35], v[208:211], v[158:161], v[20:23]
	v_mfma_f32_16x16x32_bf16 v[20:23], v[0:3], v[8:11], v[148:151]
	v_mfma_f32_16x16x32_bf16 v[8:11], v[214:217], v[8:11], v[174:177]
	v_mfma_f32_16x16x32_bf16 v[24:27], v[164:167], v[12:15], v[8:11]
	v_mfma_f32_16x16x32_bf16 v[8:11], v[0:3], v[16:19], v[234:237]
	v_mfma_f32_16x16x32_bf16 v[28:31], v[4:7], v[12:15], v[20:23]
	v_mfma_f32_16x16x32_bf16 v[20:23], v[4:7], v[178:181], v[8:11]
	v_mfma_f32_16x16x32_bf16 v[8:11], v[214:217], v[16:19], v[186:189]
	v_mfma_f32_16x16x32_bf16 v[16:19], v[164:167], v[178:181], v[8:11]
	v_mfma_f32_16x16x32_bf16 v[8:11], v[0:3], v[182:185], v[190:193]
	v_mfma_f32_16x16x32_bf16 v[0:3], v[0:3], v[238:241], v[128:131]
	v_mfma_f32_16x16x32_bf16 v[12:15], v[4:7], v[218:221], v[8:11]
	v_mfma_f32_16x16x32_bf16 v[8:11], v[214:217], v[182:185], v[194:197]
	v_mfma_f32_16x16x32_bf16 v[4:7], v[4:7], v[158:161], v[0:3]
	v_mfma_f32_16x16x32_bf16 v[0:3], v[214:217], v[238:241], v[140:143]
	v_mfma_f32_16x16x32_bf16 v[8:11], v[164:167], v[218:221], v[8:11]
	v_mfma_f32_16x16x32_bf16 v[0:3], v[164:167], v[158:161], v[0:3]
	s_movk_i32 s40, 0x100
	v_cmp_gt_u32_e32 vcc, s40, v152
	s_barrier
	s_and_saveexec_b64 s[40:41], vcc
	s_cbranch_execz .LBB0_1110
	s_barrier

; #define STAGE(P, BASE, br, kt) STAGET(tid_, P, BASE, br, kt)
; #define WAIT_V(n) asm volatile("s_waitcnt vmcnt(" #n ")" ::: "memory")
; #define BAR __builtin_amdgcn_s_barrier()
; template <int EPI, int K, int KL> ...
;     ...
;   if (wr == 1) BAR;
;   WAIT_V(4); BAR;
;   STAGE(SB(1, 0), Bt, bcol, 1); STAGE(SA(1, 0), A, brow, 1); STAGE(SB(1, 1), Bt, bcol + HALF, 1);
;   WAIT_V(6); BAR;
.LBB0_1183:
	s_or_b64 exec, exec, s[52:53]
	v_add_u32_e32 v2, v0, v2
	v_and_b32_e32 v2, 0xfffffc00, v2
	v_sub_u32_e32 v2, v0, v2
	v_lshrrev_b32_e32 v5, 4, v2
	v_add_u32_e32 v3, v154, v3
	v_bitop3_b32 v5, v5, v2, 32 bitop3:0x6c
	v_ashrrev_i32_e32 v2, 31, v2
	v_ashrrev_i32_e32 v3, 6, v3
	v_lshrrev_b32_e32 v2, 26, v2
	v_lshlrev_b32_e32 v6, 3, v3
	v_add_u32_e32 v2, v5, v2
	v_and_b32_e32 v6, -16, v6
	v_ashrrev_i32_e32 v2, 6, v2
	v_add_u32_e32 v12, v2, v6
	v_mul_i32_i24_e32 v2, 64, v2
	v_readlane_b32 s58, v254, 22
	v_lshlrev_b32_e32 v3, 5, v3
	v_sub_u32_e32 v2, v5, v2
	v_readlane_b32 s59, v254, 23
	s_add_u32 s52, s58, s57
	v_and_b32_e32 v3, 32, v3
	v_ashrrev_i16_sdwa v2, v207, sext(v2) dst_sel:DWORD dst_unused:UNUSED_PAD src0_sel:DWORD src1_sel:BYTE_0
	s_movk_i32 s60, 0x2c00
	s_addc_u32 s53, s59, s56
	v_add_u32_sdwa v128, v3, sext(v2) dst_sel:DWORD dst_unused:UNUSED_PAD src0_sel:DWORD src1_sel:WORD_0
	v_mad_i64_i32 v[130:131], s[56:57], v12, s60, 0
	v_mov_b64_e32 v[2:3], s[52:53]
	v_ashrrev_i32_e32 v129, 31, v128
	v_readlane_b32 s56, v254, 45
	v_ashrrev_i32_e32 v5, 31, v1
	v_mad_i64_i32 v[6:7], s[52:53], v12, s60, v[2:3]
	v_lshlrev_b64 v[8:9], 1, v[128:129]
	v_add_u32_e32 v164, s56, v0
	v_lshrrev_b32_e32 v5, 22, v5
	v_lshl_add_u64 v[6:7], v[6:7], 0, v[8:9]
	s_mov_b64 s[64:65], 0x80
	v_readfirstlane_b32 s52, v164
	v_add_u32_e32 v5, v1, v5
	v_lshl_add_u64 v[6:7], v[6:7], 0, s[64:65]
	s_mov_b32 m0, s52
	v_ashrrev_i32_e32 v5, 10, v5
	s_waitcnt vmcnt(4)
	s_barrier
	global_load_lds_dwordx4 v[6:7], off
	v_mul_i32_i24_e32 v6, 0x400, v5
	v_sub_u32_e32 v6, v1, v6
	v_lshrrev_b32_e32 v7, 4, v6
	v_bitop3_b32 v6, v7, v6, 32 bitop3:0x6c
	v_ashrrev_i32_e32 v10, 31, v6
	v_lshrrev_b32_e32 v10, 26, v10
	v_lshlrev_b32_e32 v7, 3, v5
	v_add_u32_e32 v10, v6, v10
	v_and_b32_e32 v7, -16, v7
	v_ashrrev_i32_e32 v11, 6, v10
	v_add_u32_e32 v13, v11, v7
	v_and_b32_e32 v7, 0xc0, v10
	v_lshlrev_b32_e32 v5, 5, v5
	v_sub_u32_e32 v6, v6, v7
	v_and_b32_e32 v5, 32, v5
	v_ashrrev_i16_sdwa v6, v207, sext(v6) dst_sel:DWORD dst_unused:UNUSED_PAD src0_sel:DWORD src1_sel:BYTE_0
	v_add_u32_sdwa v140, v5, sext(v6) dst_sel:DWORD dst_unused:UNUSED_PAD src0_sel:DWORD src1_sel:WORD_0
	v_mad_i64_i32 v[142:143], s[52:53], v13, s60, 0
	v_mad_i64_i32 v[2:3], s[52:53], v13, s60, v[2:3]
	v_ashrrev_i32_e32 v141, 31, v140
	v_add_u32_e32 v5, s56, v1
	v_lshlrev_b64 v[6:7], 1, v[140:141]
	v_readfirstlane_b32 s52, v5
	s_add_i32 s54, s54, s19
	v_lshl_add_u64 v[2:3], v[2:3], 0, v[6:7]
	s_mov_b32 m0, s52
	s_add_u32 s52, s62, s55
	v_lshl_add_u64 v[2:3], v[2:3], 0, s[64:65]
	s_addc_u32 s53, s63, s54
	global_load_lds_dwordx4 v[2:3], off
	v_mov_b64_e32 v[2:3], s[52:53]
	v_mad_i64_i32 v[10:11], s[54:55], v12, s60, v[2:3]
	v_add_u32_e32 v166, 0x8000, v157
	v_lshl_add_u64 v[10:11], v[10:11], 0, v[8:9]
	v_readfirstlane_b32 s54, v166
	s_mov_b32 m0, s54
	v_mad_i64_i32 v[2:3], s[54:55], v13, s60, v[2:3]
	v_add_u32_e32 v167, 0xa000, v157
	v_lshl_add_u64 v[10:11], v[10:11], 0, s[64:65]
	v_readfirstlane_b32 s54, v167
	global_load_lds_dwordx4 v[10:11], off
	s_mov_b32 m0, s54
	s_or_b32 s54, s18, 0x80
	s_mul_hi_i32 s55, s54, 0x2c00
	s_mulk_i32 s54, 0x2c00
	v_lshl_add_u64 v[2:3], v[2:3], 0, v[6:7]
	s_add_u32 s54, s58, s54
	v_lshl_add_u64 v[2:3], v[2:3], 0, s[64:65]
	s_addc_u32 s55, s59, s55
	global_load_lds_dwordx4 v[2:3], off
	v_mov_b64_e32 v[2:3], s[54:55]
	v_readlane_b32 s57, v254, 46
	v_mad_i64_i32 v[10:11], s[54:55], v12, s60, v[2:3]
	s_nop 0
	v_add_u32_e32 v168, s57, v0
	v_lshl_add_u64 v[10:11], v[10:11], 0, v[8:9]
	v_readfirstlane_b32 s54, v168
	s_mov_b32 m0, s54
	v_mad_i64_i32 v[2:3], s[54:55], v13, s60, v[2:3]
	v_add_u32_e32 v0, s57, v1
	v_lshl_add_u64 v[10:11], v[10:11], 0, s[64:65]
	v_lshl_add_u64 v[2:3], v[2:3], 0, v[6:7]
	v_readfirstlane_b32 s54, v0
	global_load_lds_dwordx4 v[10:11], off
	v_lshl_add_u64 v[2:3], v[2:3], 0, s[64:65]
	s_mov_b32 m0, s54
	v_and_b32_e32 v132, 15, v154
	global_load_lds_dwordx4 v[2:3], off
	v_bfe_u32 v153, v154, 4, 2
	v_lshlrev_b32_e32 v3, 2, v154
	v_lshlrev_b32_e32 v0, 4, v153
	v_lshlrev_b32_e32 v1, 6, v132
	v_and_b32_e32 v3, 32, v3
	v_bitop3_b32 v1, v0, v3, v1 bitop3:0x36
	v_readlane_b32 s54, v254, 43
	v_add_u32_e32 v11, s56, v1
	v_add_u32_e32 v12, s57, v1
	v_add_u32_e32 v5, s54, v1
	v_readlane_b32 s54, v254, 44
	v_add_u32_e32 v13, 0, v1
	v_bfe_u32 v152, v154, 6, 2
	v_add_u32_e32 v10, s54, v1
	v_lshlrev_b32_e32 v1, 6, v154
	s_movk_i32 s54, 0x3c0
	v_and_or_b32 v0, v1, s54, v0
	v_xad_u32 v3, v0, v3, 0
	v_mad_i64_i32 v[0:1], s[54:55], s18, v250, v[130:131]
	v_lshl_add_u64 v[144:145], v[0:1], 0, v[8:9]
	v_mad_i64_i32 v[0:1], s[54:55], s18, v250, v[142:143]
	v_lshl_add_u64 v[146:147], v[0:1], 0, v[6:7]
	v_mad_u64_u32 v[0:1], s[54:55], s48, v250, v[130:131]
	v_add_u32_e32 v1, s19, v1
	v_lshl_add_u64 v[148:149], v[0:1], 0, v[8:9]
	v_mad_u64_u32 v[0:1], s[54:55], s48, v250, v[142:143]
	s_waitcnt vmcnt(6)
; #define STAGE(P, BASE, br, kt) STAGET(tid_, P, BASE, br, kt)
; #define LDA(dst, b, h) UFOR(m, 4) UFOR(k, 2) \
;     dst[m][k] = *reinterpret_cast<const bf16x8*>((char*)SA(b, h) + lds_byte(wr * 64 + m * 16 + fr, k * 32 + fq * 8))
; #define LDB(dst, b, h) UFOR(n, 2) UFOR(k, 2) \
;     dst[n][k] = *reinterpret_cast<const bf16x8*>((char*)SB(b, h) + lds_byte(wc * 32 + n * 16 + fr, k * 32 + fq * 8))
; #define MMA(ai, bj, At, Bq) do { __builtin_amdgcn_s_setprio(1); \
;     UFOR(m, 4) UFOR(n, 2) UFOR(k, 2) \
;       acc[ai][bj][m][n] = __builtin_amdgcn_mfma_f32_16x16x32_bf16(Bq[n][k], At[m][k], acc[ai][bj][m][n], 0, 0, 0); \
;     __builtin_amdgcn_s_setprio(0); } while (0)
; #define WAIT_V(n) asm volatile("s_waitcnt vmcnt(" #n ")" ::: "memory")
; #define WAIT_L(n) asm volatile("s_waitcnt lgkmcnt(" #n ")" ::: "memory")
; #define BAR __builtin_amdgcn_s_barrier()
; #define SCHED __builtin_amdgcn_sched_barrier(0)
; template <int EPI, int K, int KL> ...
;     ...
;   f32x4 acc[2][2][4][2] = {};
;   bf16x8 At[4][2], B0[2][2], B1[2][2];
;   const int nt = KL / BK;
;   if (own_prologue) {
;     STAGE(SB(0, 0), Bt, bcol, 0); STAGE(SA(0, 0), A, brow, 0);
;     STAGE(SB(0, 1), Bt, bcol + HALF, 0); STAGE(SA(0, 1), A, brow + HALF, 0);
;   }
;   if (wr == 1) BAR;
;   WAIT_V(4); BAR;
;   STAGE(SB(1, 0), Bt, bcol, 1); STAGE(SA(1, 0), A, brow, 1); STAGE(SB(1, 1), Bt, bcol + HALF, 1);
;   WAIT_V(6); BAR;
;   for (int t = 0; t < nt - 2; t += 2) {
;     LDB(B0, 0, 0); SCHED; LDA(At, 0, 0); STAGE(SA(1, 1), A, brow + HALF, t + 1);
;     WAIT_L(8); BAR; WAIT_L(0); MMA(0, 0, At, B0); BAR; SCHED;
	v_lshlrev_b32_e32 v155, 6, v4
	v_lshlrev_b32_e32 v4, 13, v4
	v_add_u32_e32 v1, s19, v1
	v_lshlrev_b32_e32 v2, 12, v152
	v_or_b32_e32 v14, 0x800, v4
	v_or_b32_e32 v15, 0x1000, v4
	v_or_b32_e32 v16, 0x1800, v4
	v_lshl_add_u64 v[150:151], v[0:1], 0, v[6:7]
	v_mov_b32_e32 v0, 0
	s_mov_b32 s19, -2
	v_add_u32_e32 v170, v5, v2
	v_add_u32_e32 v162, v13, v4
	v_add_u32_e32 v161, v3, v14
	v_add_u32_e32 v160, v3, v15
	v_add_u32_e32 v159, v3, v16
	v_add_u32_e32 v169, v10, v2
	v_add_u32_e32 v165, v11, v2
	v_add_u32_e32 v163, v12, v2
	v_mov_b32_e32 v1, v0
	v_mov_b32_e32 v2, v0
	v_mov_b32_e32 v3, v0
	v_mov_b32_e32 v4, v0
	v_mov_b32_e32 v5, v0
	v_mov_b32_e32 v6, v0
	v_mov_b32_e32 v7, v0
	v_mov_b32_e32 v8, v0
	v_mov_b32_e32 v9, v0
	v_mov_b32_e32 v10, v0
	v_mov_b32_e32 v11, v0
	v_mov_b32_e32 v12, v0
	v_mov_b32_e32 v13, v0
	v_mov_b32_e32 v14, v0
	v_mov_b32_e32 v15, v0
	v_mov_b32_e32 v16, v0
	v_mov_b32_e32 v17, v0
	v_mov_b32_e32 v18, v0
	v_mov_b32_e32 v19, v0
	v_mov_b32_e32 v20, v0
	v_mov_b32_e32 v21, v0
	v_mov_b32_e32 v22, v0
	v_mov_b32_e32 v23, v0
	v_mov_b32_e32 v24, v0
	v_mov_b32_e32 v25, v0
	v_mov_b32_e32 v26, v0
	v_mov_b32_e32 v27, v0
	v_mov_b32_e32 v28, v0
	v_mov_b32_e32 v29, v0
	v_mov_b32_e32 v30, v0
	v_mov_b32_e32 v31, v0
	v_mov_b32_e32 v32, v0
	v_mov_b32_e32 v33, v0
	v_mov_b32_e32 v34, v0
	v_mov_b32_e32 v35, v0
	v_mov_b32_e32 v36, v0
	v_mov_b32_e32 v37, v0
	v_mov_b32_e32 v38, v0
	v_mov_b32_e32 v39, v0
	v_mov_b32_e32 v40, v0
	v_mov_b32_e32 v41, v0
	v_mov_b32_e32 v42, v0
	v_mov_b32_e32 v43, v0
	v_mov_b32_e32 v44, v0
	v_mov_b32_e32 v45, v0
	v_mov_b32_e32 v46, v0
	v_mov_b32_e32 v47, v0
	v_mov_b32_e32 v48, v0
	v_mov_b32_e32 v49, v0
	v_mov_b32_e32 v50, v0
	v_mov_b32_e32 v51, v0
	v_mov_b32_e32 v52, v0
	v_mov_b32_e32 v53, v0
	v_mov_b32_e32 v54, v0
	v_mov_b32_e32 v55, v0
	v_mov_b32_e32 v56, v0
	v_mov_b32_e32 v57, v0
	v_mov_b32_e32 v58, v0
	v_mov_b32_e32 v59, v0
	v_mov_b32_e32 v60, v0
	v_mov_b32_e32 v61, v0
	v_mov_b32_e32 v62, v0
	v_mov_b32_e32 v63, v0
	v_mov_b32_e32 v64, v0
	v_mov_b32_e32 v65, v0
	v_mov_b32_e32 v66, v0
	v_mov_b32_e32 v67, v0
	v_mov_b32_e32 v68, v0
	v_mov_b32_e32 v69, v0
	v_mov_b32_e32 v70, v0
	v_mov_b32_e32 v71, v0
	v_mov_b32_e32 v72, v0
	v_mov_b32_e32 v73, v0
	v_mov_b32_e32 v74, v0
	v_mov_b32_e32 v75, v0
	v_mov_b32_e32 v76, v0
	v_mov_b32_e32 v77, v0
	v_mov_b32_e32 v78, v0
	v_mov_b32_e32 v79, v0
	v_mov_b32_e32 v80, v0
	v_mov_b32_e32 v81, v0
	v_mov_b32_e32 v82, v0
	v_mov_b32_e32 v83, v0
	v_mov_b32_e32 v84, v0
	v_mov_b32_e32 v85, v0
	v_mov_b32_e32 v86, v0
	v_mov_b32_e32 v87, v0
	v_mov_b32_e32 v88, v0
	v_mov_b32_e32 v89, v0
	v_mov_b32_e32 v90, v0
	v_mov_b32_e32 v91, v0
	v_mov_b32_e32 v92, v0
	v_mov_b32_e32 v93, v0
	v_mov_b32_e32 v94, v0
	v_mov_b32_e32 v95, v0
	v_mov_b32_e32 v96, v0
	v_mov_b32_e32 v97, v0
	v_mov_b32_e32 v98, v0
	v_mov_b32_e32 v99, v0
	v_mov_b32_e32 v100, v0
	v_mov_b32_e32 v101, v0
	v_mov_b32_e32 v102, v0
	v_mov_b32_e32 v103, v0
	v_mov_b32_e32 v104, v0
	v_mov_b32_e32 v105, v0
	v_mov_b32_e32 v106, v0
	v_mov_b32_e32 v107, v0
	v_mov_b32_e32 v108, v0
	v_mov_b32_e32 v109, v0
	v_mov_b32_e32 v110, v0
	v_mov_b32_e32 v111, v0
	v_mov_b32_e32 v112, v0
	v_mov_b32_e32 v113, v0
	v_mov_b32_e32 v114, v0
	v_mov_b32_e32 v115, v0
	v_mov_b32_e32 v116, v0
	v_mov_b32_e32 v117, v0
	v_mov_b32_e32 v118, v0
	v_mov_b32_e32 v119, v0
	v_mov_b32_e32 v120, v0
	v_mov_b32_e32 v121, v0
	v_mov_b32_e32 v122, v0
	v_mov_b32_e32 v123, v0
	v_mov_b32_e32 v124, v0
	v_mov_b32_e32 v125, v0
	v_mov_b32_e32 v126, v0
	v_mov_b32_e32 v127, v0
.Lkrot_1184:
	s_barrier
.LBB0_1184:
	ds_read_b128 v[136:139], v170
	ds_read_b128 v[174:177], v170 offset:1024
	ds_read_b128 v[178:181], v170 offset:2048
	ds_read_b128 v[182:185], v170 offset:3072
	v_add_u32_e32 v171, 0xc000, v157
	v_lshl_add_u64 v[238:239], s[92:93], 0, v[148:149]
	v_readfirstlane_b32 s54, v171
	v_lshl_add_u64 v[172:173], v[238:239], 0, s[86:87]
	s_mov_b32 m0, s54
	ds_read_b128 v[186:189], v162
	ds_read_b128 v[190:193], v162 offset:1024
	ds_read_b128 v[194:197], v161
	ds_read_b128 v[198:201], v161 offset:1024
	ds_read_b128 v[202:205], v160
	ds_read_b128 v[208:211], v160 offset:1024
	ds_read_b128 v[214:217], v159
	ds_read_b128 v[218:221], v159 offset:1024
	global_load_lds_dwordx4 v[172:173], off
	v_add_u32_e32 v172, 0xe000, v157
	v_lshl_add_u64 v[240:241], s[92:93], 0, v[150:151]
	v_readfirstlane_b32 s54, v172
	v_lshl_add_u64 v[222:223], v[240:241], 0, s[86:87]
	s_mov_b32 m0, s54
	s_nop 0
	global_load_lds_dwordx4 v[222:223], off
	s_waitcnt lgkmcnt(8)
	s_barrier
	s_waitcnt lgkmcnt(0)
	s_waitcnt lgkmcnt(0)
	v_mfma_f32_16x16x32_bf16 v[124:127], v[136:139], v[186:189], v[124:127]
	v_mfma_f32_16x16x32_bf16 v[120:123], v[178:181], v[186:189], v[120:123]
	v_mfma_f32_16x16x32_bf16 v[116:119], v[136:139], v[194:197], v[116:119]
	v_mfma_f32_16x16x32_bf16 v[112:115], v[178:181], v[194:197], v[112:115]
	v_mfma_f32_16x16x32_bf16 v[108:111], v[136:139], v[202:205], v[108:111]
	v_mfma_f32_16x16x32_bf16 v[104:107], v[178:181], v[202:205], v[104:107]
	v_mfma_f32_16x16x32_bf16 v[100:103], v[136:139], v[214:217], v[100:103]
	v_mfma_f32_16x16x32_bf16 v[96:99], v[178:181], v[214:217], v[96:99]
	v_mfma_f32_16x16x32_bf16 v[124:127], v[174:177], v[190:193], v[124:127]
	v_mfma_f32_16x16x32_bf16 v[120:123], v[182:185], v[190:193], v[120:123]
	v_mfma_f32_16x16x32_bf16 v[116:119], v[174:177], v[198:201], v[116:119]
	v_mfma_f32_16x16x32_bf16 v[112:115], v[182:185], v[198:201], v[112:115]
	v_mfma_f32_16x16x32_bf16 v[108:111], v[174:177], v[208:211], v[108:111]
	v_mfma_f32_16x16x32_bf16 v[104:107], v[182:185], v[208:211], v[104:107]
	v_mfma_f32_16x16x32_bf16 v[100:103], v[174:177], v[218:221], v[100:103]
	v_mfma_f32_16x16x32_bf16 v[96:99], v[182:185], v[218:221], v[96:99]
	s_barrier
; #define STAGE(P, BASE, br, kt) STAGET(tid_, P, BASE, br, kt)
; #define LDA(dst, b, h) UFOR(m, 4) UFOR(k, 2) \
;     dst[m][k] = *reinterpret_cast<const bf16x8*>((char*)SA(b, h) + lds_byte(wr * 64 + m * 16 + fr, k * 32 + fq * 8))
; #define LDB(dst, b, h) UFOR(n, 2) UFOR(k, 2) \
;     dst[n][k] = *reinterpret_cast<const bf16x8*>((char*)SB(b, h) + lds_byte(wc * 32 + n * 16 + fr, k * 32 + fq * 8))
; #define MMA(ai, bj, At, Bq) do { __builtin_amdgcn_s_setprio(1); \
;     UFOR(m, 4) UFOR(n, 2) UFOR(k, 2) \
;       acc[ai][bj][m][n] = __builtin_amdgcn_mfma_f32_16x16x32_bf16(Bq[n][k], At[m][k], acc[ai][bj][m][n], 0, 0, 0); \
;     __builtin_amdgcn_s_setprio(0); } while (0)
; #define WAIT_V(n) asm volatile("s_waitcnt vmcnt(" #n ")" ::: "memory")
; #define WAIT_L(n) asm volatile("s_waitcnt lgkmcnt(" #n ")" ::: "memory")
; #define BAR __builtin_amdgcn_s_barrier()
; #define SCHED __builtin_amdgcn_sched_barrier(0)
; template <int EPI, int K, int KL> ...
;     ...
;     LDB(B1, 0, 1); STAGE(SB(0, 0), Bt, bcol, t + 2);
;     BAR; WAIT_L(0); MMA(0, 1, At, B1); BAR;
;     LDA(At, 0, 1); STAGE(SA(0, 0), A, brow, t + 2);
;     BAR; WAIT_L(0); MMA(1, 0, At, B0); BAR; SCHED;
;     STAGE(SB(0, 1), Bt, bcol + HALF, t + 2);
;     WAIT_V(6); BAR; MMA(1, 1, At, B1); BAR;
;     LDB(B0, 1, 0); SCHED; LDA(At, 1, 0); STAGE(SA(0, 1), A, brow + HALF, t + 2);
;     WAIT_L(8); BAR; WAIT_L(0); MMA(0, 0, At, B0); BAR; SCHED;
	v_lshl_add_u64 v[242:243], s[92:93], 0, v[144:145]
	v_readfirstlane_b32 s54, v156
	v_lshl_add_u64 v[244:245], v[242:243], 0, s[22:23]
	s_mov_b32 m0, s54
	v_add_u32_e32 v134, 0x2000, v156
	ds_read_b128 v[222:225], v169
	ds_read_b128 v[226:229], v169 offset:1024
	ds_read_b128 v[230:233], v169 offset:2048
	ds_read_b128 v[234:237], v169 offset:3072
	global_load_lds_dwordx4 v[244:245], off
	v_lshl_add_u64 v[244:245], s[92:93], 0, v[146:147]
	v_readfirstlane_b32 s54, v134
	v_lshl_add_u64 v[246:247], v[244:245], 0, s[22:23]
	s_mov_b32 m0, s54
	s_nop 0
	global_load_lds_dwordx4 v[246:247], off
	s_barrier
	s_waitcnt lgkmcnt(0)
	s_waitcnt lgkmcnt(0)
	v_mfma_f32_16x16x32_bf16 v[92:95], v[222:225], v[186:189], v[92:95]
	v_mfma_f32_16x16x32_bf16 v[88:91], v[230:233], v[186:189], v[88:91]
	v_mfma_f32_16x16x32_bf16 v[84:87], v[222:225], v[194:197], v[84:87]
	v_mfma_f32_16x16x32_bf16 v[80:83], v[230:233], v[194:197], v[80:83]
	v_mfma_f32_16x16x32_bf16 v[76:79], v[222:225], v[202:205], v[76:79]
	v_mfma_f32_16x16x32_bf16 v[72:75], v[230:233], v[202:205], v[72:75]
	v_mfma_f32_16x16x32_bf16 v[68:71], v[222:225], v[214:217], v[68:71]
	v_mfma_f32_16x16x32_bf16 v[64:67], v[230:233], v[214:217], v[64:67]
	v_mfma_f32_16x16x32_bf16 v[92:95], v[226:229], v[190:193], v[92:95]
	v_mfma_f32_16x16x32_bf16 v[88:91], v[234:237], v[190:193], v[88:91]
	v_mfma_f32_16x16x32_bf16 v[84:87], v[226:229], v[198:201], v[84:87]
	v_mfma_f32_16x16x32_bf16 v[80:83], v[234:237], v[198:201], v[80:83]
	v_mfma_f32_16x16x32_bf16 v[76:79], v[226:229], v[208:211], v[76:79]
	v_mfma_f32_16x16x32_bf16 v[72:75], v[234:237], v[208:211], v[72:75]
	v_mfma_f32_16x16x32_bf16 v[68:71], v[226:229], v[218:221], v[68:71]
	v_mfma_f32_16x16x32_bf16 v[64:67], v[234:237], v[218:221], v[64:67]
	v_readfirstlane_b32 s54, v157
	v_add_u32_e32 v134, 0x2000, v157
	v_lshl_add_u64 v[246:247], v[238:239], 0, s[34:35]
	s_mov_b32 m0, s54
	v_readfirstlane_b32 s54, v134
	s_barrier
	ds_read_b128 v[186:189], v162 offset:16384
	ds_read_b128 v[190:193], v162 offset:17408
	ds_read_b128 v[194:197], v161 offset:16384
	ds_read_b128 v[198:201], v161 offset:17408
	ds_read_b128 v[202:205], v160 offset:16384
	ds_read_b128 v[208:211], v160 offset:17408
	ds_read_b128 v[214:217], v159 offset:16384
	ds_read_b128 v[218:221], v159 offset:17408
	global_load_lds_dwordx4 v[246:247], off
	v_lshl_add_u64 v[246:247], v[240:241], 0, s[34:35]
	s_mov_b32 m0, s54
	s_nop 0
	global_load_lds_dwordx4 v[246:247], off
	s_barrier
	s_waitcnt lgkmcnt(0)
	s_waitcnt lgkmcnt(0)
	v_mfma_f32_16x16x32_bf16 v[60:63], v[136:139], v[186:189], v[60:63]
	v_mfma_f32_16x16x32_bf16 v[56:59], v[178:181], v[186:189], v[56:59]
	v_mfma_f32_16x16x32_bf16 v[52:55], v[136:139], v[194:197], v[52:55]
	v_mfma_f32_16x16x32_bf16 v[48:51], v[178:181], v[194:197], v[48:51]
	v_mfma_f32_16x16x32_bf16 v[44:47], v[136:139], v[202:205], v[44:47]
	v_mfma_f32_16x16x32_bf16 v[40:43], v[178:181], v[202:205], v[40:43]
	v_mfma_f32_16x16x32_bf16 v[36:39], v[136:139], v[214:217], v[36:39]
	v_mfma_f32_16x16x32_bf16 v[32:35], v[178:181], v[214:217], v[32:35]
	v_mfma_f32_16x16x32_bf16 v[60:63], v[174:177], v[190:193], v[60:63]
	v_mfma_f32_16x16x32_bf16 v[56:59], v[182:185], v[190:193], v[56:59]
	v_mfma_f32_16x16x32_bf16 v[52:55], v[174:177], v[198:201], v[52:55]
	v_mfma_f32_16x16x32_bf16 v[48:51], v[182:185], v[198:201], v[48:51]
	v_mfma_f32_16x16x32_bf16 v[44:47], v[174:177], v[208:211], v[44:47]
	v_mfma_f32_16x16x32_bf16 v[40:43], v[182:185], v[208:211], v[40:43]
	v_mfma_f32_16x16x32_bf16 v[36:39], v[174:177], v[218:221], v[36:39]
	v_mfma_f32_16x16x32_bf16 v[32:35], v[182:185], v[218:221], v[32:35]
	s_barrier
	v_readfirstlane_b32 s54, v158
	v_add_u32_e32 v134, 0x2000, v158
	v_lshl_add_u64 v[136:137], v[242:243], 0, s[24:25]
	s_mov_b32 m0, s54
	v_readfirstlane_b32 s54, v134
	global_load_lds_dwordx4 v[136:137], off
	v_lshl_add_u64 v[136:137], v[244:245], 0, s[24:25]
	s_mov_b32 m0, s54
	s_nop 0
	global_load_lds_dwordx4 v[136:137], off
	s_waitcnt vmcnt(6)
	s_barrier
	v_mfma_f32_16x16x32_bf16 v[28:31], v[222:225], v[186:189], v[28:31]
	v_mfma_f32_16x16x32_bf16 v[24:27], v[230:233], v[186:189], v[24:27]
	v_mfma_f32_16x16x32_bf16 v[20:23], v[222:225], v[194:197], v[20:23]
	v_mfma_f32_16x16x32_bf16 v[16:19], v[230:233], v[194:197], v[16:19]
	v_mfma_f32_16x16x32_bf16 v[12:15], v[222:225], v[202:205], v[12:15]
	v_mfma_f32_16x16x32_bf16 v[8:11], v[230:233], v[202:205], v[8:11]
	v_mfma_f32_16x16x32_bf16 v[4:7], v[222:225], v[214:217], v[4:7]
	v_mfma_f32_16x16x32_bf16 v[0:3], v[230:233], v[214:217], v[0:3]
	v_mfma_f32_16x16x32_bf16 v[28:31], v[226:229], v[190:193], v[28:31]
	v_mfma_f32_16x16x32_bf16 v[24:27], v[234:237], v[190:193], v[24:27]
	v_mfma_f32_16x16x32_bf16 v[20:23], v[226:229], v[198:201], v[20:23]
	v_mfma_f32_16x16x32_bf16 v[16:19], v[234:237], v[198:201], v[16:19]
	v_mfma_f32_16x16x32_bf16 v[12:15], v[226:229], v[208:211], v[12:15]
	v_mfma_f32_16x16x32_bf16 v[8:11], v[234:237], v[208:211], v[8:11]
	v_mfma_f32_16x16x32_bf16 v[4:7], v[226:229], v[218:221], v[4:7]
	v_mfma_f32_16x16x32_bf16 v[0:3], v[234:237], v[218:221], v[0:3]
	s_barrier
	ds_read_b128 v[136:139], v165
	ds_read_b128 v[174:177], v165 offset:1024
	ds_read_b128 v[178:181], v165 offset:2048
	ds_read_b128 v[182:185], v165 offset:3072
	v_add_u32_e32 v134, 0x4000, v157
	v_lshl_add_u64 v[222:223], v[238:239], 0, s[28:29]
	v_readfirstlane_b32 s54, v134
	v_add_u32_e32 v134, 0x6000, v157
	s_mov_b32 m0, s54
	v_readfirstlane_b32 s54, v134
	ds_read_b128 v[186:189], v162 offset:32768
	ds_read_b128 v[190:193], v162 offset:33792
	ds_read_b128 v[194:197], v161 offset:32768
	ds_read_b128 v[198:201], v161 offset:33792
	ds_read_b128 v[202:205], v160 offset:32768
	ds_read_b128 v[208:211], v160 offset:33792
	ds_read_b128 v[214:217], v159 offset:32768
	ds_read_b128 v[218:221], v159 offset:33792
	global_load_lds_dwordx4 v[222:223], off
	v_lshl_add_u64 v[222:223], v[240:241], 0, s[28:29]
	s_mov_b32 m0, s54
	s_nop 0
	global_load_lds_dwordx4 v[222:223], off
	s_waitcnt lgkmcnt(8)
	s_barrier
; #define STAGE(P, BASE, br, kt) STAGET(tid_, P, BASE, br, kt)
; #define LDA(dst, b, h) UFOR(m, 4) UFOR(k, 2) \
;     dst[m][k] = *reinterpret_cast<const bf16x8*>((char*)SA(b, h) + lds_byte(wr * 64 + m * 16 + fr, k * 32 + fq * 8))
; #define LDB(dst, b, h) UFOR(n, 2) UFOR(k, 2) \
;     dst[n][k] = *reinterpret_cast<const bf16x8*>((char*)SB(b, h) + lds_byte(wc * 32 + n * 16 + fr, k * 32 + fq * 8))
; #define MMA(ai, bj, At, Bq) do { __builtin_amdgcn_s_setprio(1); \
;     UFOR(m, 4) UFOR(n, 2) UFOR(k, 2) \
;       acc[ai][bj][m][n] = __builtin_amdgcn_mfma_f32_16x16x32_bf16(Bq[n][k], At[m][k], acc[ai][bj][m][n], 0, 0, 0); \
;     __builtin_amdgcn_s_setprio(0); } while (0)
; #define WAIT_V(n) asm volatile("s_waitcnt vmcnt(" #n ")" ::: "memory")
; #define WAIT_L(n) asm volatile("s_waitcnt lgkmcnt(" #n ")" ::: "memory")
; #define BAR __builtin_amdgcn_s_barrier()
; #define SCHED __builtin_amdgcn_sched_barrier(0)
; template <int EPI, int K, int KL> ...
;     ...
;     LDB(B0, 1, 0); SCHED; LDA(At, 1, 0); STAGE(SA(0, 1), A, brow + HALF, t + 2);
;     WAIT_L(8); BAR; WAIT_L(0); MMA(0, 0, At, B0); BAR; SCHED;
;     LDB(B1, 1, 1); STAGE(SB(1, 0), Bt, bcol, t + 3);
;     BAR; WAIT_L(0); MMA(0, 1, At, B1); BAR;
;     LDA(At, 1, 1); STAGE(SA(1, 0), A, brow, t + 3);
;     BAR; WAIT_L(0); MMA(1, 0, At, B0); BAR; SCHED;
;     STAGE(SB(1, 1), Bt, bcol + HALF, t + 3);
;     WAIT_V(6); BAR; MMA(1, 1, At, B1); BAR;
	s_waitcnt lgkmcnt(0)
	s_waitcnt lgkmcnt(0)
	v_mfma_f32_16x16x32_bf16 v[124:127], v[136:139], v[186:189], v[124:127]
	v_mfma_f32_16x16x32_bf16 v[120:123], v[178:181], v[186:189], v[120:123]
	v_mfma_f32_16x16x32_bf16 v[116:119], v[136:139], v[194:197], v[116:119]
	v_mfma_f32_16x16x32_bf16 v[112:115], v[178:181], v[194:197], v[112:115]
	v_mfma_f32_16x16x32_bf16 v[108:111], v[136:139], v[202:205], v[108:111]
	v_mfma_f32_16x16x32_bf16 v[104:107], v[178:181], v[202:205], v[104:107]
	v_mfma_f32_16x16x32_bf16 v[100:103], v[136:139], v[214:217], v[100:103]
	v_mfma_f32_16x16x32_bf16 v[96:99], v[178:181], v[214:217], v[96:99]
	v_mfma_f32_16x16x32_bf16 v[124:127], v[174:177], v[190:193], v[124:127]
	v_mfma_f32_16x16x32_bf16 v[120:123], v[182:185], v[190:193], v[120:123]
	v_mfma_f32_16x16x32_bf16 v[116:119], v[174:177], v[198:201], v[116:119]
	v_mfma_f32_16x16x32_bf16 v[112:115], v[182:185], v[198:201], v[112:115]
	v_mfma_f32_16x16x32_bf16 v[108:111], v[174:177], v[208:211], v[108:111]
	v_mfma_f32_16x16x32_bf16 v[104:107], v[182:185], v[208:211], v[104:107]
	v_mfma_f32_16x16x32_bf16 v[100:103], v[174:177], v[218:221], v[100:103]
	v_mfma_f32_16x16x32_bf16 v[96:99], v[182:185], v[218:221], v[96:99]
	s_barrier
	v_readfirstlane_b32 s54, v164
	v_add_u32_e32 v134, 0x2000, v164
	v_lshl_add_u64 v[246:247], v[242:243], 0, s[94:95]
	s_mov_b32 m0, s54
	v_readfirstlane_b32 s54, v134
	ds_read_b128 v[222:225], v163
	ds_read_b128 v[226:229], v163 offset:1024
	ds_read_b128 v[230:233], v163 offset:2048
	ds_read_b128 v[234:237], v163 offset:3072
	global_load_lds_dwordx4 v[246:247], off
	v_lshl_add_u64 v[246:247], v[244:245], 0, s[94:95]
	s_mov_b32 m0, s54
	s_nop 0
	global_load_lds_dwordx4 v[246:247], off
	s_barrier
	s_waitcnt lgkmcnt(0)
	s_waitcnt lgkmcnt(0)
	v_mfma_f32_16x16x32_bf16 v[92:95], v[222:225], v[186:189], v[92:95]
	v_mfma_f32_16x16x32_bf16 v[88:91], v[230:233], v[186:189], v[88:91]
	v_mfma_f32_16x16x32_bf16 v[84:87], v[222:225], v[194:197], v[84:87]
	v_mfma_f32_16x16x32_bf16 v[80:83], v[230:233], v[194:197], v[80:83]
	v_mfma_f32_16x16x32_bf16 v[76:79], v[222:225], v[202:205], v[76:79]
	v_mfma_f32_16x16x32_bf16 v[72:75], v[230:233], v[202:205], v[72:75]
	v_mfma_f32_16x16x32_bf16 v[68:71], v[222:225], v[214:217], v[68:71]
	v_mfma_f32_16x16x32_bf16 v[64:67], v[230:233], v[214:217], v[64:67]
	v_mfma_f32_16x16x32_bf16 v[92:95], v[226:229], v[190:193], v[92:95]
	v_mfma_f32_16x16x32_bf16 v[88:91], v[234:237], v[190:193], v[88:91]
	v_mfma_f32_16x16x32_bf16 v[84:87], v[226:229], v[198:201], v[84:87]
	v_mfma_f32_16x16x32_bf16 v[80:83], v[234:237], v[198:201], v[80:83]
	v_mfma_f32_16x16x32_bf16 v[76:79], v[226:229], v[208:211], v[76:79]
	v_mfma_f32_16x16x32_bf16 v[72:75], v[234:237], v[208:211], v[72:75]
	v_mfma_f32_16x16x32_bf16 v[68:71], v[226:229], v[218:221], v[68:71]
	v_mfma_f32_16x16x32_bf16 v[64:67], v[234:237], v[218:221], v[64:67]
	v_readfirstlane_b32 s54, v166
	v_lshl_add_u64 v[238:239], v[238:239], 0, s[4:5]
	s_mov_b32 m0, s54
	v_readfirstlane_b32 s54, v167
	s_barrier
	ds_read_b128 v[186:189], v162 offset:49152
	ds_read_b128 v[190:193], v162 offset:50176
	ds_read_b128 v[194:197], v161 offset:49152
	ds_read_b128 v[198:201], v161 offset:50176
	ds_read_b128 v[202:205], v160 offset:49152
	ds_read_b128 v[208:211], v160 offset:50176
	ds_read_b128 v[214:217], v159 offset:49152
	ds_read_b128 v[218:221], v159 offset:50176
	global_load_lds_dwordx4 v[238:239], off
	v_lshl_add_u64 v[238:239], v[240:241], 0, s[4:5]
	s_mov_b32 m0, s54
	s_nop 0
	global_load_lds_dwordx4 v[238:239], off
	s_barrier
	s_waitcnt lgkmcnt(0)
	s_waitcnt lgkmcnt(0)
	v_mfma_f32_16x16x32_bf16 v[60:63], v[136:139], v[186:189], v[60:63]
	v_mfma_f32_16x16x32_bf16 v[56:59], v[178:181], v[186:189], v[56:59]
	v_mfma_f32_16x16x32_bf16 v[52:55], v[136:139], v[194:197], v[52:55]
	v_mfma_f32_16x16x32_bf16 v[48:51], v[178:181], v[194:197], v[48:51]
	v_mfma_f32_16x16x32_bf16 v[44:47], v[136:139], v[202:205], v[44:47]
	v_mfma_f32_16x16x32_bf16 v[40:43], v[178:181], v[202:205], v[40:43]
	v_mfma_f32_16x16x32_bf16 v[36:39], v[136:139], v[214:217], v[36:39]
	v_mfma_f32_16x16x32_bf16 v[32:35], v[178:181], v[214:217], v[32:35]
	v_mfma_f32_16x16x32_bf16 v[60:63], v[174:177], v[190:193], v[60:63]
	v_mfma_f32_16x16x32_bf16 v[56:59], v[182:185], v[190:193], v[56:59]
	v_mfma_f32_16x16x32_bf16 v[52:55], v[174:177], v[198:201], v[52:55]
	v_mfma_f32_16x16x32_bf16 v[48:51], v[182:185], v[198:201], v[48:51]
	v_mfma_f32_16x16x32_bf16 v[44:47], v[174:177], v[208:211], v[44:47]
	v_mfma_f32_16x16x32_bf16 v[40:43], v[182:185], v[208:211], v[40:43]
	v_mfma_f32_16x16x32_bf16 v[36:39], v[174:177], v[218:221], v[36:39]
	v_mfma_f32_16x16x32_bf16 v[32:35], v[182:185], v[218:221], v[32:35]
	s_barrier
	v_readfirstlane_b32 s54, v168
	v_add_u32_e32 v134, 0x2000, v168
	v_lshl_add_u64 v[136:137], v[242:243], 0, s[10:11]
	s_mov_b32 m0, s54
	v_readfirstlane_b32 s54, v134
	global_load_lds_dwordx4 v[136:137], off
	v_lshl_add_u64 v[136:137], v[244:245], 0, s[10:11]
	s_mov_b32 m0, s54
	s_nop 0
	global_load_lds_dwordx4 v[136:137], off
	s_waitcnt vmcnt(6)
	s_barrier
; #define STAGE(P, BASE, br, kt) STAGET(tid_, P, BASE, br, kt)
; #define LDA(dst, b, h) UFOR(m, 4) UFOR(k, 2) \
;     dst[m][k] = *reinterpret_cast<const bf16x8*>((char*)SA(b, h) + lds_byte(wr * 64 + m * 16 + fr, k * 32 + fq * 8))
; #define LDB(dst, b, h) UFOR(n, 2) UFOR(k, 2) \
;     dst[n][k] = *reinterpret_cast<const bf16x8*>((char*)SB(b, h) + lds_byte(wc * 32 + n * 16 + fr, k * 32 + fq * 8))
; #define MMA(ai, bj, At, Bq) do { __builtin_amdgcn_s_setprio(1); \
;     UFOR(m, 4) UFOR(n, 2) UFOR(k, 2) \
;       acc[ai][bj][m][n] = __builtin_amdgcn_mfma_f32_16x16x32_bf16(Bq[n][k], At[m][k], acc[ai][bj][m][n], 0, 0, 0); \
;     __builtin_amdgcn_s_setprio(0); } while (0)
; #define WAIT_V(n) asm volatile("s_waitcnt vmcnt(" #n ")" ::: "memory")
; #define WAIT_L(n) asm volatile("s_waitcnt lgkmcnt(" #n ")" ::: "memory")
; #define BAR __builtin_amdgcn_s_barrier()
; template <int EPI, int K, int KL> ...
;     ...
;     WAIT_V(6); BAR; MMA(1, 1, At, B1); BAR;
;   }
;   { LDB(B0, 0, 0); LDA(At, 0, 0); STAGE(SA(1, 1), A, brow + HALF, nt - 1);
;     BAR; WAIT_L(0); MMA(0, 0, At, B0); BAR;
;     LDB(B1, 0, 1); BAR; WAIT_L(0); MMA(0, 1, At, B1); BAR;
;     LDA(At, 0, 1); WAIT_V(4); BAR; WAIT_L(0); MMA(1, 0, At, B0); MMA(1, 1, At, B1); BAR; }
	v_mfma_f32_16x16x32_bf16 v[28:31], v[222:225], v[186:189], v[28:31]
	v_mfma_f32_16x16x32_bf16 v[24:27], v[230:233], v[186:189], v[24:27]
	v_mfma_f32_16x16x32_bf16 v[20:23], v[222:225], v[194:197], v[20:23]
	v_mfma_f32_16x16x32_bf16 v[16:19], v[230:233], v[194:197], v[16:19]
	v_mfma_f32_16x16x32_bf16 v[12:15], v[222:225], v[202:205], v[12:15]
	v_mfma_f32_16x16x32_bf16 v[8:11], v[230:233], v[202:205], v[8:11]
	v_mfma_f32_16x16x32_bf16 v[4:7], v[222:225], v[214:217], v[4:7]
	v_mfma_f32_16x16x32_bf16 v[0:3], v[230:233], v[214:217], v[0:3]
	v_mfma_f32_16x16x32_bf16 v[28:31], v[226:229], v[190:193], v[28:31]
	v_mfma_f32_16x16x32_bf16 v[24:27], v[234:237], v[190:193], v[24:27]
	v_mfma_f32_16x16x32_bf16 v[20:23], v[226:229], v[198:201], v[20:23]
	v_mfma_f32_16x16x32_bf16 v[16:19], v[234:237], v[198:201], v[16:19]
	v_mfma_f32_16x16x32_bf16 v[12:15], v[226:229], v[208:211], v[12:15]
	v_mfma_f32_16x16x32_bf16 v[8:11], v[234:237], v[208:211], v[8:11]
	v_mfma_f32_16x16x32_bf16 v[4:7], v[226:229], v[218:221], v[4:7]
	v_mfma_f32_16x16x32_bf16 v[0:3], v[234:237], v[218:221], v[0:3]
	s_add_i32 s19, s19, 2
	v_lshl_add_u64 v[144:145], v[144:145], 0, s[20:21]
	v_lshl_add_u64 v[146:147], v[146:147], 0, s[20:21]
	v_lshl_add_u64 v[148:149], v[148:149], 0, s[20:21]
	s_cmpk_lt_u32 s19, 0x54
	v_lshl_add_u64 v[150:151], v[150:151], 0, s[20:21]
	s_cbranch_scc1 .Lkrot_1184
	s_barrier
	s_add_u32 s52, s52, 0x162b80
	s_addc_u32 s53, s53, 0
	v_lshl_add_u64 v[130:131], s[52:53], 0, v[130:131]
	v_readfirstlane_b32 s19, v171
	v_lshl_add_u64 v[128:129], v[128:129], 1, v[130:131]
	s_mov_b32 m0, s19
	ds_read_b128 v[136:139], v170
	ds_read_b128 v[144:147], v170 offset:1024
	ds_read_b128 v[148:151], v170 offset:2048
	ds_read_b128 v[174:177], v170 offset:3072
	ds_read_b128 v[178:181], v162
	ds_read_b128 v[182:185], v162 offset:1024
	ds_read_b128 v[186:189], v161
	ds_read_b128 v[190:193], v161 offset:1024
	ds_read_b128 v[194:197], v160
	ds_read_b128 v[198:201], v160 offset:1024
	ds_read_b128 v[202:205], v159
	ds_read_b128 v[208:211], v159 offset:1024
	global_load_lds_dwordx4 v[128:129], off
	v_lshl_add_u64 v[128:129], s[52:53], 0, v[142:143]
	v_readfirstlane_b32 s19, v172
	v_lshl_add_u64 v[128:129], v[140:141], 1, v[128:129]
	s_mov_b32 m0, s19
	s_nop 0
	global_load_lds_dwordx4 v[128:129], off
	s_barrier
	s_waitcnt lgkmcnt(0)
	s_waitcnt lgkmcnt(0)
	v_mfma_f32_16x16x32_bf16 v[120:123], v[148:151], v[178:181], v[120:123]
	v_mfma_f32_16x16x32_bf16 v[116:119], v[136:139], v[186:189], v[116:119]
	v_mfma_f32_16x16x32_bf16 v[112:115], v[148:151], v[186:189], v[112:115]
	v_mfma_f32_16x16x32_bf16 v[108:111], v[136:139], v[194:197], v[108:111]
	v_mfma_f32_16x16x32_bf16 v[104:107], v[148:151], v[194:197], v[104:107]
	v_mfma_f32_16x16x32_bf16 v[100:103], v[136:139], v[202:205], v[100:103]
	v_mfma_f32_16x16x32_bf16 v[96:99], v[148:151], v[202:205], v[96:99]
	v_mfma_f32_16x16x32_bf16 v[124:127], v[136:139], v[178:181], v[124:127]
	v_mfma_f32_16x16x32_bf16 v[120:123], v[174:177], v[182:185], v[120:123]
	v_mfma_f32_16x16x32_bf16 v[116:119], v[144:147], v[190:193], v[116:119]
	v_mfma_f32_16x16x32_bf16 v[112:115], v[174:177], v[190:193], v[112:115]
	v_mfma_f32_16x16x32_bf16 v[108:111], v[144:147], v[198:201], v[108:111]
	v_mfma_f32_16x16x32_bf16 v[104:107], v[174:177], v[198:201], v[104:107]
	v_mfma_f32_16x16x32_bf16 v[100:103], v[144:147], v[208:211], v[100:103]
	v_mfma_f32_16x16x32_bf16 v[96:99], v[174:177], v[208:211], v[96:99]
	v_mfma_f32_16x16x32_bf16 v[124:127], v[144:147], v[182:185], v[124:127]
	s_barrier
	ds_read_b128 v[128:131], v169
	ds_read_b128 v[140:143], v169 offset:1024
	ds_read_b128 v[170:173], v169 offset:2048
	ds_read_b128 v[166:169], v169 offset:3072
	s_barrier
	s_waitcnt lgkmcnt(0)
	s_waitcnt lgkmcnt(0)
	v_mfma_f32_16x16x32_bf16 v[80:83], v[170:173], v[186:189], v[80:83]
	v_mfma_f32_16x16x32_bf16 v[76:79], v[128:131], v[194:197], v[76:79]
	v_mfma_f32_16x16x32_bf16 v[68:71], v[128:131], v[202:205], v[68:71]
	v_mfma_f32_16x16x32_bf16 v[64:67], v[170:173], v[202:205], v[64:67]
	v_mfma_f32_16x16x32_bf16 v[92:95], v[128:131], v[178:181], v[92:95]
	v_mfma_f32_16x16x32_bf16 v[88:91], v[170:173], v[178:181], v[88:91]
	v_mfma_f32_16x16x32_bf16 v[84:87], v[128:131], v[186:189], v[84:87]
	v_mfma_f32_16x16x32_bf16 v[80:83], v[166:169], v[190:193], v[80:83]
	v_mfma_f32_16x16x32_bf16 v[76:79], v[140:143], v[198:201], v[76:79]
	v_mfma_f32_16x16x32_bf16 v[72:75], v[170:173], v[194:197], v[72:75]
	v_mfma_f32_16x16x32_bf16 v[68:71], v[140:143], v[208:211], v[68:71]
	v_mfma_f32_16x16x32_bf16 v[64:67], v[166:169], v[208:211], v[64:67]
	v_mfma_f32_16x16x32_bf16 v[214:217], v[140:143], v[182:185], v[92:95]
	v_mfma_f32_16x16x32_bf16 v[178:181], v[166:169], v[182:185], v[88:91]
	v_mfma_f32_16x16x32_bf16 v[182:185], v[140:143], v[190:193], v[84:87]
	v_mfma_f32_16x16x32_bf16 v[186:189], v[166:169], v[198:201], v[72:75]
	s_barrier
	s_nop 0
	ds_read_b128 v[72:75], v162 offset:16384
	ds_read_b128 v[84:87], v162 offset:17408
	ds_read_b128 v[88:91], v161 offset:16384
	ds_read_b128 v[92:95], v161 offset:17408
	ds_read_b128 v[190:193], v160 offset:16384
	ds_read_b128 v[194:197], v160 offset:17408
	ds_read_b128 v[198:201], v159 offset:16384
	ds_read_b128 v[202:205], v159 offset:17408
	s_waitcnt vmcnt(4)
	s_barrier
; #define STAGE(P, BASE, br, kt) STAGET(tid_, P, BASE, br, kt)
; #define LDA(dst, b, h) UFOR(m, 4) UFOR(k, 2) \
;     dst[m][k] = *reinterpret_cast<const bf16x8*>((char*)SA(b, h) + lds_byte(wr * 64 + m * 16 + fr, k * 32 + fq * 8))
; #define LDB(dst, b, h) UFOR(n, 2) UFOR(k, 2) \
;     dst[n][k] = *reinterpret_cast<const bf16x8*>((char*)SB(b, h) + lds_byte(wc * 32 + n * 16 + fr, k * 32 + fq * 8))
; #define MMA(ai, bj, At, Bq) do { __builtin_amdgcn_s_setprio(1); \
;     UFOR(m, 4) UFOR(n, 2) UFOR(k, 2) \
;       acc[ai][bj][m][n] = __builtin_amdgcn_mfma_f32_16x16x32_bf16(Bq[n][k], At[m][k], acc[ai][bj][m][n], 0, 0, 0); \
;     __builtin_amdgcn_s_setprio(0); } while (0)
; #define WAIT_V(n) asm volatile("s_waitcnt vmcnt(" #n ")" ::: "memory")
; #define WAIT_L(n) asm volatile("s_waitcnt lgkmcnt(" #n ")" ::: "memory")
; #define BAR __builtin_amdgcn_s_barrier()
; template <int EPI, int K, int KL> ...
;     ...
;   { LDB(B0, 0, 0); LDA(At, 0, 0); STAGE(SA(1, 1), A, brow + HALF, nt - 1);
;     BAR; WAIT_L(0); MMA(0, 0, At, B0); BAR;
;     LDB(B1, 0, 1); BAR; WAIT_L(0); MMA(0, 1, At, B1); BAR;
;     LDA(At, 0, 1); WAIT_V(4); BAR; WAIT_L(0); MMA(1, 0, At, B0); MMA(1, 1, At, B1); BAR; }
;   { LDB(B0, 1, 0); LDA(At, 1, 0); WAIT_V(2); BAR; WAIT_L(0); MMA(0, 0, At, B0); BAR;
;     LDB(B1, 1, 1); WAIT_V(0); BAR; WAIT_L(0); MMA(0, 1, At, B1); BAR;
;     LDA(At, 1, 1); BAR; WAIT_L(0); MMA(1, 0, At, B0); MMA(1, 1, At, B1); BAR; }
	s_waitcnt lgkmcnt(0)
	s_waitcnt lgkmcnt(0)
	v_mfma_f32_16x16x32_bf16 v[48:51], v[148:151], v[88:91], v[48:51]
	v_mfma_f32_16x16x32_bf16 v[40:43], v[148:151], v[190:193], v[40:43]
	v_mfma_f32_16x16x32_bf16 v[36:39], v[136:139], v[198:201], v[36:39]
	v_mfma_f32_16x16x32_bf16 v[32:35], v[148:151], v[198:201], v[32:35]
	v_mfma_f32_16x16x32_bf16 v[60:63], v[136:139], v[72:75], v[60:63]
	v_mfma_f32_16x16x32_bf16 v[56:59], v[148:151], v[72:75], v[56:59]
	v_mfma_f32_16x16x32_bf16 v[52:55], v[136:139], v[88:91], v[52:55]
	v_mfma_f32_16x16x32_bf16 v[48:51], v[174:177], v[92:95], v[48:51]
	v_mfma_f32_16x16x32_bf16 v[44:47], v[136:139], v[190:193], v[44:47]
	v_mfma_f32_16x16x32_bf16 v[40:43], v[174:177], v[194:197], v[40:43]
	v_mfma_f32_16x16x32_bf16 v[36:39], v[144:147], v[202:205], v[36:39]
	v_mfma_f32_16x16x32_bf16 v[32:35], v[174:177], v[202:205], v[32:35]
	v_mfma_f32_16x16x32_bf16 v[208:211], v[144:147], v[84:87], v[60:63]
	v_mfma_f32_16x16x32_bf16 v[218:221], v[174:177], v[84:87], v[56:59]
	v_mfma_f32_16x16x32_bf16 v[222:225], v[144:147], v[92:95], v[52:55]
	v_mfma_f32_16x16x32_bf16 v[226:229], v[144:147], v[194:197], v[44:47]
	v_mfma_f32_16x16x32_bf16 v[0:3], v[170:173], v[198:201], v[0:3]
	v_mfma_f32_16x16x32_bf16 v[28:31], v[128:131], v[72:75], v[28:31]
	v_mfma_f32_16x16x32_bf16 v[24:27], v[170:173], v[72:75], v[24:27]
	v_mfma_f32_16x16x32_bf16 v[20:23], v[128:131], v[88:91], v[20:23]
	v_mfma_f32_16x16x32_bf16 v[16:19], v[170:173], v[88:91], v[16:19]
	v_mfma_f32_16x16x32_bf16 v[12:15], v[128:131], v[190:193], v[12:15]
	v_mfma_f32_16x16x32_bf16 v[8:11], v[170:173], v[190:193], v[8:11]
	v_mfma_f32_16x16x32_bf16 v[4:7], v[128:131], v[198:201], v[4:7]
	v_mfma_f32_16x16x32_bf16 v[0:3], v[166:169], v[202:205], v[0:3]
	v_mfma_f32_16x16x32_bf16 v[136:139], v[140:143], v[84:87], v[28:31]
	v_mfma_f32_16x16x32_bf16 v[144:147], v[166:169], v[84:87], v[24:27]
	v_mfma_f32_16x16x32_bf16 v[148:151], v[140:143], v[92:95], v[20:23]
	v_mfma_f32_16x16x32_bf16 v[174:177], v[166:169], v[92:95], v[16:19]
	v_mfma_f32_16x16x32_bf16 v[230:233], v[140:143], v[194:197], v[12:15]
	v_mfma_f32_16x16x32_bf16 v[190:193], v[166:169], v[194:197], v[8:11]
	v_mfma_f32_16x16x32_bf16 v[140:143], v[140:143], v[202:205], v[4:7]
	s_barrier
	s_nop 0
	ds_read_b128 v[4:7], v165
	ds_read_b128 v[8:11], v165 offset:1024
	ds_read_b128 v[16:19], v165 offset:2048
	ds_read_b128 v[164:167], v165 offset:3072
	ds_read_b128 v[12:15], v162 offset:32768
	ds_read_b128 v[20:23], v162 offset:33792
	ds_read_b128 v[24:27], v161 offset:32768
	ds_read_b128 v[44:47], v161 offset:33792
	ds_read_b128 v[168:171], v160 offset:32768
	ds_read_b128 v[194:197], v160 offset:33792
	ds_read_b128 v[198:201], v159 offset:32768
	ds_read_b128 v[202:205], v159 offset:33792
	s_waitcnt vmcnt(2)
	s_barrier
	s_waitcnt lgkmcnt(0)
	s_waitcnt lgkmcnt(0)
	v_mfma_f32_16x16x32_bf16 v[28:31], v[4:7], v[12:15], v[124:127]
	v_mfma_f32_16x16x32_bf16 v[128:131], v[8:11], v[20:23], v[28:31]
	v_mfma_f32_16x16x32_bf16 v[28:31], v[16:19], v[12:15], v[120:123]
	v_mfma_f32_16x16x32_bf16 v[92:95], v[164:167], v[20:23], v[28:31]
	v_mfma_f32_16x16x32_bf16 v[28:31], v[4:7], v[24:27], v[116:119]
	v_mfma_f32_16x16x32_bf16 v[120:123], v[8:11], v[44:47], v[28:31]
	v_mfma_f32_16x16x32_bf16 v[28:31], v[16:19], v[24:27], v[112:115]
	v_mfma_f32_16x16x32_bf16 v[88:91], v[164:167], v[44:47], v[28:31]
	v_mfma_f32_16x16x32_bf16 v[28:31], v[4:7], v[168:171], v[108:111]
	v_mfma_f32_16x16x32_bf16 v[116:119], v[8:11], v[194:197], v[28:31]
	v_mfma_f32_16x16x32_bf16 v[28:31], v[16:19], v[168:171], v[104:107]
	v_mfma_f32_16x16x32_bf16 v[84:87], v[164:167], v[194:197], v[28:31]
	v_mfma_f32_16x16x32_bf16 v[28:31], v[4:7], v[198:201], v[100:103]
	v_mfma_f32_16x16x32_bf16 v[108:111], v[8:11], v[202:205], v[28:31]
	v_mfma_f32_16x16x32_bf16 v[28:31], v[16:19], v[198:201], v[96:99]
	v_mfma_f32_16x16x32_bf16 v[72:75], v[164:167], v[202:205], v[28:31]
	s_barrier
	ds_read_b128 v[124:127], v163
	ds_read_b128 v[234:237], v163 offset:1024
	ds_read_b128 v[238:241], v163 offset:2048
	ds_read_b128 v[242:245], v163 offset:3072
	s_waitcnt vmcnt(0)
	s_barrier
; #define LDA(dst, b, h) UFOR(m, 4) UFOR(k, 2) \
;     dst[m][k] = *reinterpret_cast<const bf16x8*>((char*)SA(b, h) + lds_byte(wr * 64 + m * 16 + fr, k * 32 + fq * 8))
; #define LDB(dst, b, h) UFOR(n, 2) UFOR(k, 2) \
;     dst[n][k] = *reinterpret_cast<const bf16x8*>((char*)SB(b, h) + lds_byte(wc * 32 + n * 16 + fr, k * 32 + fq * 8))
; #define MMA(ai, bj, At, Bq) do { __builtin_amdgcn_s_setprio(1); \
;     UFOR(m, 4) UFOR(n, 2) UFOR(k, 2) \
;       acc[ai][bj][m][n] = __builtin_amdgcn_mfma_f32_16x16x32_bf16(Bq[n][k], At[m][k], acc[ai][bj][m][n], 0, 0, 0); \
;     __builtin_amdgcn_s_setprio(0); } while (0)
; #define WAIT_V(n) asm volatile("s_waitcnt vmcnt(" #n ")" ::: "memory")
; #define WAIT_L(n) asm volatile("s_waitcnt lgkmcnt(" #n ")" ::: "memory")
; #define BAR __builtin_amdgcn_s_barrier()
; template <int EPI, int K, int KL> ...
;     ...
;   { LDB(B0, 1, 0); LDA(At, 1, 0); WAIT_V(2); BAR; WAIT_L(0); MMA(0, 0, At, B0); BAR;
;     LDB(B1, 1, 1); WAIT_V(0); BAR; WAIT_L(0); MMA(0, 1, At, B1); BAR;
;     LDA(At, 1, 1); BAR; WAIT_L(0); MMA(1, 0, At, B0); MMA(1, 1, At, B1); BAR; }
;   if (wr == 0) BAR;
;   if (EPI != EPI_UPG && EPI != EPI_PART && has_next) {
	s_waitcnt lgkmcnt(0)
	s_waitcnt lgkmcnt(0)
	v_mfma_f32_16x16x32_bf16 v[28:31], v[124:127], v[12:15], v[214:217]
	v_mfma_f32_16x16x32_bf16 v[12:15], v[238:241], v[12:15], v[178:181]
	v_mfma_f32_16x16x32_bf16 v[60:63], v[234:237], v[20:23], v[28:31]
	v_mfma_f32_16x16x32_bf16 v[28:31], v[242:245], v[20:23], v[12:15]
	v_mfma_f32_16x16x32_bf16 v[12:15], v[124:127], v[24:27], v[182:185]
	v_mfma_f32_16x16x32_bf16 v[56:59], v[234:237], v[44:47], v[12:15]
	v_mfma_f32_16x16x32_bf16 v[12:15], v[238:241], v[24:27], v[80:83]
	v_mfma_f32_16x16x32_bf16 v[24:27], v[242:245], v[44:47], v[12:15]
	v_mfma_f32_16x16x32_bf16 v[12:15], v[124:127], v[168:171], v[76:79]
	v_mfma_f32_16x16x32_bf16 v[52:55], v[234:237], v[194:197], v[12:15]
	v_mfma_f32_16x16x32_bf16 v[12:15], v[238:241], v[168:171], v[186:189]
	v_mfma_f32_16x16x32_bf16 v[20:23], v[242:245], v[194:197], v[12:15]
	v_mfma_f32_16x16x32_bf16 v[12:15], v[124:127], v[198:201], v[68:71]
	v_mfma_f32_16x16x32_bf16 v[44:47], v[234:237], v[202:205], v[12:15]
	v_mfma_f32_16x16x32_bf16 v[12:15], v[238:241], v[198:201], v[64:67]
	v_mfma_f32_16x16x32_bf16 v[12:15], v[242:245], v[202:205], v[12:15]
	s_barrier
	ds_read_b128 v[168:171], v162 offset:49152
	ds_read_b128 v[178:181], v162 offset:50176
	ds_read_b128 v[182:185], v161 offset:49152
	ds_read_b128 v[186:189], v161 offset:50176
	ds_read_b128 v[194:197], v160 offset:49152
	ds_read_b128 v[160:163], v160 offset:50176
	ds_read_b128 v[198:201], v159 offset:49152
	ds_read_b128 v[156:159], v159 offset:50176
	s_barrier
	s_waitcnt lgkmcnt(0)
	s_waitcnt lgkmcnt(0)
	v_mfma_f32_16x16x32_bf16 v[64:67], v[4:7], v[168:171], v[208:211]
	v_mfma_f32_16x16x32_bf16 v[112:115], v[8:11], v[178:181], v[64:67]
	v_mfma_f32_16x16x32_bf16 v[64:67], v[16:19], v[168:171], v[218:221]
	v_mfma_f32_16x16x32_bf16 v[48:51], v[16:19], v[182:185], v[48:51]
	v_mfma_f32_16x16x32_bf16 v[80:83], v[164:167], v[178:181], v[64:67]
	v_mfma_f32_16x16x32_bf16 v[64:67], v[4:7], v[182:185], v[222:225]
	v_mfma_f32_16x16x32_bf16 v[76:79], v[164:167], v[186:189], v[48:51]
	v_mfma_f32_16x16x32_bf16 v[48:51], v[4:7], v[194:197], v[226:229]
	v_mfma_f32_16x16x32_bf16 v[4:7], v[4:7], v[198:201], v[36:39]
	v_mfma_f32_16x16x32_bf16 v[40:43], v[16:19], v[194:197], v[40:43]
	v_mfma_f32_16x16x32_bf16 v[96:99], v[8:11], v[156:159], v[4:7]
	v_mfma_f32_16x16x32_bf16 v[4:7], v[16:19], v[198:201], v[32:35]
	v_mfma_f32_16x16x32_bf16 v[104:107], v[8:11], v[186:189], v[64:67]
	v_mfma_f32_16x16x32_bf16 v[100:103], v[8:11], v[160:163], v[48:51]
	v_mfma_f32_16x16x32_bf16 v[68:71], v[164:167], v[160:163], v[40:43]
	v_mfma_f32_16x16x32_bf16 v[64:67], v[164:167], v[156:159], v[4:7]
	v_mfma_f32_16x16x32_bf16 v[4:7], v[124:127], v[168:171], v[136:139]
	v_mfma_f32_16x16x32_bf16 v[48:51], v[234:237], v[178:181], v[4:7]
	v_mfma_f32_16x16x32_bf16 v[4:7], v[238:241], v[168:171], v[144:147]
	v_mfma_f32_16x16x32_bf16 v[16:19], v[242:245], v[178:181], v[4:7]
	v_mfma_f32_16x16x32_bf16 v[4:7], v[124:127], v[182:185], v[148:151]
	v_mfma_f32_16x16x32_bf16 v[40:43], v[234:237], v[186:189], v[4:7]
	v_mfma_f32_16x16x32_bf16 v[4:7], v[238:241], v[182:185], v[174:177]
	v_mfma_f32_16x16x32_bf16 v[8:11], v[242:245], v[186:189], v[4:7]
	v_mfma_f32_16x16x32_bf16 v[4:7], v[124:127], v[194:197], v[230:233]
	v_mfma_f32_16x16x32_bf16 v[36:39], v[234:237], v[160:163], v[4:7]
	v_mfma_f32_16x16x32_bf16 v[4:7], v[238:241], v[194:197], v[190:193]
	v_mfma_f32_16x16x32_bf16 v[32:35], v[124:127], v[198:201], v[140:143]
	v_mfma_f32_16x16x32_bf16 v[0:3], v[238:241], v[198:201], v[0:3]
	v_mfma_f32_16x16x32_bf16 v[4:7], v[242:245], v[160:163], v[4:7]
	v_mfma_f32_16x16x32_bf16 v[32:35], v[234:237], v[156:159], v[32:35]
	v_mfma_f32_16x16x32_bf16 v[0:3], v[242:245], v[156:159], v[0:3]
	s_movk_i32 s19, 0x100
	v_cmp_gt_u32_e32 vcc, s19, v154
	s_barrier
	s_and_saveexec_b64 s[52:53], vcc
	s_cbranch_execnz .LBB0_1189
	s_or_b64 exec, exec, s[52:53]
	s_andn2_b64 vcc, exec, s[50:51]
	s_cbranch_vccz .LBB0_1190

; #define STAGE(P, BASE, br, kt) STAGET(tid_, P, BASE, br, kt)
; #define WAIT_V(n) asm volatile("s_waitcnt vmcnt(" #n ")" ::: "memory")
; #define BAR __builtin_amdgcn_s_barrier()
; template <int EPI, int K, int KL> ...
;     ...
;   const int wid = tid_ >> 6, lane = tid_ & 63, wr = wid >> 2, wc = wid & 3, fr = lane & 15, fq = lane >> 4;
;   f32x4 acc[2][2][4][2] = {};
;   bf16x8 At[4][2], B0[2][2], B1[2][2];
;   const int nt = KL / BK;
;   if (own_prologue) {
;     STAGE(SB(0, 0), Bt, bcol, 0); STAGE(SA(0, 0), A, brow, 0);
;     STAGE(SB(0, 1), Bt, bcol + HALF, 0); STAGE(SA(0, 1), A, brow + HALF, 0);
;   }
;   if (wr == 1) BAR;
;   WAIT_V(4); BAR;
;   STAGE(SB(1, 0), Bt, bcol, 1); STAGE(SA(1, 0), A, brow, 1); STAGE(SB(1, 1), Bt, bcol + HALF, 1);
;   WAIT_V(6); BAR;
; __device__ __forceinline__ void gemm_ctx_splitk_down(const u16* A, const u16* Bt, float* P2, const EpiArgs& e0) {
;     ...
;   for (int u = bid_; u < 16 * P2_PARTS; u += gridDim.x) {
;     const int tile = u / P2_PARTS, part = u % P2_PARTS, pm = 128 + (tile >> 3), pn = tile & 7;
;     EpiArgs e = e0; e.part = P2 + (size_t)part * 512 * DM;
;     const long koff = (long)part * (DFF / P2_PARTS);
;     gemm_tile<EPI_PART, DFF, DFF / P2_PARTS>(A + koff, Bt + koff, (long)pm * BM, pn * BM, pn, 0, 0, e, true, false, 0, 0);
.LBB0_1203:
	s_or_b64 exec, exec, s[50:51]
	s_movk_i32 s50, 0x2c00
	v_mad_i64_i32 v[142:143], s[18:19], v13, s50, 0
	v_mad_i64_i32 v[140:141], s[18:19], v15, s50, 0
	v_readlane_b32 s50, v254, 45
	s_mov_b64 s[56:57], 0x80
	v_lshl_add_u64 v[4:5], v[4:5], 0, s[56:57]
	v_add_u32_e32 v168, s50, v12
	v_add_u32_e32 v169, 0x2000, v168
	v_readfirstlane_b32 s18, v168
	s_mov_b32 m0, s18
	v_readfirstlane_b32 s18, v169
	v_add_u32_e32 v170, 0x8000, v161
	s_waitcnt vmcnt(4)
	s_barrier
	global_load_lds_dwordx4 v[4:5], off
	v_lshl_add_u64 v[4:5], v[6:7], 0, s[56:57]
	s_mov_b32 m0, s18
	v_readfirstlane_b32 s18, v170
	v_add_u32_e32 v171, 0xa000, v161
	global_load_lds_dwordx4 v[4:5], off
	v_lshl_add_u64 v[4:5], v[8:9], 0, s[56:57]
	s_mov_b32 m0, s18
	v_readfirstlane_b32 s18, v171
	global_load_lds_dwordx4 v[4:5], off
	s_mov_b32 m0, s18
	s_add_u32 s18, s48, 0x160080
	s_addc_u32 s19, s49, 0
	v_readlane_b32 s49, v254, 46
	v_lshl_add_u64 v[4:5], v[10:11], 0, s[56:57]
	global_load_lds_dwordx4 v[4:5], off
	v_add_u32_e32 v172, s49, v12
	v_lshl_add_u64 v[4:5], s[18:19], 0, v[142:143]
	v_readfirstlane_b32 s48, v172
	v_lshl_add_u64 v[4:5], v[4:5], 0, v[0:1]
	s_mov_b32 m0, s48
	v_add_u32_e32 v174, 0x2000, v172
	global_load_lds_dwordx4 v[4:5], off
	v_lshl_add_u64 v[4:5], s[18:19], 0, v[140:141]
	v_readfirstlane_b32 s18, v174
	v_lshl_add_u64 v[4:5], v[4:5], 0, v[2:3]
	s_mov_b32 m0, s18
	v_and_b32_e32 v251, 15, v132
	global_load_lds_dwordx4 v[4:5], off
	v_bfe_u32 v252, v132, 4, 2
	v_lshlrev_b32_e32 v7, 2, v132
	v_lshlrev_b32_e32 v4, 4, v252
	v_lshlrev_b32_e32 v5, 6, v251
	v_and_b32_e32 v7, 32, v7
	v_bitop3_b32 v5, v4, v7, v5 bitop3:0x36
	v_readlane_b32 s18, v254, 43
	v_add_u32_e32 v10, s50, v5
	v_add_u32_e32 v11, s49, v5
	v_add_u32_e32 v8, s18, v5
	v_readlane_b32 s18, v254, 44
	v_add_u32_e32 v13, 0, v5
	s_and_b32 s15, s15, 7
	v_add_u32_e32 v9, s18, v5
	v_lshlrev_b32_e32 v5, 6, v132
	s_movk_i32 s18, 0x3c0
	v_and_or_b32 v4, v5, s18, v4
	v_mov_b32_e32 v17, 0x2c0000
	v_xad_u32 v7, v4, v7, 0
	v_mad_u64_u32 v[4:5], s[18:19], s15, v17, v[142:143]
	v_lshl_add_u64 v[4:5], v[4:5], 0, v[0:1]
	v_lshl_add_u64 v[144:145], s[92:93], 0, v[4:5]
	v_mad_u64_u32 v[4:5], s[18:19], s15, v17, v[140:141]
	v_lshl_add_u64 v[4:5], v[4:5], 0, v[2:3]
	v_lshl_add_u64 v[146:147], s[92:93], 0, v[4:5]
	v_mad_i64_i32 v[4:5], s[18:19], s14, v17, v[142:143]
	v_lshl_add_u64 v[0:1], v[4:5], 0, v[0:1]
	v_lshl_add_u64 v[148:149], s[92:93], 0, v[0:1]
	v_mad_i64_i32 v[0:1], s[14:15], s14, v17, v[140:141]
	v_bfe_u32 v206, v132, 6, 2
	s_waitcnt vmcnt(6)
	v_lshlrev_b32_e32 v12, 13, v14
	v_lshl_add_u64 v[0:1], v[0:1], 0, v[2:3]
	v_lshlrev_b32_e32 v6, 12, v206
	v_lshlrev_b32_e32 v134, 6, v14
	v_or_b32_e32 v14, 0x800, v12
	v_or_b32_e32 v15, 0x1000, v12
	v_or_b32_e32 v16, 0x1800, v12
	v_lshl_add_u64 v[150:151], s[92:93], 0, v[0:1]
	v_mov_b32_e32 v0, 0
	s_mov_b32 s14, -2
	v_add_u32_e32 v175, v8, v6
	v_add_u32_e32 v160, v13, v12
	v_add_u32_e32 v159, v7, v14
	v_add_u32_e32 v158, v7, v15
	v_add_u32_e32 v157, v7, v16
	v_add_u32_e32 v173, v9, v6
	v_add_u32_e32 v166, v10, v6
	v_add_u32_e32 v163, v11, v6
	v_mov_b32_e32 v1, v0
	v_mov_b32_e32 v2, v0
	v_mov_b32_e32 v3, v0
	v_mov_b32_e32 v4, v0
	v_mov_b32_e32 v5, v0
	v_mov_b32_e32 v6, v0
	v_mov_b32_e32 v7, v0
	v_mov_b32_e32 v8, v0
	v_mov_b32_e32 v9, v0
	v_mov_b32_e32 v10, v0
	v_mov_b32_e32 v11, v0
	v_mov_b32_e32 v12, v0
	v_mov_b32_e32 v13, v0
	v_mov_b32_e32 v14, v0
	v_mov_b32_e32 v15, v0
	v_mov_b32_e32 v16, v0
	v_mov_b32_e32 v17, v0
	v_mov_b32_e32 v18, v0
	v_mov_b32_e32 v19, v0
	v_mov_b32_e32 v20, v0
	v_mov_b32_e32 v21, v0
	v_mov_b32_e32 v22, v0
	v_mov_b32_e32 v23, v0
	s_waitcnt vmcnt(0)
	v_mov_b32_e32 v24, v0
	v_mov_b32_e32 v25, v0
	v_mov_b32_e32 v26, v0
	v_mov_b32_e32 v27, v0
	v_mov_b32_e32 v28, v0
	v_mov_b32_e32 v29, v0
	v_mov_b32_e32 v30, v0
	v_mov_b32_e32 v31, v0
	v_mov_b32_e32 v32, v0
	v_mov_b32_e32 v33, v0
	v_mov_b32_e32 v34, v0
	v_mov_b32_e32 v35, v0
	v_mov_b32_e32 v36, v0
	v_mov_b32_e32 v37, v0
	v_mov_b32_e32 v38, v0
	v_mov_b32_e32 v39, v0
	v_mov_b32_e32 v40, v0
	v_mov_b32_e32 v41, v0
	v_mov_b32_e32 v42, v0
	v_mov_b32_e32 v43, v0
	v_mov_b32_e32 v44, v0
	v_mov_b32_e32 v45, v0
	v_mov_b32_e32 v46, v0
	v_mov_b32_e32 v47, v0
	v_mov_b32_e32 v48, v0
	v_mov_b32_e32 v49, v0
	v_mov_b32_e32 v50, v0
	v_mov_b32_e32 v51, v0
	v_mov_b32_e32 v52, v0
	v_mov_b32_e32 v53, v0
	v_mov_b32_e32 v54, v0
	v_mov_b32_e32 v55, v0
	v_mov_b32_e32 v56, v0
	v_mov_b32_e32 v57, v0
	v_mov_b32_e32 v58, v0
	v_mov_b32_e32 v59, v0
	v_mov_b32_e32 v60, v0
	v_mov_b32_e32 v61, v0
	v_mov_b32_e32 v62, v0
	v_mov_b32_e32 v63, v0
	v_mov_b32_e32 v64, v0
	v_mov_b32_e32 v65, v0
	v_mov_b32_e32 v66, v0
	v_mov_b32_e32 v67, v0
	v_mov_b32_e32 v68, v0
	v_mov_b32_e32 v69, v0
	v_mov_b32_e32 v70, v0
	v_mov_b32_e32 v71, v0
	v_mov_b32_e32 v72, v0
	v_mov_b32_e32 v73, v0
	v_mov_b32_e32 v74, v0
	v_mov_b32_e32 v75, v0
	v_mov_b32_e32 v76, v0
	v_mov_b32_e32 v77, v0
	v_mov_b32_e32 v78, v0
	v_mov_b32_e32 v79, v0
	v_mov_b32_e32 v80, v0
	v_mov_b32_e32 v81, v0
	v_mov_b32_e32 v82, v0
	v_mov_b32_e32 v83, v0
	v_mov_b32_e32 v84, v0
	v_mov_b32_e32 v85, v0
	v_mov_b32_e32 v86, v0
	v_mov_b32_e32 v87, v0
	v_mov_b32_e32 v88, v0
	v_mov_b32_e32 v89, v0
	v_mov_b32_e32 v90, v0
	v_mov_b32_e32 v91, v0
	v_mov_b32_e32 v92, v0
	v_mov_b32_e32 v93, v0
	v_mov_b32_e32 v94, v0
	v_mov_b32_e32 v95, v0
	v_mov_b32_e32 v96, v0
	v_mov_b32_e32 v97, v0
	v_mov_b32_e32 v98, v0
	v_mov_b32_e32 v99, v0
	v_mov_b32_e32 v100, v0
	v_mov_b32_e32 v101, v0
	v_mov_b32_e32 v102, v0
	v_mov_b32_e32 v103, v0
	v_mov_b32_e32 v104, v0
	v_mov_b32_e32 v105, v0
	v_mov_b32_e32 v106, v0
	v_mov_b32_e32 v107, v0
	v_mov_b32_e32 v108, v0
	v_mov_b32_e32 v109, v0
	v_mov_b32_e32 v110, v0
	v_mov_b32_e32 v111, v0
	v_mov_b32_e32 v112, v0
	v_mov_b32_e32 v113, v0
	v_mov_b32_e32 v114, v0
	v_mov_b32_e32 v115, v0
	v_mov_b32_e32 v116, v0
	v_mov_b32_e32 v117, v0
	v_mov_b32_e32 v118, v0
	v_mov_b32_e32 v119, v0
	v_mov_b32_e32 v120, v0
	v_mov_b32_e32 v121, v0
	v_mov_b32_e32 v122, v0
	v_mov_b32_e32 v123, v0
	v_mov_b32_e32 v124, v0
	v_mov_b32_e32 v125, v0
	v_mov_b32_e32 v126, v0
	v_mov_b32_e32 v127, v0
; #define STAGE(P, BASE, br, kt) STAGET(tid_, P, BASE, br, kt)
; #define LDA(dst, b, h) UFOR(m, 4) UFOR(k, 2) \
;     dst[m][k] = *reinterpret_cast<const bf16x8*>((char*)SA(b, h) + lds_byte(wr * 64 + m * 16 + fr, k * 32 + fq * 8))
; #define LDB(dst, b, h) UFOR(n, 2) UFOR(k, 2) \
;     dst[n][k] = *reinterpret_cast<const bf16x8*>((char*)SB(b, h) + lds_byte(wc * 32 + n * 16 + fr, k * 32 + fq * 8))
; #define MMA(ai, bj, At, Bq) do { __builtin_amdgcn_s_setprio(1); \
;     UFOR(m, 4) UFOR(n, 2) UFOR(k, 2) \
;       acc[ai][bj][m][n] = __builtin_amdgcn_mfma_f32_16x16x32_bf16(Bq[n][k], At[m][k], acc[ai][bj][m][n], 0, 0, 0); \
;     __builtin_amdgcn_s_setprio(0); } while (0)
; #define WAIT_V(n) asm volatile("s_waitcnt vmcnt(" #n ")" ::: "memory")
; #define WAIT_L(n) asm volatile("s_waitcnt lgkmcnt(" #n ")" ::: "memory")
; #define BAR __builtin_amdgcn_s_barrier()
; #define SCHED __builtin_amdgcn_sched_barrier(0)
; template <int EPI, int K, int KL> ...
;     ...
;   for (int t = 0; t < nt - 2; t += 2) {
;     LDB(B0, 0, 0); SCHED; LDA(At, 0, 0); STAGE(SA(1, 1), A, brow + HALF, t + 1);
;     WAIT_L(8); BAR; WAIT_L(0); MMA(0, 0, At, B0); BAR; SCHED;
;     LDB(B1, 0, 1); STAGE(SB(0, 0), Bt, bcol, t + 2);
;     BAR; WAIT_L(0); MMA(0, 1, At, B1); BAR;
;     LDA(At, 0, 1); STAGE(SA(0, 0), A, brow, t + 2);
;     BAR; WAIT_L(0); MMA(1, 0, At, B0); BAR; SCHED;
;     STAGE(SB(0, 1), Bt, bcol + HALF, t + 2);
;     WAIT_V(6); BAR; MMA(1, 1, At, B1); BAR;
;     LDB(B0, 1, 0); SCHED; LDA(At, 1, 0); STAGE(SA(0, 1), A, brow + HALF, t + 2);
;     WAIT_L(8); BAR; WAIT_L(0); MMA(0, 0, At, B0); BAR; SCHED;
.Lkrot_1204:
	s_barrier
.LBB0_1204:
	ds_read_b128 v[136:139], v175
	ds_read_b128 v[178:181], v175 offset:1024
	ds_read_b128 v[182:185], v175 offset:2048
	ds_read_b128 v[186:189], v175 offset:3072
	v_add_u32_e32 v176, 0xc000, v161
	v_lshl_add_u64 v[152:153], v[148:149], 0, s[44:45]
	v_readfirstlane_b32 s15, v176
	v_lshl_add_u64 v[154:155], v[152:153], 0, s[58:59]
	s_mov_b32 m0, s15
	v_add_u32_e32 v177, 0xe000, v161
	ds_read_b128 v[190:193], v160
	ds_read_b128 v[194:197], v160 offset:1024
	ds_read_b128 v[198:201], v159
	ds_read_b128 v[202:205], v159 offset:1024
	ds_read_b128 v[208:211], v158
	ds_read_b128 v[214:217], v158 offset:1024
	ds_read_b128 v[218:221], v157
	ds_read_b128 v[222:225], v157 offset:1024
	global_load_lds_dwordx4 v[154:155], off
	v_lshl_add_u64 v[154:155], v[150:151], 0, s[44:45]
	v_readfirstlane_b32 s15, v177
	v_lshl_add_u64 v[226:227], v[154:155], 0, s[58:59]
	s_mov_b32 m0, s15
	s_nop 0
	global_load_lds_dwordx4 v[226:227], off
	s_waitcnt lgkmcnt(8)
	s_barrier
	s_waitcnt lgkmcnt(0)
	s_waitcnt lgkmcnt(0)
	v_mfma_f32_16x16x32_bf16 v[124:127], v[136:139], v[190:193], v[124:127]
	v_mfma_f32_16x16x32_bf16 v[120:123], v[182:185], v[190:193], v[120:123]
	v_mfma_f32_16x16x32_bf16 v[116:119], v[136:139], v[198:201], v[116:119]
	v_mfma_f32_16x16x32_bf16 v[112:115], v[182:185], v[198:201], v[112:115]
	v_mfma_f32_16x16x32_bf16 v[108:111], v[136:139], v[208:211], v[108:111]
	v_mfma_f32_16x16x32_bf16 v[104:107], v[182:185], v[208:211], v[104:107]
	v_mfma_f32_16x16x32_bf16 v[100:103], v[136:139], v[218:221], v[100:103]
	v_mfma_f32_16x16x32_bf16 v[96:99], v[182:185], v[218:221], v[96:99]
	v_mfma_f32_16x16x32_bf16 v[124:127], v[178:181], v[194:197], v[124:127]
	v_mfma_f32_16x16x32_bf16 v[120:123], v[186:189], v[194:197], v[120:123]
	v_mfma_f32_16x16x32_bf16 v[116:119], v[178:181], v[202:205], v[116:119]
	v_mfma_f32_16x16x32_bf16 v[112:115], v[186:189], v[202:205], v[112:115]
	v_mfma_f32_16x16x32_bf16 v[108:111], v[178:181], v[214:217], v[108:111]
	v_mfma_f32_16x16x32_bf16 v[104:107], v[186:189], v[214:217], v[104:107]
	v_mfma_f32_16x16x32_bf16 v[100:103], v[178:181], v[222:225], v[100:103]
	v_mfma_f32_16x16x32_bf16 v[96:99], v[186:189], v[222:225], v[96:99]
	s_barrier
	v_lshl_add_u64 v[242:243], v[144:145], 0, s[44:45]
	v_readfirstlane_b32 s15, v156
	v_lshl_add_u64 v[244:245], v[242:243], 0, s[22:23]
	s_mov_b32 m0, s15
	v_add_u32_e32 v248, 0x2000, v156
	ds_read_b128 v[226:229], v173
	ds_read_b128 v[230:233], v173 offset:1024
	ds_read_b128 v[234:237], v173 offset:2048
	ds_read_b128 v[238:241], v173 offset:3072
	global_load_lds_dwordx4 v[244:245], off
	v_lshl_add_u64 v[244:245], v[146:147], 0, s[44:45]
	v_readfirstlane_b32 s15, v248
	v_lshl_add_u64 v[246:247], v[244:245], 0, s[22:23]
	s_mov_b32 m0, s15
	s_nop 0
	global_load_lds_dwordx4 v[246:247], off
	s_barrier
	s_waitcnt lgkmcnt(0)
	s_waitcnt lgkmcnt(0)
	v_mfma_f32_16x16x32_bf16 v[92:95], v[226:229], v[190:193], v[92:95]
	v_mfma_f32_16x16x32_bf16 v[88:91], v[234:237], v[190:193], v[88:91]
	v_mfma_f32_16x16x32_bf16 v[84:87], v[226:229], v[198:201], v[84:87]
	v_mfma_f32_16x16x32_bf16 v[80:83], v[234:237], v[198:201], v[80:83]
	v_mfma_f32_16x16x32_bf16 v[76:79], v[226:229], v[208:211], v[76:79]
	v_mfma_f32_16x16x32_bf16 v[72:75], v[234:237], v[208:211], v[72:75]
	v_mfma_f32_16x16x32_bf16 v[68:71], v[226:229], v[218:221], v[68:71]
	v_mfma_f32_16x16x32_bf16 v[64:67], v[234:237], v[218:221], v[64:67]
	v_mfma_f32_16x16x32_bf16 v[92:95], v[230:233], v[194:197], v[92:95]
	v_mfma_f32_16x16x32_bf16 v[88:91], v[238:241], v[194:197], v[88:91]
	v_mfma_f32_16x16x32_bf16 v[84:87], v[230:233], v[202:205], v[84:87]
	v_mfma_f32_16x16x32_bf16 v[80:83], v[238:241], v[202:205], v[80:83]
	v_mfma_f32_16x16x32_bf16 v[76:79], v[230:233], v[214:217], v[76:79]
	v_mfma_f32_16x16x32_bf16 v[72:75], v[238:241], v[214:217], v[72:75]
	v_mfma_f32_16x16x32_bf16 v[68:71], v[230:233], v[222:225], v[68:71]
	v_mfma_f32_16x16x32_bf16 v[64:67], v[238:241], v[222:225], v[64:67]
	v_readfirstlane_b32 s15, v161
	v_lshl_add_u64 v[246:247], v[152:153], 0, s[60:61]
	s_mov_b32 m0, s15
	v_readfirstlane_b32 s15, v162
	s_barrier
	ds_read_b128 v[190:193], v160 offset:16384
	ds_read_b128 v[194:197], v160 offset:17408
	ds_read_b128 v[198:201], v159 offset:16384
	ds_read_b128 v[202:205], v159 offset:17408
	ds_read_b128 v[208:211], v158 offset:16384
	ds_read_b128 v[214:217], v158 offset:17408
	ds_read_b128 v[218:221], v157 offset:16384
	ds_read_b128 v[222:225], v157 offset:17408
	global_load_lds_dwordx4 v[246:247], off
	v_lshl_add_u64 v[246:247], v[154:155], 0, s[60:61]
	s_mov_b32 m0, s15
	s_nop 0
	global_load_lds_dwordx4 v[246:247], off
	s_barrier
	s_waitcnt lgkmcnt(0)
	s_waitcnt lgkmcnt(0)
	v_mfma_f32_16x16x32_bf16 v[60:63], v[136:139], v[190:193], v[60:63]
	v_mfma_f32_16x16x32_bf16 v[56:59], v[182:185], v[190:193], v[56:59]
	v_mfma_f32_16x16x32_bf16 v[52:55], v[136:139], v[198:201], v[52:55]
	v_mfma_f32_16x16x32_bf16 v[48:51], v[182:185], v[198:201], v[48:51]
	v_mfma_f32_16x16x32_bf16 v[44:47], v[136:139], v[208:211], v[44:47]
	v_mfma_f32_16x16x32_bf16 v[40:43], v[182:185], v[208:211], v[40:43]
	v_mfma_f32_16x16x32_bf16 v[36:39], v[136:139], v[218:221], v[36:39]
	v_mfma_f32_16x16x32_bf16 v[32:35], v[182:185], v[218:221], v[32:35]
	v_mfma_f32_16x16x32_bf16 v[60:63], v[178:181], v[194:197], v[60:63]
	v_mfma_f32_16x16x32_bf16 v[56:59], v[186:189], v[194:197], v[56:59]
	v_mfma_f32_16x16x32_bf16 v[52:55], v[178:181], v[202:205], v[52:55]
	v_mfma_f32_16x16x32_bf16 v[48:51], v[186:189], v[202:205], v[48:51]
	v_mfma_f32_16x16x32_bf16 v[44:47], v[178:181], v[214:217], v[44:47]
	v_mfma_f32_16x16x32_bf16 v[40:43], v[186:189], v[214:217], v[40:43]
	v_mfma_f32_16x16x32_bf16 v[36:39], v[178:181], v[222:225], v[36:39]
	v_mfma_f32_16x16x32_bf16 v[32:35], v[186:189], v[222:225], v[32:35]
	s_barrier
; #define STAGE(P, BASE, br, kt) STAGET(tid_, P, BASE, br, kt)
; #define LDA(dst, b, h) UFOR(m, 4) UFOR(k, 2) \
;     dst[m][k] = *reinterpret_cast<const bf16x8*>((char*)SA(b, h) + lds_byte(wr * 64 + m * 16 + fr, k * 32 + fq * 8))
; #define LDB(dst, b, h) UFOR(n, 2) UFOR(k, 2) \
;     dst[n][k] = *reinterpret_cast<const bf16x8*>((char*)SB(b, h) + lds_byte(wc * 32 + n * 16 + fr, k * 32 + fq * 8))
; #define MMA(ai, bj, At, Bq) do { __builtin_amdgcn_s_setprio(1); \
;     UFOR(m, 4) UFOR(n, 2) UFOR(k, 2) \
;       acc[ai][bj][m][n] = __builtin_amdgcn_mfma_f32_16x16x32_bf16(Bq[n][k], At[m][k], acc[ai][bj][m][n], 0, 0, 0); \
;     __builtin_amdgcn_s_setprio(0); } while (0)
; #define WAIT_V(n) asm volatile("s_waitcnt vmcnt(" #n ")" ::: "memory")
; #define WAIT_L(n) asm volatile("s_waitcnt lgkmcnt(" #n ")" ::: "memory")
; #define BAR __builtin_amdgcn_s_barrier()
; #define SCHED __builtin_amdgcn_sched_barrier(0)
; template <int EPI, int K, int KL> ...
;     ...
;     LDA(At, 0, 1); STAGE(SA(0, 0), A, brow, t + 2);
;     BAR; WAIT_L(0); MMA(1, 0, At, B0); BAR; SCHED;
;     STAGE(SB(0, 1), Bt, bcol + HALF, t + 2);
;     WAIT_V(6); BAR; MMA(1, 1, At, B1); BAR;
;     LDB(B0, 1, 0); SCHED; LDA(At, 1, 0); STAGE(SA(0, 1), A, brow + HALF, t + 2);
;     WAIT_L(8); BAR; WAIT_L(0); MMA(0, 0, At, B0); BAR; SCHED;
;     LDB(B1, 1, 1); STAGE(SB(1, 0), Bt, bcol, t + 3);
;     BAR; WAIT_L(0); MMA(0, 1, At, B1); BAR;
;     LDA(At, 1, 1); STAGE(SA(1, 0), A, brow, t + 3);
;     BAR; WAIT_L(0); MMA(1, 0, At, B0); BAR; SCHED;
	v_readfirstlane_b32 s15, v164
	v_add_u32_e32 v138, 0x2000, v164
	v_lshl_add_u64 v[136:137], v[242:243], 0, s[24:25]
	s_mov_b32 m0, s15
	v_readfirstlane_b32 s15, v138
	global_load_lds_dwordx4 v[136:137], off
	v_lshl_add_u64 v[136:137], v[244:245], 0, s[24:25]
	s_mov_b32 m0, s15
	s_nop 0
	global_load_lds_dwordx4 v[136:137], off
	s_waitcnt vmcnt(6)
	s_barrier
	v_mfma_f32_16x16x32_bf16 v[28:31], v[226:229], v[190:193], v[28:31]
	v_mfma_f32_16x16x32_bf16 v[24:27], v[234:237], v[190:193], v[24:27]
	v_mfma_f32_16x16x32_bf16 v[20:23], v[226:229], v[198:201], v[20:23]
	v_mfma_f32_16x16x32_bf16 v[16:19], v[234:237], v[198:201], v[16:19]
	v_mfma_f32_16x16x32_bf16 v[12:15], v[226:229], v[208:211], v[12:15]
	v_mfma_f32_16x16x32_bf16 v[8:11], v[234:237], v[208:211], v[8:11]
	v_mfma_f32_16x16x32_bf16 v[4:7], v[226:229], v[218:221], v[4:7]
	v_mfma_f32_16x16x32_bf16 v[0:3], v[234:237], v[218:221], v[0:3]
	v_mfma_f32_16x16x32_bf16 v[28:31], v[230:233], v[194:197], v[28:31]
	v_mfma_f32_16x16x32_bf16 v[24:27], v[238:241], v[194:197], v[24:27]
	v_mfma_f32_16x16x32_bf16 v[20:23], v[230:233], v[202:205], v[20:23]
	v_mfma_f32_16x16x32_bf16 v[16:19], v[238:241], v[202:205], v[16:19]
	v_mfma_f32_16x16x32_bf16 v[12:15], v[230:233], v[214:217], v[12:15]
	v_mfma_f32_16x16x32_bf16 v[8:11], v[238:241], v[214:217], v[8:11]
	v_mfma_f32_16x16x32_bf16 v[4:7], v[230:233], v[222:225], v[4:7]
	v_mfma_f32_16x16x32_bf16 v[0:3], v[238:241], v[222:225], v[0:3]
	s_barrier
	ds_read_b128 v[136:139], v166
	ds_read_b128 v[178:181], v166 offset:1024
	ds_read_b128 v[182:185], v166 offset:2048
	ds_read_b128 v[186:189], v166 offset:3072
	v_readfirstlane_b32 s15, v165
	v_lshl_add_u64 v[226:227], v[152:153], 0, s[62:63]
	s_mov_b32 m0, s15
	v_readfirstlane_b32 s15, v167
	ds_read_b128 v[190:193], v160 offset:32768
	ds_read_b128 v[194:197], v160 offset:33792
	ds_read_b128 v[198:201], v159 offset:32768
	ds_read_b128 v[202:205], v159 offset:33792
	ds_read_b128 v[208:211], v158 offset:32768
	ds_read_b128 v[214:217], v158 offset:33792
	ds_read_b128 v[218:221], v157 offset:32768
	ds_read_b128 v[222:225], v157 offset:33792
	global_load_lds_dwordx4 v[226:227], off
	v_lshl_add_u64 v[226:227], v[154:155], 0, s[62:63]
	s_mov_b32 m0, s15
	s_nop 0
	global_load_lds_dwordx4 v[226:227], off
	s_waitcnt lgkmcnt(8)
	s_barrier
	s_waitcnt lgkmcnt(0)
	s_waitcnt lgkmcnt(0)
	v_mfma_f32_16x16x32_bf16 v[124:127], v[136:139], v[190:193], v[124:127]
	v_mfma_f32_16x16x32_bf16 v[120:123], v[182:185], v[190:193], v[120:123]
	v_mfma_f32_16x16x32_bf16 v[116:119], v[136:139], v[198:201], v[116:119]
	v_mfma_f32_16x16x32_bf16 v[112:115], v[182:185], v[198:201], v[112:115]
	v_mfma_f32_16x16x32_bf16 v[108:111], v[136:139], v[208:211], v[108:111]
	v_mfma_f32_16x16x32_bf16 v[104:107], v[182:185], v[208:211], v[104:107]
	v_mfma_f32_16x16x32_bf16 v[100:103], v[136:139], v[218:221], v[100:103]
	v_mfma_f32_16x16x32_bf16 v[96:99], v[182:185], v[218:221], v[96:99]
	v_mfma_f32_16x16x32_bf16 v[124:127], v[178:181], v[194:197], v[124:127]
	v_mfma_f32_16x16x32_bf16 v[120:123], v[186:189], v[194:197], v[120:123]
	v_mfma_f32_16x16x32_bf16 v[116:119], v[178:181], v[202:205], v[116:119]
	v_mfma_f32_16x16x32_bf16 v[112:115], v[186:189], v[202:205], v[112:115]
	v_mfma_f32_16x16x32_bf16 v[108:111], v[178:181], v[214:217], v[108:111]
	v_mfma_f32_16x16x32_bf16 v[104:107], v[186:189], v[214:217], v[104:107]
	v_mfma_f32_16x16x32_bf16 v[100:103], v[178:181], v[222:225], v[100:103]
	v_mfma_f32_16x16x32_bf16 v[96:99], v[186:189], v[222:225], v[96:99]
	s_barrier
	v_readfirstlane_b32 s15, v168
	v_lshl_add_u64 v[246:247], v[242:243], 0, s[94:95]
	s_mov_b32 m0, s15
	v_readfirstlane_b32 s15, v169
	ds_read_b128 v[226:229], v163
	ds_read_b128 v[230:233], v163 offset:1024
	ds_read_b128 v[234:237], v163 offset:2048
	ds_read_b128 v[238:241], v163 offset:3072
	global_load_lds_dwordx4 v[246:247], off
	v_lshl_add_u64 v[246:247], v[244:245], 0, s[94:95]
	s_mov_b32 m0, s15
	s_nop 0
	global_load_lds_dwordx4 v[246:247], off
	s_barrier
	s_waitcnt lgkmcnt(0)
	s_waitcnt lgkmcnt(0)
	v_mfma_f32_16x16x32_bf16 v[92:95], v[226:229], v[190:193], v[92:95]
	v_mfma_f32_16x16x32_bf16 v[88:91], v[234:237], v[190:193], v[88:91]
	v_mfma_f32_16x16x32_bf16 v[84:87], v[226:229], v[198:201], v[84:87]
	v_mfma_f32_16x16x32_bf16 v[80:83], v[234:237], v[198:201], v[80:83]
	v_mfma_f32_16x16x32_bf16 v[76:79], v[226:229], v[208:211], v[76:79]
	v_mfma_f32_16x16x32_bf16 v[72:75], v[234:237], v[208:211], v[72:75]
	v_mfma_f32_16x16x32_bf16 v[68:71], v[226:229], v[218:221], v[68:71]
	v_mfma_f32_16x16x32_bf16 v[64:67], v[234:237], v[218:221], v[64:67]
	v_mfma_f32_16x16x32_bf16 v[92:95], v[230:233], v[194:197], v[92:95]
	v_mfma_f32_16x16x32_bf16 v[88:91], v[238:241], v[194:197], v[88:91]
	v_mfma_f32_16x16x32_bf16 v[84:87], v[230:233], v[202:205], v[84:87]
	v_mfma_f32_16x16x32_bf16 v[80:83], v[238:241], v[202:205], v[80:83]
	v_mfma_f32_16x16x32_bf16 v[76:79], v[230:233], v[214:217], v[76:79]
	v_mfma_f32_16x16x32_bf16 v[72:75], v[238:241], v[214:217], v[72:75]
	v_mfma_f32_16x16x32_bf16 v[68:71], v[230:233], v[222:225], v[68:71]
	v_mfma_f32_16x16x32_bf16 v[64:67], v[238:241], v[222:225], v[64:67]
	v_readfirstlane_b32 s15, v170
	v_lshl_add_u64 v[152:153], v[152:153], 0, s[64:65]
	s_mov_b32 m0, s15
	v_readfirstlane_b32 s15, v171
	s_barrier
	ds_read_b128 v[190:193], v160 offset:49152
	ds_read_b128 v[194:197], v160 offset:50176
	ds_read_b128 v[198:201], v159 offset:49152
	ds_read_b128 v[202:205], v159 offset:50176
	ds_read_b128 v[208:211], v158 offset:49152
	ds_read_b128 v[214:217], v158 offset:50176
	ds_read_b128 v[218:221], v157 offset:49152
	ds_read_b128 v[222:225], v157 offset:50176
	global_load_lds_dwordx4 v[152:153], off
	v_lshl_add_u64 v[152:153], v[154:155], 0, s[64:65]
	s_mov_b32 m0, s15
	s_nop 0
	global_load_lds_dwordx4 v[152:153], off
	s_barrier
; #define STAGE(P, BASE, br, kt) STAGET(tid_, P, BASE, br, kt)
; #define LDA(dst, b, h) UFOR(m, 4) UFOR(k, 2) \
;     dst[m][k] = *reinterpret_cast<const bf16x8*>((char*)SA(b, h) + lds_byte(wr * 64 + m * 16 + fr, k * 32 + fq * 8))
; #define LDB(dst, b, h) UFOR(n, 2) UFOR(k, 2) \
;     dst[n][k] = *reinterpret_cast<const bf16x8*>((char*)SB(b, h) + lds_byte(wc * 32 + n * 16 + fr, k * 32 + fq * 8))
; #define MMA(ai, bj, At, Bq) do { __builtin_amdgcn_s_setprio(1); \
;     UFOR(m, 4) UFOR(n, 2) UFOR(k, 2) \
;       acc[ai][bj][m][n] = __builtin_amdgcn_mfma_f32_16x16x32_bf16(Bq[n][k], At[m][k], acc[ai][bj][m][n], 0, 0, 0); \
;     __builtin_amdgcn_s_setprio(0); } while (0)
; #define WAIT_V(n) asm volatile("s_waitcnt vmcnt(" #n ")" ::: "memory")
; #define WAIT_L(n) asm volatile("s_waitcnt lgkmcnt(" #n ")" ::: "memory")
; #define BAR __builtin_amdgcn_s_barrier()
; #define SCHED __builtin_amdgcn_sched_barrier(0)
; template <int EPI, int K, int KL> ...
;     ...
;     BAR; WAIT_L(0); MMA(1, 0, At, B0); BAR; SCHED;
;     STAGE(SB(1, 1), Bt, bcol + HALF, t + 3);
;     WAIT_V(6); BAR; MMA(1, 1, At, B1); BAR;
;   }
;   { LDB(B0, 0, 0); LDA(At, 0, 0); STAGE(SA(1, 1), A, brow + HALF, nt - 1);
;     BAR; WAIT_L(0); MMA(0, 0, At, B0); BAR;
	s_waitcnt lgkmcnt(0)
	s_waitcnt lgkmcnt(0)
	v_mfma_f32_16x16x32_bf16 v[60:63], v[136:139], v[190:193], v[60:63]
	v_mfma_f32_16x16x32_bf16 v[56:59], v[182:185], v[190:193], v[56:59]
	v_mfma_f32_16x16x32_bf16 v[52:55], v[136:139], v[198:201], v[52:55]
	v_mfma_f32_16x16x32_bf16 v[48:51], v[182:185], v[198:201], v[48:51]
	v_mfma_f32_16x16x32_bf16 v[44:47], v[136:139], v[208:211], v[44:47]
	v_mfma_f32_16x16x32_bf16 v[40:43], v[182:185], v[208:211], v[40:43]
	v_mfma_f32_16x16x32_bf16 v[36:39], v[136:139], v[218:221], v[36:39]
	v_mfma_f32_16x16x32_bf16 v[32:35], v[182:185], v[218:221], v[32:35]
	v_mfma_f32_16x16x32_bf16 v[60:63], v[178:181], v[194:197], v[60:63]
	v_mfma_f32_16x16x32_bf16 v[56:59], v[186:189], v[194:197], v[56:59]
	v_mfma_f32_16x16x32_bf16 v[52:55], v[178:181], v[202:205], v[52:55]
	v_mfma_f32_16x16x32_bf16 v[48:51], v[186:189], v[202:205], v[48:51]
	v_mfma_f32_16x16x32_bf16 v[44:47], v[178:181], v[214:217], v[44:47]
	v_mfma_f32_16x16x32_bf16 v[40:43], v[186:189], v[214:217], v[40:43]
	v_mfma_f32_16x16x32_bf16 v[36:39], v[178:181], v[222:225], v[36:39]
	v_mfma_f32_16x16x32_bf16 v[32:35], v[186:189], v[222:225], v[32:35]
	s_barrier
	v_readfirstlane_b32 s15, v172
	v_lshl_add_u64 v[136:137], v[242:243], 0, s[10:11]
	s_mov_b32 m0, s15
	v_readfirstlane_b32 s15, v174
	global_load_lds_dwordx4 v[136:137], off
	v_lshl_add_u64 v[136:137], v[244:245], 0, s[10:11]
	s_mov_b32 m0, s15
	s_nop 0
	global_load_lds_dwordx4 v[136:137], off
	s_waitcnt vmcnt(6)
	s_barrier
	v_mfma_f32_16x16x32_bf16 v[28:31], v[226:229], v[190:193], v[28:31]
	v_mfma_f32_16x16x32_bf16 v[24:27], v[234:237], v[190:193], v[24:27]
	v_mfma_f32_16x16x32_bf16 v[20:23], v[226:229], v[198:201], v[20:23]
	v_mfma_f32_16x16x32_bf16 v[16:19], v[234:237], v[198:201], v[16:19]
	v_mfma_f32_16x16x32_bf16 v[12:15], v[226:229], v[208:211], v[12:15]
	v_mfma_f32_16x16x32_bf16 v[8:11], v[234:237], v[208:211], v[8:11]
	v_mfma_f32_16x16x32_bf16 v[4:7], v[226:229], v[218:221], v[4:7]
	v_mfma_f32_16x16x32_bf16 v[0:3], v[234:237], v[218:221], v[0:3]
	v_mfma_f32_16x16x32_bf16 v[28:31], v[230:233], v[194:197], v[28:31]
	v_mfma_f32_16x16x32_bf16 v[24:27], v[238:241], v[194:197], v[24:27]
	v_mfma_f32_16x16x32_bf16 v[20:23], v[230:233], v[202:205], v[20:23]
	v_mfma_f32_16x16x32_bf16 v[16:19], v[238:241], v[202:205], v[16:19]
	v_mfma_f32_16x16x32_bf16 v[12:15], v[230:233], v[214:217], v[12:15]
	v_mfma_f32_16x16x32_bf16 v[8:11], v[238:241], v[214:217], v[8:11]
	v_mfma_f32_16x16x32_bf16 v[4:7], v[230:233], v[222:225], v[4:7]
	v_mfma_f32_16x16x32_bf16 v[0:3], v[238:241], v[222:225], v[0:3]
	s_add_i32 s14, s14, 2
	v_lshl_add_u64 v[144:145], v[144:145], 0, s[20:21]
	v_lshl_add_u64 v[146:147], v[146:147], 0, s[20:21]
	v_lshl_add_u64 v[148:149], v[148:149], 0, s[20:21]
	s_cmp_lt_u32 s14, 4
	v_lshl_add_u64 v[150:151], v[150:151], 0, s[20:21]
	s_cbranch_scc1 .Lkrot_1204
	s_barrier
	s_add_u32 s14, s46, 0x160380
	s_addc_u32 s15, s47, 0
	v_lshl_add_u64 v[142:143], s[14:15], 0, v[142:143]
	v_readfirstlane_b32 s18, v176
	v_lshl_add_u64 v[128:129], v[128:129], 1, v[142:143]
	s_mov_b32 m0, s18
	ds_read_b128 v[136:139], v175
	ds_read_b128 v[144:147], v175 offset:1024
	ds_read_b128 v[148:151], v175 offset:2048
	ds_read_b128 v[168:171], v175 offset:3072
	ds_read_b128 v[178:181], v160
	ds_read_b128 v[182:185], v160 offset:1024
	ds_read_b128 v[186:189], v159
	ds_read_b128 v[190:193], v159 offset:1024
	ds_read_b128 v[194:197], v158
	ds_read_b128 v[198:201], v158 offset:1024
	ds_read_b128 v[202:205], v157
	ds_read_b128 v[208:211], v157 offset:1024
	global_load_lds_dwordx4 v[128:129], off
	v_lshl_add_u64 v[128:129], s[14:15], 0, v[140:141]
	v_readfirstlane_b32 s14, v177
	v_lshl_add_u64 v[128:129], v[130:131], 1, v[128:129]
	s_mov_b32 m0, s14
	s_nop 0
	global_load_lds_dwordx4 v[128:129], off
	s_barrier
	s_waitcnt lgkmcnt(0)
	s_waitcnt lgkmcnt(0)
	v_mfma_f32_16x16x32_bf16 v[124:127], v[136:139], v[178:181], v[124:127]
	v_mfma_f32_16x16x32_bf16 v[120:123], v[148:151], v[178:181], v[120:123]
	v_mfma_f32_16x16x32_bf16 v[116:119], v[136:139], v[186:189], v[116:119]
	v_mfma_f32_16x16x32_bf16 v[112:115], v[148:151], v[186:189], v[112:115]
	v_mfma_f32_16x16x32_bf16 v[108:111], v[136:139], v[194:197], v[108:111]
	v_mfma_f32_16x16x32_bf16 v[104:107], v[148:151], v[194:197], v[104:107]
	v_mfma_f32_16x16x32_bf16 v[100:103], v[136:139], v[202:205], v[100:103]
	v_mfma_f32_16x16x32_bf16 v[96:99], v[148:151], v[202:205], v[96:99]
	v_mfma_f32_16x16x32_bf16 v[124:127], v[144:147], v[182:185], v[124:127]
	v_mfma_f32_16x16x32_bf16 v[120:123], v[168:171], v[182:185], v[120:123]
	v_mfma_f32_16x16x32_bf16 v[116:119], v[144:147], v[190:193], v[116:119]
	v_mfma_f32_16x16x32_bf16 v[112:115], v[168:171], v[190:193], v[112:115]
	v_mfma_f32_16x16x32_bf16 v[108:111], v[144:147], v[198:201], v[108:111]
	v_mfma_f32_16x16x32_bf16 v[104:107], v[168:171], v[198:201], v[104:107]
	v_mfma_f32_16x16x32_bf16 v[100:103], v[144:147], v[208:211], v[100:103]
	v_mfma_f32_16x16x32_bf16 v[96:99], v[168:171], v[208:211], v[96:99]
	s_barrier
	ds_read_b128 v[128:131], v173
	ds_read_b128 v[140:143], v173 offset:1024
	ds_read_b128 v[174:177], v173 offset:2048
	ds_read_b128 v[214:217], v173 offset:3072
	s_barrier
; #define LDA(dst, b, h) UFOR(m, 4) UFOR(k, 2) \
;     dst[m][k] = *reinterpret_cast<const bf16x8*>((char*)SA(b, h) + lds_byte(wr * 64 + m * 16 + fr, k * 32 + fq * 8))
; #define LDB(dst, b, h) UFOR(n, 2) UFOR(k, 2) \
;     dst[n][k] = *reinterpret_cast<const bf16x8*>((char*)SB(b, h) + lds_byte(wc * 32 + n * 16 + fr, k * 32 + fq * 8))
; #define MMA(ai, bj, At, Bq) do { __builtin_amdgcn_s_setprio(1); \
;     UFOR(m, 4) UFOR(n, 2) UFOR(k, 2) \
;       acc[ai][bj][m][n] = __builtin_amdgcn_mfma_f32_16x16x32_bf16(Bq[n][k], At[m][k], acc[ai][bj][m][n], 0, 0, 0); \
;     __builtin_amdgcn_s_setprio(0); } while (0)
; #define WAIT_V(n) asm volatile("s_waitcnt vmcnt(" #n ")" ::: "memory")
; #define WAIT_L(n) asm volatile("s_waitcnt lgkmcnt(" #n ")" ::: "memory")
; #define BAR __builtin_amdgcn_s_barrier()
; template <int EPI, int K, int KL> ...
;     ...
;     BAR; WAIT_L(0); MMA(0, 0, At, B0); BAR;
;     LDB(B1, 0, 1); BAR; WAIT_L(0); MMA(0, 1, At, B1); BAR;
;     LDA(At, 0, 1); WAIT_V(4); BAR; WAIT_L(0); MMA(1, 0, At, B0); MMA(1, 1, At, B1); BAR; }
;   { LDB(B0, 1, 0); LDA(At, 1, 0); WAIT_V(2); BAR; WAIT_L(0); MMA(0, 0, At, B0); BAR;
;     LDB(B1, 1, 1); WAIT_V(0); BAR; WAIT_L(0); MMA(0, 1, At, B1); BAR;
	s_waitcnt lgkmcnt(0)
	s_waitcnt lgkmcnt(0)
	v_mfma_f32_16x16x32_bf16 v[92:95], v[128:131], v[178:181], v[92:95]
	v_mfma_f32_16x16x32_bf16 v[88:91], v[174:177], v[178:181], v[88:91]
	v_mfma_f32_16x16x32_bf16 v[84:87], v[128:131], v[186:189], v[84:87]
	v_mfma_f32_16x16x32_bf16 v[80:83], v[174:177], v[186:189], v[80:83]
	v_mfma_f32_16x16x32_bf16 v[76:79], v[128:131], v[194:197], v[76:79]
	v_mfma_f32_16x16x32_bf16 v[68:71], v[128:131], v[202:205], v[68:71]
	v_mfma_f32_16x16x32_bf16 v[64:67], v[174:177], v[202:205], v[64:67]
	v_mfma_f32_16x16x32_bf16 v[92:95], v[140:143], v[182:185], v[92:95]
	v_mfma_f32_16x16x32_bf16 v[88:91], v[214:217], v[182:185], v[88:91]
	v_mfma_f32_16x16x32_bf16 v[84:87], v[140:143], v[190:193], v[84:87]
	v_mfma_f32_16x16x32_bf16 v[80:83], v[214:217], v[190:193], v[80:83]
	v_mfma_f32_16x16x32_bf16 v[76:79], v[140:143], v[198:201], v[76:79]
	v_mfma_f32_16x16x32_bf16 v[72:75], v[174:177], v[194:197], v[72:75]
	v_mfma_f32_16x16x32_bf16 v[68:71], v[140:143], v[208:211], v[68:71]
	v_mfma_f32_16x16x32_bf16 v[64:67], v[214:217], v[208:211], v[64:67]
	v_mfma_f32_16x16x32_bf16 v[178:181], v[214:217], v[198:201], v[72:75]
	s_barrier
	s_nop 3
	ds_read_b128 v[72:75], v160 offset:16384
	ds_read_b128 v[182:185], v160 offset:17408
	ds_read_b128 v[186:189], v159 offset:16384
	ds_read_b128 v[190:193], v159 offset:17408
	ds_read_b128 v[194:197], v158 offset:16384
	ds_read_b128 v[198:201], v158 offset:17408
	ds_read_b128 v[202:205], v157 offset:16384
	ds_read_b128 v[208:211], v157 offset:17408
	s_waitcnt vmcnt(4)
	s_barrier
	s_waitcnt lgkmcnt(0)
	s_waitcnt lgkmcnt(0)
	v_mfma_f32_16x16x32_bf16 v[48:51], v[148:151], v[186:189], v[48:51]
	v_mfma_f32_16x16x32_bf16 v[60:63], v[136:139], v[72:75], v[60:63]
	v_mfma_f32_16x16x32_bf16 v[56:59], v[148:151], v[72:75], v[56:59]
	v_mfma_f32_16x16x32_bf16 v[52:55], v[136:139], v[186:189], v[52:55]
	v_mfma_f32_16x16x32_bf16 v[48:51], v[168:171], v[190:193], v[48:51]
	v_mfma_f32_16x16x32_bf16 v[44:47], v[136:139], v[194:197], v[44:47]
	v_mfma_f32_16x16x32_bf16 v[40:43], v[148:151], v[194:197], v[40:43]
	v_mfma_f32_16x16x32_bf16 v[36:39], v[136:139], v[202:205], v[36:39]
	v_mfma_f32_16x16x32_bf16 v[32:35], v[148:151], v[202:205], v[32:35]
	v_mfma_f32_16x16x32_bf16 v[218:221], v[144:147], v[182:185], v[60:63]
	v_mfma_f32_16x16x32_bf16 v[222:225], v[168:171], v[182:185], v[56:59]
	v_mfma_f32_16x16x32_bf16 v[226:229], v[144:147], v[190:193], v[52:55]
	v_mfma_f32_16x16x32_bf16 v[230:233], v[144:147], v[198:201], v[44:47]
	v_mfma_f32_16x16x32_bf16 v[234:237], v[168:171], v[198:201], v[40:43]
	v_mfma_f32_16x16x32_bf16 v[136:139], v[144:147], v[208:211], v[36:39]
	v_mfma_f32_16x16x32_bf16 v[144:147], v[168:171], v[208:211], v[32:35]
	v_mfma_f32_16x16x32_bf16 v[28:31], v[128:131], v[72:75], v[28:31]
	v_mfma_f32_16x16x32_bf16 v[24:27], v[174:177], v[72:75], v[24:27]
	v_mfma_f32_16x16x32_bf16 v[20:23], v[128:131], v[186:189], v[20:23]
	v_mfma_f32_16x16x32_bf16 v[16:19], v[174:177], v[186:189], v[16:19]
	v_mfma_f32_16x16x32_bf16 v[12:15], v[128:131], v[194:197], v[12:15]
	v_mfma_f32_16x16x32_bf16 v[8:11], v[174:177], v[194:197], v[8:11]
	v_mfma_f32_16x16x32_bf16 v[4:7], v[128:131], v[202:205], v[4:7]
	v_mfma_f32_16x16x32_bf16 v[0:3], v[174:177], v[202:205], v[0:3]
	v_mfma_f32_16x16x32_bf16 v[148:151], v[140:143], v[182:185], v[28:31]
	v_mfma_f32_16x16x32_bf16 v[168:171], v[214:217], v[182:185], v[24:27]
	v_mfma_f32_16x16x32_bf16 v[182:185], v[140:143], v[190:193], v[20:23]
	v_mfma_f32_16x16x32_bf16 v[186:189], v[214:217], v[190:193], v[16:19]
	v_mfma_f32_16x16x32_bf16 v[190:193], v[140:143], v[198:201], v[12:15]
	v_mfma_f32_16x16x32_bf16 v[194:197], v[214:217], v[198:201], v[8:11]
	v_mfma_f32_16x16x32_bf16 v[128:131], v[140:143], v[208:211], v[4:7]
	v_mfma_f32_16x16x32_bf16 v[140:143], v[214:217], v[208:211], v[0:3]
	s_barrier
	ds_read_b128 v[172:175], v166
	ds_read_b128 v[198:201], v166 offset:1024
	ds_read_b128 v[202:205], v166 offset:2048
	ds_read_b128 v[164:167], v166 offset:3072
	ds_read_b128 v[20:23], v160 offset:32768
	ds_read_b128 v[24:27], v160 offset:33792
	ds_read_b128 v[28:31], v159 offset:32768
	ds_read_b128 v[32:35], v159 offset:33792
	ds_read_b128 v[36:39], v158 offset:32768
	ds_read_b128 v[208:211], v158 offset:33792
	ds_read_b128 v[214:217], v157 offset:32768
	ds_read_b128 v[238:241], v157 offset:33792
	s_waitcnt vmcnt(2)
	s_barrier
; #define LDA(dst, b, h) UFOR(m, 4) UFOR(k, 2) \
;     dst[m][k] = *reinterpret_cast<const bf16x8*>((char*)SA(b, h) + lds_byte(wr * 64 + m * 16 + fr, k * 32 + fq * 8))
; #define LDB(dst, b, h) UFOR(n, 2) UFOR(k, 2) \
;     dst[n][k] = *reinterpret_cast<const bf16x8*>((char*)SB(b, h) + lds_byte(wc * 32 + n * 16 + fr, k * 32 + fq * 8))
; #define MMA(ai, bj, At, Bq) do { __builtin_amdgcn_s_setprio(1); \
;     UFOR(m, 4) UFOR(n, 2) UFOR(k, 2) \
;       acc[ai][bj][m][n] = __builtin_amdgcn_mfma_f32_16x16x32_bf16(Bq[n][k], At[m][k], acc[ai][bj][m][n], 0, 0, 0); \
;     __builtin_amdgcn_s_setprio(0); } while (0)
; #define WAIT_V(n) asm volatile("s_waitcnt vmcnt(" #n ")" ::: "memory")
; #define WAIT_L(n) asm volatile("s_waitcnt lgkmcnt(" #n ")" ::: "memory")
; #define BAR __builtin_amdgcn_s_barrier()
; template <int EPI, int K, int KL> ...
;     ...
;   { LDB(B0, 1, 0); LDA(At, 1, 0); WAIT_V(2); BAR; WAIT_L(0); MMA(0, 0, At, B0); BAR;
;     LDB(B1, 1, 1); WAIT_V(0); BAR; WAIT_L(0); MMA(0, 1, At, B1); BAR;
;     LDA(At, 1, 1); BAR; WAIT_L(0); MMA(1, 0, At, B0); MMA(1, 1, At, B1); BAR; }
;   if (wr == 0) BAR;
	s_waitcnt lgkmcnt(0)
	s_waitcnt lgkmcnt(0)
	v_mfma_f32_16x16x32_bf16 v[0:3], v[172:175], v[20:23], v[124:127]
	v_mfma_f32_16x16x32_bf16 v[44:47], v[198:201], v[24:27], v[0:3]
	v_mfma_f32_16x16x32_bf16 v[0:3], v[202:205], v[20:23], v[120:123]
	v_mfma_f32_16x16x32_bf16 v[52:55], v[164:167], v[24:27], v[0:3]
	v_mfma_f32_16x16x32_bf16 v[0:3], v[172:175], v[28:31], v[116:119]
	v_mfma_f32_16x16x32_bf16 v[40:43], v[198:201], v[32:35], v[0:3]
	v_mfma_f32_16x16x32_bf16 v[0:3], v[202:205], v[28:31], v[112:115]
	v_mfma_f32_16x16x32_bf16 v[16:19], v[164:167], v[32:35], v[0:3]
	v_mfma_f32_16x16x32_bf16 v[0:3], v[172:175], v[36:39], v[108:111]
	v_mfma_f32_16x16x32_bf16 v[8:11], v[198:201], v[208:211], v[0:3]
	v_mfma_f32_16x16x32_bf16 v[0:3], v[202:205], v[36:39], v[104:107]
	v_mfma_f32_16x16x32_bf16 v[12:15], v[164:167], v[208:211], v[0:3]
	v_mfma_f32_16x16x32_bf16 v[0:3], v[172:175], v[214:217], v[100:103]
	v_mfma_f32_16x16x32_bf16 v[4:7], v[202:205], v[214:217], v[96:99]
	v_mfma_f32_16x16x32_bf16 v[0:3], v[198:201], v[238:241], v[0:3]
	v_mfma_f32_16x16x32_bf16 v[4:7], v[164:167], v[238:241], v[4:7]
	s_barrier
	ds_read_b128 v[108:111], v163
	ds_read_b128 v[242:245], v163 offset:1024
	ds_read_b128 v[246:249], v163 offset:2048
	ds_read_b128 v[152:155], v163 offset:3072
	s_waitcnt vmcnt(0)
	s_barrier
	s_waitcnt lgkmcnt(0)
	s_waitcnt lgkmcnt(0)
	v_mfma_f32_16x16x32_bf16 v[56:59], v[108:111], v[20:23], v[92:95]
	v_mfma_f32_16x16x32_bf16 v[20:23], v[246:249], v[20:23], v[88:91]
	v_mfma_f32_16x16x32_bf16 v[72:75], v[152:155], v[24:27], v[20:23]
	v_mfma_f32_16x16x32_bf16 v[20:23], v[108:111], v[28:31], v[84:87]
	v_mfma_f32_16x16x32_bf16 v[60:63], v[242:245], v[24:27], v[56:59]
	v_mfma_f32_16x16x32_bf16 v[56:59], v[242:245], v[32:35], v[20:23]
	v_mfma_f32_16x16x32_bf16 v[20:23], v[246:249], v[28:31], v[80:83]
	v_mfma_f32_16x16x32_bf16 v[20:23], v[152:155], v[32:35], v[20:23]
	v_mfma_f32_16x16x32_bf16 v[24:27], v[108:111], v[36:39], v[76:79]
	v_mfma_f32_16x16x32_bf16 v[28:31], v[246:249], v[36:39], v[178:181]
	v_mfma_f32_16x16x32_bf16 v[32:35], v[108:111], v[214:217], v[68:71]
	v_mfma_f32_16x16x32_bf16 v[36:39], v[246:249], v[214:217], v[64:67]
	v_mfma_f32_16x16x32_bf16 v[24:27], v[242:245], v[208:211], v[24:27]
	v_mfma_f32_16x16x32_bf16 v[28:31], v[152:155], v[208:211], v[28:31]
	v_mfma_f32_16x16x32_bf16 v[32:35], v[242:245], v[238:241], v[32:35]
	v_mfma_f32_16x16x32_bf16 v[36:39], v[152:155], v[238:241], v[36:39]
	s_barrier
	ds_read_b128 v[88:91], v160 offset:49152
	ds_read_b128 v[92:95], v160 offset:50176
	ds_read_b128 v[96:99], v159 offset:49152
	ds_read_b128 v[100:103], v159 offset:50176
	ds_read_b128 v[104:107], v158 offset:49152
	ds_read_b128 v[158:161], v158 offset:50176
	ds_read_b128 v[176:179], v157 offset:49152
	ds_read_b128 v[208:211], v157 offset:50176
	s_barrier
	s_waitcnt lgkmcnt(0)
	s_waitcnt lgkmcnt(0)
	v_mfma_f32_16x16x32_bf16 v[48:51], v[202:205], v[96:99], v[48:51]
	v_mfma_f32_16x16x32_bf16 v[64:67], v[172:175], v[88:91], v[218:221]
	v_mfma_f32_16x16x32_bf16 v[116:119], v[164:167], v[100:103], v[48:51]
	v_mfma_f32_16x16x32_bf16 v[48:51], v[172:175], v[104:107], v[230:233]
	v_mfma_f32_16x16x32_bf16 v[120:123], v[198:201], v[92:95], v[64:67]
	v_mfma_f32_16x16x32_bf16 v[64:67], v[202:205], v[88:91], v[222:225]
	v_mfma_f32_16x16x32_bf16 v[76:79], v[198:201], v[158:161], v[48:51]
	v_mfma_f32_16x16x32_bf16 v[48:51], v[202:205], v[104:107], v[234:237]
	v_mfma_f32_16x16x32_bf16 v[124:127], v[164:167], v[92:95], v[64:67]
	v_mfma_f32_16x16x32_bf16 v[64:67], v[172:175], v[96:99], v[226:229]
	v_mfma_f32_16x16x32_bf16 v[80:83], v[164:167], v[158:161], v[48:51]
	v_mfma_f32_16x16x32_bf16 v[48:51], v[172:175], v[176:179], v[136:139]
	v_mfma_f32_16x16x32_bf16 v[112:115], v[198:201], v[100:103], v[64:67]
	v_mfma_f32_16x16x32_bf16 v[64:67], v[198:201], v[208:211], v[48:51]
	v_mfma_f32_16x16x32_bf16 v[48:51], v[202:205], v[176:179], v[144:147]
	v_mfma_f32_16x16x32_bf16 v[68:71], v[164:167], v[208:211], v[48:51]
	v_mfma_f32_16x16x32_bf16 v[48:51], v[108:111], v[88:91], v[148:151]
	v_mfma_f32_16x16x32_bf16 v[84:87], v[242:245], v[92:95], v[48:51]
	v_mfma_f32_16x16x32_bf16 v[48:51], v[246:249], v[88:91], v[168:171]
	v_mfma_f32_16x16x32_bf16 v[88:91], v[152:155], v[92:95], v[48:51]
	v_mfma_f32_16x16x32_bf16 v[48:51], v[108:111], v[96:99], v[182:185]
	v_mfma_f32_16x16x32_bf16 v[92:95], v[242:245], v[100:103], v[48:51]
	v_mfma_f32_16x16x32_bf16 v[48:51], v[246:249], v[96:99], v[186:189]
	v_mfma_f32_16x16x32_bf16 v[96:99], v[152:155], v[100:103], v[48:51]
	v_mfma_f32_16x16x32_bf16 v[48:51], v[108:111], v[104:107], v[190:193]
	v_mfma_f32_16x16x32_bf16 v[100:103], v[242:245], v[158:161], v[48:51]
	v_mfma_f32_16x16x32_bf16 v[48:51], v[246:249], v[104:107], v[194:197]
	v_mfma_f32_16x16x32_bf16 v[104:107], v[152:155], v[158:161], v[48:51]
	v_mfma_f32_16x16x32_bf16 v[48:51], v[108:111], v[176:179], v[128:131]
	v_mfma_f32_16x16x32_bf16 v[108:111], v[242:245], v[208:211], v[48:51]
	v_mfma_f32_16x16x32_bf16 v[48:51], v[246:249], v[176:179], v[140:143]
	v_mfma_f32_16x16x32_bf16 v[48:51], v[152:155], v[208:211], v[48:51]
	s_movk_i32 s14, 0x100
	v_cmp_gt_u32_e32 vcc, s14, v132
	s_barrier
	s_and_saveexec_b64 s[44:45], vcc
	s_cbranch_execz .LBB0_1200
	s_barrier
	s_branch .LBB0_1200
